# rebalanced LDS reads (7 loops) + uniform vmcnt(10) stage guards + Mx rewrite + 4-byte code shift around the O2 loop
# speedup vs baseline: 1.0028x; 1.0028x over previous
; #define PG8_STAGE_A(bufoff, ptr, half, rev) do { if (REVA && (rev)) { const char* _p = (ptr) - ((half) ? hstepA : 0); PG8_STAGE(bufoff, _p, voffAr); } else { const char* _p = (ptr) + ((half) ? hstepA : 0); PG8_STAGE(bufoff, _p, voffA); } } while (0)
; #define PG8_LDA(dst, b, h) do { _Pragma("unroll") for (int m = 0; m < 4; ++m) _Pragma("unroll") for (int k = 0; k < 2; ++k) dst[m][k] = *(const LAS bf16x8*)(lds + PG8_SA(b, h) + aoff + m * 2048 + k * 1024); } while (0)
; #define PG8_LDB(dst, b, h) do { _Pragma("unroll") for (int n = 0; n < 2; ++n) _Pragma("unroll") for (int k = 0; k < 2; ++k) dst[n][k] = *(const LAS bf16x8*)(lds + PG8_SB(b, h) + boff + n * 2048 + k * 1024); } while (0)
; #define PG8_WAIT_L(n) asm volatile("s_waitcnt lgkmcnt(" #n ")" ::: "memory")
; #define PG8_BAR __builtin_amdgcn_s_barrier()
; #define PG8_SCHED __builtin_amdgcn_sched_barrier(0)
;     ...
;     for (;;) {
;         const bool has_next = next_unit(ui + 1, nM, nN, MP, nxt, rot);
;         const char* nA = has_next ? nxt.a : cA; const char* nB = has_next ? nxt.b : cB; const char* nAr = has_next ? nxt.ar : cAr; const size_t nHb = has_next ? nxt.hb : cHb;
;         for (int t = 0; t < nt; t += 2) {
;             const bool last = (t == nt - 2);
;             const char* a1 = PG8_APTR(cA, cAr, t + 1); const bool r1 = REVA && ((t + 1) & 4);
;             const char* a2 = last ? nA : PG8_APTR(cA, cAr, t + 2); const bool r2 = REVA && !last && ((t + 2) & 4);
;             const char* a3 = last ? nA + kstep : PG8_APTR(cA, cAr, t + 3); const bool r3 = REVA && !last && ((t + 3) & 4);
;             const char* b2 = last ? nB : cB + (size_t)(t + 2) * kstep; const char* b3 = b2 + kstep; const size_t hb2 = last ? nHb : cHb;
;             PG8_LDB(B0, 0, 0); PG8_SCHED; PG8_LDA(At, 0, 0); PG8_STAGE_A(PG8_SA(1, 1), a1, 1, r1);
;             PG8_WAIT_L(8); PG8_BAR; PG8_WAIT_L(0); PG8_MMA(0, 0, At, B0); PG8_BAR; PG8_SCHED;
;     ...
; #pragma unroll
;         for (int a = 0; a < 2; ++a)
; #pragma unroll
;             for (int b = 0; b < 2; ++b)
; #pragma unroll
;                 for (int m = 0; m < 4; ++m)
; #pragma unroll
;                     for (int n = 0; n < 2; ++n) acc[a][b][m][n] = (f32x4){0.f, 0.f, 0.f, 0.f};
;         cur = nxt; cA = nA; cB = nB; cAr = nAr; cHb = nHb; ++ui;
.LBB0_233:
	s_add_u32 s3, s0, 0x80
	s_addc_u32 s6, s1, 0
	s_add_u32 s8, s38, 0x80080
	s_addc_u32 s9, s39, 0
	s_add_u32 s7, s20, 0x100
	v_mov_b32_e32 v0, 0
	v_lshl_add_u64 v[88:89], s[8:9], 0, v[150:151]
	v_lshl_add_u64 v[90:91], s[8:9], 0, v[152:153]
	s_addc_u32 s8, s21, 0
	s_mov_b32 s9, -2
	s_mov_b64 vcc, 0
	v_mov_b32_e32 v1, v0
	v_mov_b32_e32 v2, v0
	v_mov_b32_e32 v3, v0
	v_mov_b32_e32 v32, v0
	v_mov_b32_e32 v33, v0
	v_mov_b32_e32 v34, v0
	v_mov_b32_e32 v35, v0
	v_mov_b32_e32 v8, v0
	v_mov_b32_e32 v9, v0
	v_mov_b32_e32 v10, v0
	v_mov_b32_e32 v11, v0
	v_mov_b32_e32 v40, v0
	v_mov_b32_e32 v41, v0
	v_mov_b32_e32 v42, v0
	v_mov_b32_e32 v43, v0
	v_mov_b32_e32 v16, v0
	v_mov_b32_e32 v17, v0
	v_mov_b32_e32 v18, v0
	v_mov_b32_e32 v19, v0
	v_mov_b32_e32 v48, v0
	v_mov_b32_e32 v49, v0
	v_mov_b32_e32 v50, v0
	v_mov_b32_e32 v51, v0
	v_mov_b32_e32 v24, v0
	v_mov_b32_e32 v25, v0
	v_mov_b32_e32 v26, v0
	v_mov_b32_e32 v27, v0
	v_mov_b32_e32 v56, v0
	v_mov_b32_e32 v57, v0
	v_mov_b32_e32 v58, v0
	v_mov_b32_e32 v59, v0
	v_mov_b32_e32 v36, v0
	v_mov_b32_e32 v37, v0
	v_mov_b32_e32 v38, v0
	v_mov_b32_e32 v39, v0
	v_mov_b32_e32 v4, v0
	v_mov_b32_e32 v5, v0
	v_mov_b32_e32 v6, v0
	v_mov_b32_e32 v7, v0
	v_mov_b32_e32 v44, v0
	v_mov_b32_e32 v45, v0
	v_mov_b32_e32 v46, v0
	v_mov_b32_e32 v47, v0
	v_mov_b32_e32 v12, v0
	v_mov_b32_e32 v13, v0
	v_mov_b32_e32 v14, v0
	v_mov_b32_e32 v15, v0
	v_mov_b32_e32 v52, v0
	v_mov_b32_e32 v53, v0
	v_mov_b32_e32 v54, v0
	v_mov_b32_e32 v55, v0
	v_mov_b32_e32 v20, v0
	v_mov_b32_e32 v21, v0
	v_mov_b32_e32 v22, v0
	v_mov_b32_e32 v23, v0
	v_mov_b32_e32 v60, v0
	v_mov_b32_e32 v61, v0
	v_mov_b32_e32 v62, v0
	v_mov_b32_e32 v63, v0
	v_mov_b32_e32 v28, v0
	v_mov_b32_e32 v29, v0
	v_mov_b32_e32 v30, v0
	v_mov_b32_e32 v31, v0
	v_mov_b32_e32 v64, v0
	v_mov_b32_e32 v65, v0
	v_mov_b32_e32 v66, v0
	v_mov_b32_e32 v67, v0
	v_mov_b32_e32 v108, v0
	v_mov_b32_e32 v109, v0
	v_mov_b32_e32 v110, v0
	v_mov_b32_e32 v111, v0
	v_mov_b32_e32 v72, v0
	v_mov_b32_e32 v73, v0
	v_mov_b32_e32 v74, v0
	v_mov_b32_e32 v75, v0
	v_mov_b32_e32 v116, v0
	v_mov_b32_e32 v117, v0
	v_mov_b32_e32 v118, v0
	v_mov_b32_e32 v119, v0
	v_mov_b32_e32 v80, v0
	v_mov_b32_e32 v81, v0
	v_mov_b32_e32 v82, v0
	v_mov_b32_e32 v83, v0
	v_mov_b32_e32 v124, v0
	v_mov_b32_e32 v125, v0
	v_mov_b32_e32 v126, v0
	v_mov_b32_e32 v127, v0
	v_mov_b32_e32 v100, v0
	v_mov_b32_e32 v101, v0
	v_mov_b32_e32 v102, v0
	v_mov_b32_e32 v103, v0
	v_mov_b32_e32 v132, v0
	v_mov_b32_e32 v133, v0
	v_mov_b32_e32 v134, v0
	v_mov_b32_e32 v135, v0
	v_mov_b32_e32 v112, v0
	v_mov_b32_e32 v113, v0
	v_mov_b32_e32 v114, v0
	v_mov_b32_e32 v115, v0
	v_mov_b32_e32 v68, v0
	v_mov_b32_e32 v69, v0
	v_mov_b32_e32 v70, v0
	v_mov_b32_e32 v71, v0
	v_mov_b32_e32 v120, v0
	v_mov_b32_e32 v121, v0
	v_mov_b32_e32 v122, v0
	v_mov_b32_e32 v123, v0
	v_mov_b32_e32 v76, v0
	v_mov_b32_e32 v77, v0
	v_mov_b32_e32 v78, v0
	v_mov_b32_e32 v79, v0
	v_mov_b32_e32 v128, v0
	v_mov_b32_e32 v129, v0
	v_mov_b32_e32 v130, v0
	v_mov_b32_e32 v131, v0
	v_mov_b32_e32 v84, v0
	v_mov_b32_e32 v85, v0
	v_mov_b32_e32 v86, v0
	v_mov_b32_e32 v87, v0
	v_mov_b32_e32 v136, v0
	v_mov_b32_e32 v137, v0
	v_mov_b32_e32 v138, v0
	v_mov_b32_e32 v139, v0
	v_mov_b32_e32 v104, v0
	v_mov_b32_e32 v105, v0
	v_mov_b32_e32 v106, v0
	v_mov_b32_e32 v107, v0
	s_nop 0
	v_add_u32_e32 v154, 0x10000, v156
	ds_read_b128 v[92:95], v154
	ds_read_b128 v[96:99], v154 offset:1024
	ds_read_b128 v[172:175], v154 offset:2048
	ds_read_b128 v[176:179], v154 offset:3072
.LBB0_234:
	s_add_u32 s10, s38, vcc_lo
	s_addc_u32 s11, s39, vcc_hi
	s_add_u32 s16, s10, 0x100
	s_addc_u32 s17, s11, 0
	s_add_u32 s10, s10, 0x180
	s_addc_u32 s11, s11, 0
	s_add_u32 s14, s7, vcc_lo
	s_addc_u32 s15, s8, vcc_hi
	s_add_i32 s27, 0, 0x10000
	s_cmpk_eq_i32 vcc_lo, 0xf00
	s_cselect_b32 s15, s71, s15
	s_cselect_b32 s14, s70, s14
	s_cselect_b32 s21, s1, s17
	s_cselect_b32 s20, s0, s16
	s_cselect_b32 s17, s6, s11
	s_cselect_b32 s16, s3, s10
	v_lshl_add_u64 v[154:155], v[88:89], 0, vcc
	s_add_i32 m0, s91, 0xc000
	ds_read_b128 v[180:183], v171
	ds_read_b128 v[204:207], v171 offset:1024
	ds_read_b128 v[208:211], v171 offset:2048
	ds_read_b128 v[212:215], v171 offset:3072
	ds_read_b128 v[216:219], v171 offset:4096
	ds_read_b128 v[220:223], v171 offset:5120
	ds_read_b128 v[224:227], v171 offset:6144
	ds_read_b128 v[228:231], v171 offset:7168
	global_load_lds_dwordx4 v[154:155], off
	v_lshl_add_u64 v[154:155], v[90:91], 0, vcc
	s_add_i32 m0, s91, 0xe000
	s_nop 0
	global_load_lds_dwordx4 v[154:155], off
	s_waitcnt lgkmcnt(8)
	s_waitcnt vmcnt(10)
	s_barrier
	s_waitcnt lgkmcnt(0)
	s_setprio 1
	s_waitcnt lgkmcnt(0)
	v_mfma_f32_16x16x32_bf16 v[104:107], v[92:95], v[180:183], v[104:107]
	v_mfma_f32_16x16x32_bf16 v[136:139], v[172:175], v[180:183], v[136:139]
	v_mfma_f32_16x16x32_bf16 v[84:87], v[92:95], v[208:211], v[84:87]
	v_mfma_f32_16x16x32_bf16 v[128:131], v[172:175], v[208:211], v[128:131]
	v_mfma_f32_16x16x32_bf16 v[76:79], v[92:95], v[216:219], v[76:79]
	v_mfma_f32_16x16x32_bf16 v[120:123], v[172:175], v[216:219], v[120:123]
	v_mfma_f32_16x16x32_bf16 v[68:71], v[92:95], v[224:227], v[68:71]
	v_mfma_f32_16x16x32_bf16 v[112:115], v[172:175], v[224:227], v[112:115]
	v_mfma_f32_16x16x32_bf16 v[104:107], v[96:99], v[204:207], v[104:107]
	v_mfma_f32_16x16x32_bf16 v[136:139], v[176:179], v[204:207], v[136:139]
	v_mfma_f32_16x16x32_bf16 v[84:87], v[96:99], v[212:215], v[84:87]
	v_mfma_f32_16x16x32_bf16 v[128:131], v[176:179], v[212:215], v[128:131]
	v_mfma_f32_16x16x32_bf16 v[76:79], v[96:99], v[220:223], v[76:79]
	v_mfma_f32_16x16x32_bf16 v[120:123], v[176:179], v[220:223], v[120:123]
	v_mfma_f32_16x16x32_bf16 v[68:71], v[96:99], v[228:231], v[68:71]
	v_mfma_f32_16x16x32_bf16 v[112:115], v[176:179], v[228:231], v[112:115]
	s_setprio 0
	s_barrier
; #define PG8_STAGE(bufoff, gbase, voff) do { _Pragma("unroll") for (int _i = 0; _i < 2; ++_i) \
;         __builtin_amdgcn_global_load_lds((const unsigned*)((const char*)(gbase) + (voff)[_i]), (LAS unsigned*)(lds + (bufoff) + ldsw + _i * 8192), 16, 0, 0); } while (0)
; #define PG8_STAGE_A(bufoff, ptr, half, rev) do { if (REVA && (rev)) { const char* _p = (ptr) - ((half) ? hstepA : 0); PG8_STAGE(bufoff, _p, voffAr); } else { const char* _p = (ptr) + ((half) ? hstepA : 0); PG8_STAGE(bufoff, _p, voffA); } } while (0)
; #define PG8_LDA(dst, b, h) do { _Pragma("unroll") for (int m = 0; m < 4; ++m) _Pragma("unroll") for (int k = 0; k < 2; ++k) dst[m][k] = *(const LAS bf16x8*)(lds + PG8_SA(b, h) + aoff + m * 2048 + k * 1024); } while (0)
; #define PG8_LDB(dst, b, h) do { _Pragma("unroll") for (int n = 0; n < 2; ++n) _Pragma("unroll") for (int k = 0; k < 2; ++k) dst[n][k] = *(const LAS bf16x8*)(lds + PG8_SB(b, h) + boff + n * 2048 + k * 1024); } while (0)
; #define PG8_MMA(ai, bj, At, Bt) do { __builtin_amdgcn_s_setprio(1); _Pragma("unroll") for (int m = 0; m < 4; ++m) _Pragma("unroll") for (int n = 0; n < 2; ++n) _Pragma("unroll") for (int k = 0; k < 2; ++k) \
;         acc[ai][bj][m][n] = __builtin_amdgcn_mfma_f32_16x16x32_bf16(Bt[n][k], At[m][k], acc[ai][bj][m][n], 0, 0, 0); __builtin_amdgcn_s_setprio(0); } while (0)
; #define PG8_WAIT_V(n) asm volatile("s_waitcnt vmcnt(" #n ")" ::: "memory")
; #define PG8_WAIT_L(n) asm volatile("s_waitcnt lgkmcnt(" #n ")" ::: "memory")
; #define PG8_BAR __builtin_amdgcn_s_barrier()
; #define PG8_SCHED __builtin_amdgcn_sched_barrier(0)
;     ...
;             PG8_LDB(B1, 0, 1); PG8_STAGE(PG8_SB(0, 0), b2, voffB);
;             PG8_BAR; PG8_WAIT_L(0); PG8_MMA(0, 1, At, B1); PG8_BAR;
;             PG8_LDA(At, 0, 1); PG8_STAGE_A(PG8_SA(0, 0), a2, 0, r2);
;             PG8_BAR; PG8_WAIT_L(0); PG8_MMA(1, 0, At, B0); PG8_BAR; PG8_SCHED;
;             PG8_STAGE(PG8_SB(0, 1), b2 + hb2, voffB);
;             PG8_WAIT_V(6); PG8_BAR; PG8_MMA(1, 1, At, B1); PG8_BAR;
;             PG8_LDB(B0, 1, 0); PG8_SCHED; PG8_LDA(At, 1, 0); PG8_STAGE_A(PG8_SA(0, 1), a2, 1, r2);
;             PG8_WAIT_L(8); PG8_BAR; PG8_WAIT_L(0); PG8_MMA(0, 0, At, B0); PG8_BAR; PG8_SCHED;
	s_add_i32 s37, 0, 0x14000
	v_add_u32_e32 v154, s37, v156
	s_add_i32 s10, s27, s90
	ds_read_b128 v[232:235], v154
	ds_read_b128 v[236:239], v154 offset:1024
	ds_read_b128 v[240:243], v154 offset:2048
	ds_read_b128 v[244:247], v154 offset:3072
	v_lshl_add_u64 v[154:155], s[14:15], 0, v[160:161]
	s_mov_b32 m0, s10
	v_lshl_add_u64 v[184:185], s[14:15], 0, v[140:141]
	global_load_lds_dwordx4 v[154:155], off
	s_add_i32 m0, s10, 0x2000
	s_nop 0
	global_load_lds_dwordx4 v[184:185], off
	s_waitcnt vmcnt(10)
	s_barrier
	s_waitcnt lgkmcnt(0)
	s_setprio 1
	s_waitcnt lgkmcnt(0)
	v_mfma_f32_16x16x32_bf16 v[132:135], v[232:235], v[180:183], v[132:135]
	v_mfma_f32_16x16x32_bf16 v[100:103], v[240:243], v[180:183], v[100:103]
	v_mfma_f32_16x16x32_bf16 v[124:127], v[232:235], v[208:211], v[124:127]
	v_mfma_f32_16x16x32_bf16 v[80:83], v[240:243], v[208:211], v[80:83]
	v_mfma_f32_16x16x32_bf16 v[116:119], v[232:235], v[216:219], v[116:119]
	v_mfma_f32_16x16x32_bf16 v[72:75], v[240:243], v[216:219], v[72:75]
	v_mfma_f32_16x16x32_bf16 v[108:111], v[232:235], v[224:227], v[108:111]
	v_mfma_f32_16x16x32_bf16 v[64:67], v[240:243], v[224:227], v[64:67]
	v_mfma_f32_16x16x32_bf16 v[132:135], v[236:239], v[204:207], v[132:135]
	v_mfma_f32_16x16x32_bf16 v[100:103], v[244:247], v[204:207], v[100:103]
	v_mfma_f32_16x16x32_bf16 v[124:127], v[236:239], v[212:215], v[124:127]
	v_mfma_f32_16x16x32_bf16 v[80:83], v[244:247], v[212:215], v[80:83]
	v_mfma_f32_16x16x32_bf16 v[116:119], v[236:239], v[220:223], v[116:119]
	v_mfma_f32_16x16x32_bf16 v[72:75], v[244:247], v[220:223], v[72:75]
	v_mfma_f32_16x16x32_bf16 v[108:111], v[236:239], v[228:231], v[108:111]
	v_mfma_f32_16x16x32_bf16 v[64:67], v[244:247], v[228:231], v[64:67]
	s_setprio 0
	s_mov_b32 m0, s91
	v_lshl_add_u64 v[190:191], s[20:21], 0, v[160:161]
	s_barrier
	ds_read_b128 v[180:183], v171 offset:16384
	ds_read_b128 v[204:207], v171 offset:17408
	ds_read_b128 v[208:211], v171 offset:18432
	ds_read_b128 v[212:215], v171 offset:19456
	ds_read_b128 v[216:219], v171 offset:20480
	ds_read_b128 v[220:223], v171 offset:21504
	ds_read_b128 v[224:227], v171 offset:22528
	ds_read_b128 v[228:231], v171 offset:23552
	global_load_lds_dwordx4 v[190:191], off
	v_lshl_add_u64 v[190:191], s[20:21], 0, v[140:141]
	s_mov_b32 m0, s92
	s_nop 0
	global_load_lds_dwordx4 v[190:191], off
	s_waitcnt vmcnt(10)
	s_barrier
	s_waitcnt lgkmcnt(0)
	s_setprio 1
	s_waitcnt lgkmcnt(0)
	v_mfma_f32_16x16x32_bf16 v[28:31], v[92:95], v[180:183], v[28:31]
	v_mfma_f32_16x16x32_bf16 v[60:63], v[172:175], v[180:183], v[60:63]
	v_mfma_f32_16x16x32_bf16 v[20:23], v[92:95], v[208:211], v[20:23]
	v_mfma_f32_16x16x32_bf16 v[52:55], v[172:175], v[208:211], v[52:55]
	v_mfma_f32_16x16x32_bf16 v[12:15], v[92:95], v[216:219], v[12:15]
	v_mfma_f32_16x16x32_bf16 v[44:47], v[172:175], v[216:219], v[44:47]
	v_mfma_f32_16x16x32_bf16 v[4:7], v[92:95], v[224:227], v[4:7]
	v_mfma_f32_16x16x32_bf16 v[36:39], v[172:175], v[224:227], v[36:39]
	v_mfma_f32_16x16x32_bf16 v[28:31], v[96:99], v[204:207], v[28:31]
	v_mfma_f32_16x16x32_bf16 v[60:63], v[176:179], v[204:207], v[60:63]
	v_mfma_f32_16x16x32_bf16 v[20:23], v[96:99], v[212:215], v[20:23]
	v_mfma_f32_16x16x32_bf16 v[52:55], v[176:179], v[212:215], v[52:55]
	v_mfma_f32_16x16x32_bf16 v[12:15], v[96:99], v[220:223], v[12:15]
	v_mfma_f32_16x16x32_bf16 v[44:47], v[176:179], v[220:223], v[44:47]
	v_mfma_f32_16x16x32_bf16 v[4:7], v[96:99], v[228:231], v[4:7]
	v_mfma_f32_16x16x32_bf16 v[36:39], v[176:179], v[228:231], v[36:39]
	s_setprio 0
	s_barrier
	s_add_u32 s10, s14, 0x80000
	s_addc_u32 s11, s15, 0
	s_add_i32 s27, s37, s90
	v_lshl_add_u64 v[92:93], s[10:11], 0, v[160:161]
	s_mov_b32 m0, s27
	s_nop 0
	global_load_lds_dwordx4 v[92:93], off
	v_lshl_add_u64 v[92:93], s[10:11], 0, v[140:141]
	s_add_i32 m0, s27, 0x2000
	s_nop 0
	global_load_lds_dwordx4 v[92:93], off
	v_add_u32_e32 v176, 0x18000, v156
	ds_read_b128 v[92:95], v176
	ds_read_b128 v[96:99], v176 offset:1024
	ds_read_b128 v[172:175], v176 offset:2048
	ds_read_b128 v[176:179], v176 offset:3072
	s_waitcnt vmcnt(10)
	s_barrier
	s_setprio 1
	v_mfma_f32_16x16x32_bf16 v[56:59], v[232:235], v[180:183], v[56:59]
	v_mfma_f32_16x16x32_bf16 v[24:27], v[240:243], v[180:183], v[24:27]
	v_mfma_f32_16x16x32_bf16 v[48:51], v[232:235], v[208:211], v[48:51]
	v_mfma_f32_16x16x32_bf16 v[16:19], v[240:243], v[208:211], v[16:19]
	v_mfma_f32_16x16x32_bf16 v[40:43], v[232:235], v[216:219], v[40:43]
	v_mfma_f32_16x16x32_bf16 v[8:11], v[240:243], v[216:219], v[8:11]
	v_mfma_f32_16x16x32_bf16 v[32:35], v[232:235], v[224:227], v[32:35]
	v_mfma_f32_16x16x32_bf16 v[0:3], v[240:243], v[224:227], v[0:3]
	v_mfma_f32_16x16x32_bf16 v[56:59], v[236:239], v[204:207], v[56:59]
	v_mfma_f32_16x16x32_bf16 v[24:27], v[244:247], v[204:207], v[24:27]
	v_mfma_f32_16x16x32_bf16 v[48:51], v[236:239], v[212:215], v[48:51]
	v_mfma_f32_16x16x32_bf16 v[16:19], v[244:247], v[212:215], v[16:19]
	v_mfma_f32_16x16x32_bf16 v[40:43], v[236:239], v[220:223], v[40:43]
	v_mfma_f32_16x16x32_bf16 v[8:11], v[244:247], v[220:223], v[8:11]
	v_mfma_f32_16x16x32_bf16 v[32:35], v[236:239], v[228:231], v[32:35]
	v_mfma_f32_16x16x32_bf16 v[0:3], v[244:247], v[228:231], v[0:3]
	s_setprio 0
	s_add_i32 s27, 0, 0x18000
	s_barrier
	s_add_u32 s10, s20, 0x80000
	s_addc_u32 s11, s21, 0
	s_mov_b32 m0, s93
	v_lshl_add_u64 v[190:191], s[10:11], 0, v[160:161]
	ds_read_b128 v[180:183], v171 offset:32768
	ds_read_b128 v[204:207], v171 offset:33792
	ds_read_b128 v[208:211], v171 offset:34816
	ds_read_b128 v[212:215], v171 offset:35840
	ds_read_b128 v[216:219], v171 offset:36864
	ds_read_b128 v[220:223], v171 offset:37888
	ds_read_b128 v[224:227], v171 offset:38912
	ds_read_b128 v[228:231], v171 offset:39936
	global_load_lds_dwordx4 v[190:191], off
	v_lshl_add_u64 v[190:191], s[10:11], 0, v[140:141]
	s_mov_b32 m0, s94
	s_nop 0
	global_load_lds_dwordx4 v[190:191], off
	s_waitcnt lgkmcnt(8)
	s_waitcnt vmcnt(10)
	s_barrier
; #define PG8_STAGE(bufoff, gbase, voff) do { _Pragma("unroll") for (int _i = 0; _i < 2; ++_i) \
;         __builtin_amdgcn_global_load_lds((const unsigned*)((const char*)(gbase) + (voff)[_i]), (LAS unsigned*)(lds + (bufoff) + ldsw + _i * 8192), 16, 0, 0); } while (0)
; #define PG8_STAGE_A(bufoff, ptr, half, rev) do { if (REVA && (rev)) { const char* _p = (ptr) - ((half) ? hstepA : 0); PG8_STAGE(bufoff, _p, voffAr); } else { const char* _p = (ptr) + ((half) ? hstepA : 0); PG8_STAGE(bufoff, _p, voffA); } } while (0)
; #define PG8_LDA(dst, b, h) do { _Pragma("unroll") for (int m = 0; m < 4; ++m) _Pragma("unroll") for (int k = 0; k < 2; ++k) dst[m][k] = *(const LAS bf16x8*)(lds + PG8_SA(b, h) + aoff + m * 2048 + k * 1024); } while (0)
; #define PG8_LDB(dst, b, h) do { _Pragma("unroll") for (int n = 0; n < 2; ++n) _Pragma("unroll") for (int k = 0; k < 2; ++k) dst[n][k] = *(const LAS bf16x8*)(lds + PG8_SB(b, h) + boff + n * 2048 + k * 1024); } while (0)
; #define PG8_MMA(ai, bj, At, Bt) do { __builtin_amdgcn_s_setprio(1); _Pragma("unroll") for (int m = 0; m < 4; ++m) _Pragma("unroll") for (int n = 0; n < 2; ++n) _Pragma("unroll") for (int k = 0; k < 2; ++k) \
;         acc[ai][bj][m][n] = __builtin_amdgcn_mfma_f32_16x16x32_bf16(Bt[n][k], At[m][k], acc[ai][bj][m][n], 0, 0, 0); __builtin_amdgcn_s_setprio(0); } while (0)
; #define PG8_WAIT_V(n) asm volatile("s_waitcnt vmcnt(" #n ")" ::: "memory")
; #define PG8_WAIT_L(n) asm volatile("s_waitcnt lgkmcnt(" #n ")" ::: "memory")
; #define PG8_BAR __builtin_amdgcn_s_barrier()
; #define PG8_SCHED __builtin_amdgcn_sched_barrier(0)
;     ...
;             PG8_WAIT_L(8); PG8_BAR; PG8_WAIT_L(0); PG8_MMA(0, 0, At, B0); PG8_BAR; PG8_SCHED;
;             PG8_LDB(B1, 1, 1); PG8_STAGE(PG8_SB(1, 0), b3, voffB);
;             PG8_BAR; PG8_WAIT_L(0); PG8_MMA(0, 1, At, B1); PG8_BAR;
;             PG8_LDA(At, 1, 1); PG8_STAGE_A(PG8_SA(1, 0), a3, 0, r3);
;             PG8_BAR; PG8_WAIT_L(0); PG8_MMA(1, 0, At, B0); PG8_BAR; PG8_SCHED;
;             PG8_STAGE(PG8_SB(1, 1), b3 + hb2, voffB);
;             PG8_WAIT_V(6); PG8_BAR; PG8_MMA(1, 1, At, B1); PG8_BAR;
	s_waitcnt lgkmcnt(0)
	s_setprio 1
	s_waitcnt lgkmcnt(0)
	v_mfma_f32_16x16x32_bf16 v[104:107], v[92:95], v[180:183], v[104:107]
	v_mfma_f32_16x16x32_bf16 v[136:139], v[172:175], v[180:183], v[136:139]
	v_mfma_f32_16x16x32_bf16 v[84:87], v[92:95], v[208:211], v[84:87]
	v_mfma_f32_16x16x32_bf16 v[128:131], v[172:175], v[208:211], v[128:131]
	v_mfma_f32_16x16x32_bf16 v[76:79], v[92:95], v[216:219], v[76:79]
	v_mfma_f32_16x16x32_bf16 v[120:123], v[172:175], v[216:219], v[120:123]
	v_mfma_f32_16x16x32_bf16 v[68:71], v[92:95], v[224:227], v[68:71]
	v_mfma_f32_16x16x32_bf16 v[112:115], v[172:175], v[224:227], v[112:115]
	v_mfma_f32_16x16x32_bf16 v[104:107], v[96:99], v[204:207], v[104:107]
	v_mfma_f32_16x16x32_bf16 v[136:139], v[176:179], v[204:207], v[136:139]
	v_mfma_f32_16x16x32_bf16 v[84:87], v[96:99], v[212:215], v[84:87]
	v_mfma_f32_16x16x32_bf16 v[128:131], v[176:179], v[212:215], v[128:131]
	v_mfma_f32_16x16x32_bf16 v[76:79], v[96:99], v[220:223], v[76:79]
	v_mfma_f32_16x16x32_bf16 v[120:123], v[176:179], v[220:223], v[120:123]
	v_mfma_f32_16x16x32_bf16 v[68:71], v[96:99], v[228:231], v[68:71]
	v_mfma_f32_16x16x32_bf16 v[112:115], v[176:179], v[228:231], v[112:115]
	s_setprio 0
	s_barrier
	s_add_i32 s20, 0, 0x1c000
	s_add_i32 s10, s27, s90
	v_add_u32_e32 v190, s20, v156
	v_lshl_add_u64 v[154:155], v[154:155], 0, s[28:29]
	s_mov_b32 m0, s10
	ds_read_b128 v[232:235], v190
	ds_read_b128 v[236:239], v190 offset:1024
	ds_read_b128 v[240:243], v190 offset:2048
	ds_read_b128 v[244:247], v190 offset:3072
	global_load_lds_dwordx4 v[154:155], off
	v_lshl_add_u64 v[154:155], v[184:185], 0, s[28:29]
	s_add_i32 m0, s10, 0x2000
	s_nop 0
	global_load_lds_dwordx4 v[154:155], off
	s_waitcnt vmcnt(10)
	s_barrier
	s_waitcnt lgkmcnt(0)
	s_setprio 1
	s_waitcnt lgkmcnt(0)
	v_mfma_f32_16x16x32_bf16 v[132:135], v[232:235], v[180:183], v[132:135]
	v_mfma_f32_16x16x32_bf16 v[100:103], v[240:243], v[180:183], v[100:103]
	v_mfma_f32_16x16x32_bf16 v[124:127], v[232:235], v[208:211], v[124:127]
	v_mfma_f32_16x16x32_bf16 v[80:83], v[240:243], v[208:211], v[80:83]
	v_mfma_f32_16x16x32_bf16 v[116:119], v[232:235], v[216:219], v[116:119]
	v_mfma_f32_16x16x32_bf16 v[72:75], v[240:243], v[216:219], v[72:75]
	v_mfma_f32_16x16x32_bf16 v[108:111], v[232:235], v[224:227], v[108:111]
	v_mfma_f32_16x16x32_bf16 v[64:67], v[240:243], v[224:227], v[64:67]
	v_mfma_f32_16x16x32_bf16 v[132:135], v[236:239], v[204:207], v[132:135]
	v_mfma_f32_16x16x32_bf16 v[100:103], v[244:247], v[204:207], v[100:103]
	v_mfma_f32_16x16x32_bf16 v[124:127], v[236:239], v[212:215], v[124:127]
	v_mfma_f32_16x16x32_bf16 v[80:83], v[244:247], v[212:215], v[80:83]
	v_mfma_f32_16x16x32_bf16 v[116:119], v[236:239], v[220:223], v[116:119]
	v_mfma_f32_16x16x32_bf16 v[72:75], v[244:247], v[220:223], v[72:75]
	v_mfma_f32_16x16x32_bf16 v[108:111], v[236:239], v[228:231], v[108:111]
	v_mfma_f32_16x16x32_bf16 v[64:67], v[244:247], v[228:231], v[64:67]
	s_setprio 0
	s_mov_b32 m0, s95
	v_lshl_add_u64 v[154:155], s[16:17], 0, v[160:161]
	s_barrier
	ds_read_b128 v[180:183], v171 offset:49152
	ds_read_b128 v[204:207], v171 offset:50176
	ds_read_b128 v[208:211], v171 offset:51200
	ds_read_b128 v[212:215], v171 offset:52224
	ds_read_b128 v[216:219], v171 offset:53248
	ds_read_b128 v[220:223], v171 offset:54272
	ds_read_b128 v[224:227], v171 offset:55296
	ds_read_b128 v[228:231], v171 offset:56320
	global_load_lds_dwordx4 v[154:155], off
	v_lshl_add_u64 v[154:155], s[16:17], 0, v[140:141]
	s_mov_b32 m0, s96
	s_nop 0
	global_load_lds_dwordx4 v[154:155], off
	s_waitcnt vmcnt(10)
	s_barrier
	s_waitcnt lgkmcnt(0)
	s_setprio 1
	s_waitcnt lgkmcnt(0)
	v_mfma_f32_16x16x32_bf16 v[28:31], v[92:95], v[180:183], v[28:31]
	v_mfma_f32_16x16x32_bf16 v[60:63], v[172:175], v[180:183], v[60:63]
	v_mfma_f32_16x16x32_bf16 v[20:23], v[92:95], v[208:211], v[20:23]
	v_mfma_f32_16x16x32_bf16 v[52:55], v[172:175], v[208:211], v[52:55]
	v_mfma_f32_16x16x32_bf16 v[12:15], v[92:95], v[216:219], v[12:15]
	v_mfma_f32_16x16x32_bf16 v[44:47], v[172:175], v[216:219], v[44:47]
	v_mfma_f32_16x16x32_bf16 v[4:7], v[92:95], v[224:227], v[4:7]
	v_mfma_f32_16x16x32_bf16 v[36:39], v[172:175], v[224:227], v[36:39]
	v_mfma_f32_16x16x32_bf16 v[28:31], v[96:99], v[204:207], v[28:31]
	v_mfma_f32_16x16x32_bf16 v[60:63], v[176:179], v[204:207], v[60:63]
	v_mfma_f32_16x16x32_bf16 v[20:23], v[96:99], v[212:215], v[20:23]
	v_mfma_f32_16x16x32_bf16 v[52:55], v[176:179], v[212:215], v[52:55]
	v_mfma_f32_16x16x32_bf16 v[12:15], v[96:99], v[220:223], v[12:15]
	v_mfma_f32_16x16x32_bf16 v[44:47], v[176:179], v[220:223], v[44:47]
	v_mfma_f32_16x16x32_bf16 v[4:7], v[96:99], v[228:231], v[4:7]
	v_mfma_f32_16x16x32_bf16 v[36:39], v[176:179], v[228:231], v[36:39]
	s_setprio 0
	s_barrier
	s_add_u32 s10, s14, 0x80080
	s_addc_u32 s11, s15, 0
	s_add_i32 s14, s20, s90
	v_lshl_add_u64 v[92:93], s[10:11], 0, v[160:161]
	s_mov_b32 m0, s14
	s_nop 0
	global_load_lds_dwordx4 v[92:93], off
	v_lshl_add_u64 v[92:93], s[10:11], 0, v[140:141]
	s_add_i32 m0, s14, 0x2000
	s_nop 0
	global_load_lds_dwordx4 v[92:93], off
	v_add_u32_e32 v154, 0x10000, v156
	ds_read_b128 v[92:95], v154
	ds_read_b128 v[96:99], v154 offset:1024
	ds_read_b128 v[172:175], v154 offset:2048
	ds_read_b128 v[176:179], v154 offset:3072
	s_waitcnt vmcnt(10)
	s_barrier
; #define PG8_MMA(ai, bj, At, Bt) do { __builtin_amdgcn_s_setprio(1); _Pragma("unroll") for (int m = 0; m < 4; ++m) _Pragma("unroll") for (int n = 0; n < 2; ++n) _Pragma("unroll") for (int k = 0; k < 2; ++k) \
;         acc[ai][bj][m][n] = __builtin_amdgcn_mfma_f32_16x16x32_bf16(Bt[n][k], At[m][k], acc[ai][bj][m][n], 0, 0, 0); __builtin_amdgcn_s_setprio(0); } while (0)
; #define PG8_WAIT_V(n) asm volatile("s_waitcnt vmcnt(" #n ")" ::: "memory")
; #define PG8_BAR __builtin_amdgcn_s_barrier()
;     ...
;             PG8_WAIT_V(6); PG8_BAR; PG8_MMA(1, 1, At, B1); PG8_BAR;
;         }
;     __device__ __forceinline__ void operator()(const f32x4 (&acc)[2][2][4][2], const Unit& u, int wr, int wc, int fr, int fq, int lane) const {
;         const int ch = u.pn * 64 + wc * 16 + 4 * fq;
;         const f32x4 w0 = *(const f32x4*)(cw + ch), w1 = *(const f32x4*)(cw + 4096 + ch), w2 = *(const f32x4*)(cw + 8192 + ch);
; #pragma unroll
;         for (int ai = 0; ai < 2; ++ai) {
;             f32x4 z[4], up[4], dn[4];
; #pragma unroll
;             for (int m = 0; m < 4; ++m) {
;                 z[m] = acc[ai][0][m][1] * acc[ai][1][m][0];
; #pragma unroll
;                 for (int j = 0; j < 4; ++j) { up[m][j] = __int_as_float(__builtin_amdgcn_update_dpp(0, __float_as_int(z[m][j]), 0x121, 0xF, 0xF, false));
;                                               dn[m][j] = __int_as_float(__builtin_amdgcn_update_dpp(0, __float_as_int(z[m][j]), 0x12F, 0xF, 0xF, false)); }
;             }
;             u32x2 wv[4];
; #pragma unroll
;             for (int m = 0; m < 4; ++m) {
;                 f32x4 zp, zn;
; #pragma unroll
;                 for (int j = 0; j < 4; ++j) {
;                     zp[j] = (fr > 0) ? up[m][j] : (m > 0 ? up[m > 0 ? m - 1 : 0][j] : 0.f);
;                     zn[j] = (fr < 15) ? dn[m][j] : (m < 3 ? dn[m < 3 ? m + 1 : 3][j] : 0.f);
	s_setprio 1
	v_mfma_f32_16x16x32_bf16 v[56:59], v[232:235], v[180:183], v[56:59]
	v_mfma_f32_16x16x32_bf16 v[24:27], v[240:243], v[180:183], v[24:27]
	v_mfma_f32_16x16x32_bf16 v[48:51], v[232:235], v[208:211], v[48:51]
	v_mfma_f32_16x16x32_bf16 v[16:19], v[240:243], v[208:211], v[16:19]
	v_mfma_f32_16x16x32_bf16 v[40:43], v[232:235], v[216:219], v[40:43]
	v_mfma_f32_16x16x32_bf16 v[8:11], v[240:243], v[216:219], v[8:11]
	v_mfma_f32_16x16x32_bf16 v[32:35], v[232:235], v[224:227], v[32:35]
	v_mfma_f32_16x16x32_bf16 v[0:3], v[240:243], v[224:227], v[0:3]
	v_mfma_f32_16x16x32_bf16 v[56:59], v[236:239], v[204:207], v[56:59]
	v_mfma_f32_16x16x32_bf16 v[24:27], v[244:247], v[204:207], v[24:27]
	v_mfma_f32_16x16x32_bf16 v[48:51], v[236:239], v[212:215], v[48:51]
	v_mfma_f32_16x16x32_bf16 v[16:19], v[244:247], v[212:215], v[16:19]
	v_mfma_f32_16x16x32_bf16 v[40:43], v[236:239], v[220:223], v[40:43]
	v_mfma_f32_16x16x32_bf16 v[8:11], v[244:247], v[220:223], v[8:11]
	v_mfma_f32_16x16x32_bf16 v[32:35], v[236:239], v[228:231], v[32:35]
	v_mfma_f32_16x16x32_bf16 v[0:3], v[244:247], v[228:231], v[0:3]
	s_setprio 0
	s_add_i32 s9, s9, 2
	s_add_u32 vcc_lo, vcc_lo, 0x100
	s_addc_u32 vcc_hi, vcc_hi, 0
	s_cmp_gt_u32 s9, 29
	s_barrier
	s_cbranch_scc0 .LBB0_234
	s_waitcnt lgkmcnt(0)
	s_nop 0
	v_lshl_or_b32 v154, s5, 6, v158
	v_ashrrev_i32_e32 v155, 31, v154
	v_lshlrev_b64 v[92:93], 2, v[154:155]
	v_lshl_add_u64 v[88:89], v[142:143], 0, v[92:93]
	v_lshl_add_u64 v[90:91], v[144:145], 0, v[92:93]
	global_load_dwordx4 v[96:99], v[88:89], off
	s_nop 0
	global_load_dwordx4 v[88:91], v[90:91], off
	v_lshl_add_u64 v[92:93], v[146:147], 0, v[92:93]
	global_load_dwordx4 v[92:95], v[92:93], off
	v_pk_mul_f32 v[134:135], v[138:139], v[134:135]
	v_mov_b32_e32 v172, v161
	v_mov_b32_e32 v174, v161
	v_mov_b32_e32 v173, v161
	v_mov_b32_dpp v172, v134 row_ror:1 row_mask:0xf bank_mask:0xf
	v_mov_b32_dpp v174, v135 row_ror:1 row_mask:0xf bank_mask:0xf
	v_mov_b32_e32 v175, v161
	v_pk_mul_f32 v[126:127], v[130:131], v[126:127]
	v_mov_b32_e32 v177, v161
	v_mov_b32_e32 v179, v161
	v_pk_mul_f32 v[116:117], v[120:121], v[116:117]
	v_cndmask_b32_e64 v120, v172, 0, s[42:43]
	v_cndmask_b32_e64 v121, v174, 0, s[42:43]
	v_mov_b32_dpp v173, v134 row_ror:15 row_mask:0xf bank_mask:0xf
	v_mov_b32_dpp v175, v135 row_ror:15 row_mask:0xf bank_mask:0xf
	v_mov_b32_dpp v177, v126 row_ror:15 row_mask:0xf bank_mask:0xf
	v_mov_b32_dpp v179, v127 row_ror:15 row_mask:0xf bank_mask:0xf
	v_pk_mul_f32 v[132:133], v[136:137], v[132:133]
	v_mov_b32_e32 v136, v161
	v_mov_b32_e32 v138, v161
	v_pk_mul_f32 v[118:119], v[122:123], v[118:119]
	v_cndmask_b32_e64 v122, v173, v177, s[44:45]
	v_cndmask_b32_e64 v123, v175, v179, s[44:45]
	v_mov_b32_dpp v136, v132 row_ror:1 row_mask:0xf bank_mask:0xf
	v_mov_b32_dpp v138, v133 row_ror:1 row_mask:0xf bank_mask:0xf
	v_mov_b32_e32 v137, v161
	v_mov_b32_e32 v139, v161
	v_pk_mul_f32 v[124:125], v[128:129], v[124:125]
	v_mov_b32_e32 v129, v161
	v_mov_b32_e32 v131, v161
	v_pk_mul_f32 v[108:109], v[112:113], v[108:109]
	v_cndmask_b32_e64 v112, v136, 0, s[42:43]
	v_cndmask_b32_e64 v113, v138, 0, s[42:43]
	v_mov_b32_dpp v137, v132 row_ror:15 row_mask:0xf bank_mask:0xf
	v_mov_b32_dpp v139, v133 row_ror:15 row_mask:0xf bank_mask:0xf
	v_mov_b32_dpp v129, v124 row_ror:15 row_mask:0xf bank_mask:0xf
	v_mov_b32_dpp v131, v125 row_ror:15 row_mask:0xf bank_mask:0xf
	v_pk_mul_f32 v[110:111], v[114:115], v[110:111]
	v_cndmask_b32_e64 v114, v137, v129, s[44:45]
	v_cndmask_b32_e64 v115, v139, v131, s[44:45]
	v_mov_b32_e32 v176, v161
	v_mov_b32_e32 v178, v161
	v_mov_b32_e32 v185, v161
	v_mov_b32_dpp v176, v126 row_ror:1 row_mask:0xf bank_mask:0xf
	v_mov_b32_dpp v178, v127 row_ror:1 row_mask:0xf bank_mask:0xf
	v_mov_b32_e32 v191, v161
	v_mov_b32_dpp v185, v118 row_ror:15 row_mask:0xf bank_mask:0xf
	v_mov_b32_e32 v128, v161
	v_mov_b32_dpp v191, v119 row_ror:15 row_mask:0xf bank_mask:0xf
	v_mov_b32_e32 v130, v161
	v_mov_b32_dpp v128, v124 row_ror:1 row_mask:0xf bank_mask:0xf
	v_mov_b32_e32 v181, v161
	v_mov_b32_dpp v130, v125 row_ror:1 row_mask:0xf bank_mask:0xf
	v_mov_b32_e32 v183, v161
	v_mov_b32_dpp v181, v116 row_ror:15 row_mask:0xf bank_mask:0xf
	v_mov_b32_e32 v184, v161
	v_mov_b32_dpp v183, v117 row_ror:15 row_mask:0xf bank_mask:0xf
	v_mov_b32_e32 v190, v161
	v_mov_b32_dpp v184, v118 row_ror:1 row_mask:0xf bank_mask:0xf
	v_mov_b32_e32 v209, v161
	v_mov_b32_dpp v190, v119 row_ror:1 row_mask:0xf bank_mask:0xf
	v_mov_b32_e32 v211, v161
	v_mov_b32_dpp v209, v110 row_ror:15 row_mask:0xf bank_mask:0xf
	v_mov_b32_e32 v180, v161
	v_mov_b32_dpp v211, v111 row_ror:15 row_mask:0xf bank_mask:0xf
	v_mov_b32_e32 v182, v161
	v_mov_b32_dpp v180, v116 row_ror:1 row_mask:0xf bank_mask:0xf
	v_mov_b32_e32 v205, v161
	v_mov_b32_dpp v182, v117 row_ror:1 row_mask:0xf bank_mask:0xf
	v_mov_b32_e32 v207, v161
	v_mov_b32_dpp v205, v108 row_ror:15 row_mask:0xf bank_mask:0xf
	v_mov_b32_e32 v208, v161
	v_mov_b32_dpp v207, v109 row_ror:15 row_mask:0xf bank_mask:0xf
	v_mov_b32_e32 v210, v161
	v_mov_b32_dpp v208, v110 row_ror:1 row_mask:0xf bank_mask:0xf
	v_mov_b32_e32 v204, v161
	s_waitcnt vmcnt(0)
; __device__ __forceinline__ unsigned cvt_pk_bf16(float lo, float hi) { unsigned r; asm volatile("v_cvt_pk_bf16_f32 %0, %1, %2" : "=v"(r) : "v"(lo), "v"(hi)); return r; }
; __device__ __forceinline__ float silu_f(float x) { return x * __builtin_amdgcn_rcpf(1.f + __expf(-x)); }
;     __device__ __forceinline__ void operator()(const f32x4 (&acc)[2][2][4][2], const Unit& u, int wr, int wc, int fr, int fq, int lane) const {
;     ...
;             for (int m = 0; m < 4; ++m) {
;                 f32x4 zp, zn;
; #pragma unroll
;                 for (int j = 0; j < 4; ++j) {
;                     zp[j] = (fr > 0) ? up[m][j] : (m > 0 ? up[m > 0 ? m - 1 : 0][j] : 0.f);
;                     zn[j] = (fr < 15) ? dn[m][j] : (m < 3 ? dn[m < 3 ? m + 1 : 3][j] : 0.f);
;                 }
;                 f32x4 y = w0 * zp + w1 * z[m] + w2 * zn;
;                 const f32x4 bg = acc[ai][0][m][0], g = acc[ai][1][m][1];
; #pragma unroll
;                 for (int j = 0; j < 4; ++j) y[j] = y[j] * bg[j] * silu_f(g[j]);
;                 wv[m].x = cvt_pk_bf16(y[0], y[1]); wv[m].y = cvt_pk_bf16(y[2], y[3]);
;             }
;             if (u.pm < 128) {
	v_pk_mul_f32 v[120:121], v[98:99], v[120:121]
	v_pk_mul_f32 v[112:113], v[96:97], v[112:113]
	v_pk_fma_f32 v[120:121], v[134:135], v[90:91], v[120:121]
	v_mul_f32_e32 v134, 0xbfb8aa3b, v100
	v_exp_f32_e32 v134, v134
	v_pk_fma_f32 v[120:121], v[94:95], v[122:123], v[120:121]
	v_mov_b32_e32 v122, v100
	v_mul_f32_e32 v100, 0xbfb8aa3b, v101
	v_exp_f32_e32 v100, v100
	v_pk_fma_f32 v[112:113], v[132:133], v[88:89], v[112:113]
	v_mov_b32_e32 v123, v104
	v_pk_fma_f32 v[112:113], v[92:93], v[114:115], v[112:113]
	v_add_f32_e32 v114, 1.0, v134
	v_rcp_f32_e32 v114, v114
	v_add_f32_e32 v100, 1.0, v100
	v_mov_b32_e32 v115, v112
	v_rcp_f32_e32 v112, v100
	v_pk_mul_f32 v[114:115], v[122:123], v[114:115]
	v_mul_f32_e32 v100, 0xbfb8aa3b, v102
	v_mov_b32_e32 v104, v101
	v_mul_f32_e32 v114, v114, v115
	v_exp_f32_e32 v115, v100
	v_pk_mul_f32 v[100:101], v[104:105], v[112:113]
	v_mov_b32_e32 v104, v102
	v_mul_f32_e32 v112, v100, v101
	v_mul_f32_e32 v101, 0xbfb8aa3b, v103
	v_exp_f32_e32 v113, v101
	v_add_f32_e32 v100, 1.0, v115
	v_rcp_f32_e32 v100, v100
	v_mov_b32_e32 v101, v120
	v_add_f32_e32 v102, 1.0, v113
	v_rcp_f32_e32 v120, v102
	v_mov_b32_e32 v105, v106
	v_pk_mul_f32 v[100:101], v[104:105], v[100:101]
	v_mov_b32_e32 v106, v103
	v_mul_f32_e32 v102, v100, v101
	v_pk_mul_f32 v[100:101], v[106:107], v[120:121]
	v_cndmask_b32_e64 v106, v176, v172, s[42:43]
	v_cndmask_b32_e64 v107, v178, v174, s[42:43]
	v_pk_mul_f32 v[106:107], v[98:99], v[106:107]
	v_mul_f32_e32 v101, v100, v101
	v_cvt_pk_bf16_f32 v100, v114, v112
	v_cndmask_b32_e64 v112, v177, v185, s[44:45]
	v_cndmask_b32_e64 v113, v179, v191, s[44:45]
	v_pk_fma_f32 v[106:107], v[126:127], v[90:91], v[106:107]
	v_mul_f32_e32 v114, 0xbfb8aa3b, v80
	v_exp_f32_e32 v114, v114
	v_pk_fma_f32 v[106:107], v[94:95], v[112:113], v[106:107]
	v_mov_b32_e32 v112, v80
	v_mul_f32_e32 v80, 0xbfb8aa3b, v81
	v_cvt_pk_bf16_f32 v101, v102, v101
	v_cndmask_b32_e64 v102, v128, v136, s[42:43]
	v_cndmask_b32_e64 v103, v130, v138, s[42:43]
	v_exp_f32_e32 v80, v80
	v_pk_mul_f32 v[102:103], v[96:97], v[102:103]
	v_cndmask_b32_e64 v104, v129, v181, s[44:45]
	v_cndmask_b32_e64 v105, v131, v183, s[44:45]
	v_pk_fma_f32 v[102:103], v[124:125], v[88:89], v[102:103]
	v_add_f32_e32 v80, 1.0, v80
	v_pk_fma_f32 v[102:103], v[92:93], v[104:105], v[102:103]
	v_add_f32_e32 v104, 1.0, v114
	v_rcp_f32_e32 v104, v104
	v_mov_b32_e32 v105, v102
	v_rcp_f32_e32 v102, v80
	v_mov_b32_e32 v113, v84
	v_pk_mul_f32 v[104:105], v[112:113], v[104:105]
	v_mul_f32_e32 v80, 0xbfb8aa3b, v82
	v_mov_b32_e32 v84, v81
	v_mul_f32_e32 v104, v104, v105
	v_exp_f32_e32 v105, v80
	v_pk_mul_f32 v[80:81], v[84:85], v[102:103]
	v_mov_b32_e32 v84, v82
	v_mul_f32_e32 v102, v80, v81
	v_mul_f32_e32 v81, 0xbfb8aa3b, v83
	v_exp_f32_e32 v103, v81
	v_add_f32_e32 v80, 1.0, v105
	v_rcp_f32_e32 v80, v80
	v_mov_b32_e32 v81, v106
	v_add_f32_e32 v82, 1.0, v103
	v_rcp_f32_e32 v106, v82
	v_mov_b32_e32 v85, v86
	v_pk_mul_f32 v[80:81], v[84:85], v[80:81]
	v_mov_b32_e32 v86, v83
	v_mul_f32_e32 v82, v80, v81
	v_pk_mul_f32 v[80:81], v[86:87], v[106:107]
	v_cndmask_b32_e64 v86, v184, v176, s[42:43]
	v_cndmask_b32_e64 v87, v190, v178, s[42:43]
	v_pk_mul_f32 v[86:87], v[98:99], v[86:87]
	v_mul_f32_e32 v81, v80, v81
	v_cvt_pk_bf16_f32 v80, v104, v102
	v_cndmask_b32_e64 v102, v185, v209, s[44:45]
	v_cndmask_b32_e64 v103, v191, v211, s[44:45]
	v_pk_fma_f32 v[86:87], v[118:119], v[90:91], v[86:87]
	v_mul_f32_e32 v104, 0xbfb8aa3b, v72
	v_exp_f32_e32 v104, v104
	v_pk_fma_f32 v[86:87], v[94:95], v[102:103], v[86:87]
	v_mov_b32_e32 v102, v72
	v_mul_f32_e32 v72, 0xbfb8aa3b, v73
	v_cvt_pk_bf16_f32 v81, v82, v81
	v_cndmask_b32_e64 v82, v180, v128, s[42:43]
	v_cndmask_b32_e64 v83, v182, v130, s[42:43]
	v_exp_f32_e32 v72, v72
	v_pk_mul_f32 v[82:83], v[96:97], v[82:83]
	v_cndmask_b32_e64 v84, v181, v205, s[44:45]
	v_cndmask_b32_e64 v85, v183, v207, s[44:45]
	v_pk_fma_f32 v[82:83], v[116:117], v[88:89], v[82:83]
	v_add_f32_e32 v72, 1.0, v72
	v_pk_fma_f32 v[82:83], v[92:93], v[84:85], v[82:83]
	v_add_f32_e32 v84, 1.0, v104
	v_rcp_f32_e32 v84, v84
	v_mov_b32_e32 v85, v82
	v_rcp_f32_e32 v82, v72
	v_mov_b32_e32 v103, v76
	v_pk_mul_f32 v[84:85], v[102:103], v[84:85]
	v_mul_f32_e32 v72, 0xbfb8aa3b, v74
	v_mov_b32_e32 v76, v73
	v_mul_f32_e32 v84, v84, v85
	v_exp_f32_e32 v85, v72
	v_pk_mul_f32 v[72:73], v[76:77], v[82:83]
	v_mov_b32_e32 v76, v74
	v_mul_f32_e32 v82, v72, v73
	v_mul_f32_e32 v73, 0xbfb8aa3b, v75
	v_exp_f32_e32 v83, v73
	v_add_f32_e32 v72, 1.0, v85
	v_rcp_f32_e32 v72, v72
	v_mov_b32_e32 v73, v86
	v_add_f32_e32 v74, 1.0, v83
	v_rcp_f32_e32 v86, v74
	v_mov_b32_e32 v77, v78
	v_mov_b32_dpp v210, v111 row_ror:1 row_mask:0xf bank_mask:0xf
	v_pk_mul_f32 v[72:73], v[76:77], v[72:73]
	v_mov_b32_e32 v78, v75
	v_mul_f32_e32 v74, v72, v73
	v_pk_mul_f32 v[72:73], v[78:79], v[86:87]
	v_cndmask_b32_e64 v78, v208, v184, s[42:43]
	v_cndmask_b32_e64 v79, v210, v190, s[42:43]
	v_pk_mul_f32 v[78:79], v[98:99], v[78:79]
	v_mov_b32_e32 v206, v161
	v_mul_f32_e32 v73, v72, v73
	v_cvt_pk_bf16_f32 v72, v84, v82
	v_cndmask_b32_e64 v82, v209, 0, s[44:45]
	v_cndmask_b32_e64 v83, v211, 0, s[44:45]
	v_pk_fma_f32 v[78:79], v[110:111], v[90:91], v[78:79]
	v_mul_f32_e32 v84, 0xbfb8aa3b, v64
	v_mov_b32_dpp v204, v108 row_ror:1 row_mask:0xf bank_mask:0xf
	v_mov_b32_dpp v206, v109 row_ror:1 row_mask:0xf bank_mask:0xf
	v_exp_f32_e32 v84, v84
	v_pk_fma_f32 v[78:79], v[94:95], v[82:83], v[78:79]
	v_mov_b32_e32 v82, v64
	v_mul_f32_e32 v64, 0xbfb8aa3b, v65
	v_cvt_pk_bf16_f32 v73, v74, v73
	v_cndmask_b32_e64 v74, v204, v180, s[42:43]
	v_cndmask_b32_e64 v75, v206, v182, s[42:43]
	v_exp_f32_e32 v64, v64
	v_pk_mul_f32 v[74:75], v[96:97], v[74:75]
	v_cndmask_b32_e64 v76, v205, 0, s[44:45]
	v_cndmask_b32_e64 v77, v207, 0, s[44:45]
	v_pk_fma_f32 v[74:75], v[108:109], v[88:89], v[74:75]
	v_add_f32_e32 v64, 1.0, v64
	v_pk_fma_f32 v[74:75], v[92:93], v[76:77], v[74:75]
	v_add_f32_e32 v76, 1.0, v84
	v_rcp_f32_e32 v76, v76
	v_mov_b32_e32 v77, v74
	v_rcp_f32_e32 v74, v64
	v_mov_b32_e32 v83, v68
	v_pk_mul_f32 v[76:77], v[82:83], v[76:77]
	v_mul_f32_e32 v64, 0xbfb8aa3b, v66
	v_mov_b32_e32 v68, v65
	v_mul_f32_e32 v76, v76, v77
	v_exp_f32_e32 v77, v64
	v_pk_mul_f32 v[64:65], v[68:69], v[74:75]
	v_mov_b32_e32 v68, v66
	v_mul_f32_e32 v74, v64, v65
	v_mul_f32_e32 v65, 0xbfb8aa3b, v67
	v_exp_f32_e32 v75, v65
	v_add_f32_e32 v64, 1.0, v77
	v_rcp_f32_e32 v64, v64
	v_mov_b32_e32 v65, v78
	v_add_f32_e32 v66, 1.0, v75
	v_rcp_f32_e32 v78, v66
	s_cmpk_gt_i32 s36, 0x7f
	v_mov_b32_e32 v69, v70
	s_cselect_b64 s[38:39], -1, 0
	s_lshl_b32 s3, s36, 2
	v_pk_mul_f32 v[64:65], v[68:69], v[64:65]
	v_mov_b32_e32 v70, v67
	s_add_i32 s3, s4, s3
	v_mul_f32_e32 v68, v64, v65
	v_pk_mul_f32 v[64:65], v[70:71], v[78:79]
	s_and_b64 vcc, exec, s[38:39]
	v_mul_f32_e32 v64, v64, v65
	v_cvt_pk_bf16_f32 v66, v76, v74
	v_cvt_pk_bf16_f32 v67, v68, v64
	s_cbranch_vccz .LBB0_241
;     __device__ __forceinline__ void operator()(const f32x4 (&acc)[2][2][4][2], const Unit& u, int wr, int wc, int fr, int fq, int lane) const {
;     ...
;             } else {
;                 const int gidx = (u.pm - 128) * 4 + ai * 2 + wr, b = gidx / 5, g5 = gidx - b * 5, t0 = 62 * g5 - 1;
;                 bf16_t* p = O + ((size_t)(TL + b * 256 + t0 + fr)) * 4096 + ch;
; #pragma unroll
;                 for (int m = 0; m < 4; ++m) { const int i2 = m * 16 + fr; if (i2 >= 1 && i2 <= 62 && t0 + i2 < 256) *(u32x2*)(p + (size_t)(m * 16) * 4096) = wv[m]; }
;             }
	s_mul_hi_i32 s5, s3, 0x66666667
	s_lshr_b32 s6, s5, 31
	s_ashr_i32 s5, s5, 1
	s_add_i32 s6, s5, s6
	s_mul_i32 s5, s6, -5
	s_add_i32 s5, s5, s3
	s_mul_i32 s5, s5, 62
	s_lshl_b32 s6, s6, 8
	s_add_i32 s6, s5, s6
	v_add_u32_e32 v64, s6, v170
	v_ashrrev_i32_e32 v65, 31, v64
	v_lshlrev_b64 v[68:69], 13, v[64:65]
	v_lshl_add_u64 v[64:65], s[24:25], 0, v[68:69]
	v_cmp_le_i32_e32 vcc, s5, v157
	v_lshl_add_u64 v[64:65], v[154:155], 1, v[64:65]
	s_and_b64 s[6:7], s[46:47], vcc
	s_and_saveexec_b64 s[14:15], s[6:7]
	s_cbranch_execnz .LBB0_256
	s_or_b64 exec, exec, s[14:15]
	v_cmp_le_i32_e32 vcc, s5, v159
	s_and_saveexec_b64 s[14:15], vcc
	s_cbranch_execnz .LBB0_257

; #define PG8_STAGE(bufoff, gbase, voff) do { _Pragma("unroll") for (int _i = 0; _i < 2; ++_i) \
;         __builtin_amdgcn_global_load_lds((const unsigned*)((const char*)(gbase) + (voff)[_i]), (LAS unsigned*)(lds + (bufoff) + ldsw + _i * 8192), 16, 0, 0); } while (0)
; #define PG8_STAGE_A(bufoff, ptr, half, rev) do { if (REVA && (rev)) { const char* _p = (ptr) - ((half) ? hstepA : 0); PG8_STAGE(bufoff, _p, voffAr); } else { const char* _p = (ptr) + ((half) ? hstepA : 0); PG8_STAGE(bufoff, _p, voffA); } } while (0)
; #define PG8_LDA(dst, b, h) do { _Pragma("unroll") for (int m = 0; m < 4; ++m) _Pragma("unroll") for (int k = 0; k < 2; ++k) dst[m][k] = *(const LAS bf16x8*)(lds + PG8_SA(b, h) + aoff + m * 2048 + k * 1024); } while (0)
; #define PG8_LDB(dst, b, h) do { _Pragma("unroll") for (int n = 0; n < 2; ++n) _Pragma("unroll") for (int k = 0; k < 2; ++k) dst[n][k] = *(const LAS bf16x8*)(lds + PG8_SB(b, h) + boff + n * 2048 + k * 1024); } while (0)
; #define PG8_WAIT_V(n) asm volatile("s_waitcnt vmcnt(" #n ")" ::: "memory")
; #define PG8_WAIT_L(n) asm volatile("s_waitcnt lgkmcnt(" #n ")" ::: "memory")
; #define PG8_BAR __builtin_amdgcn_s_barrier()
;     ...
;         for (int t = 0; t < nt; t += 2) {
;             const bool last = (t == nt - 2);
;             const char* a1 = PG8_APTR(cA, cAr, t + 1); const bool r1 = REVA && ((t + 1) & 4);
;             const char* a2 = last ? nA : PG8_APTR(cA, cAr, t + 2); const bool r2 = REVA && !last && ((t + 2) & 4);
;             const char* a3 = last ? nA + kstep : PG8_APTR(cA, cAr, t + 3); const bool r3 = REVA && !last && ((t + 3) & 4);
;             const char* b2 = last ? nB : cB + (size_t)(t + 2) * kstep; const char* b3 = b2 + kstep; const size_t hb2 = last ? nHb : cHb;
;             PG8_LDB(B0, 0, 0); PG8_SCHED; PG8_LDA(At, 0, 0); PG8_STAGE_A(PG8_SA(1, 1), a1, 1, r1);
;             PG8_WAIT_L(8); PG8_BAR; PG8_WAIT_L(0); PG8_MMA(0, 0, At, B0); PG8_BAR; PG8_SCHED;
;             PG8_LDB(B1, 0, 1); PG8_STAGE(PG8_SB(0, 0), b2, voffB);
;             PG8_BAR; PG8_WAIT_L(0); PG8_MMA(0, 1, At, B1); PG8_BAR;
;             PG8_LDA(At, 0, 1); PG8_STAGE_A(PG8_SA(0, 0), a2, 0, r2);
;             PG8_BAR; PG8_WAIT_L(0); PG8_MMA(1, 0, At, B0); PG8_BAR; PG8_SCHED;
;             PG8_STAGE(PG8_SB(0, 1), b2 + hb2, voffB);
;             PG8_WAIT_V(6); PG8_BAR; PG8_MMA(1, 1, At, B1); PG8_BAR;
.LBB0_335:
	s_add_u32 s10, s44, s46
	s_addc_u32 s11, s45, s47
	s_add_u32 s16, s10, 0x100
	s_addc_u32 s17, s11, 0
	s_add_u32 s10, s10, 0x180
	s_addc_u32 s11, s11, 0
	s_add_u32 s14, s27, s46
	s_addc_u32 s15, s91, s47
	s_add_i32 s93, 0, 0x10000
	s_cmpk_eq_i32 s46, 0x1f00
	s_cselect_b32 s15, s39, s15
	s_cselect_b32 s14, s38, s14
	s_cselect_b32 s21, s37, s17
	s_cselect_b32 s20, s36, s16
	s_cselect_b32 s17, s9, s11
	s_cselect_b32 s16, s3, s10
	v_lshl_add_u64 v[154:155], v[128:129], 0, s[46:47]
	s_add_i32 m0, s1, 0xc000
	ds_read_b128 v[172:175], v158
	ds_read_b128 v[176:179], v158 offset:1024
	ds_read_b128 v[180:183], v158 offset:2048
	ds_read_b128 v[204:207], v158 offset:3072
	ds_read_b128 v[208:211], v158 offset:4096
	ds_read_b128 v[212:215], v158 offset:5120
	ds_read_b128 v[216:219], v158 offset:6144
	ds_read_b128 v[220:223], v158 offset:7168
	global_load_lds_dwordx4 v[154:155], off
	v_lshl_add_u64 v[154:155], v[130:131], 0, s[46:47]
	s_add_i32 m0, s1, 0xe000
	s_nop 0
	global_load_lds_dwordx4 v[154:155], off
	s_waitcnt lgkmcnt(8)
	s_waitcnt vmcnt(10)
	s_barrier
	s_waitcnt lgkmcnt(0)
	s_setprio 1
	s_waitcnt lgkmcnt(0)
	v_mfma_f32_16x16x32_bf16 v[124:127], v[132:135], v[172:175], v[124:127]
	v_mfma_f32_16x16x32_bf16 v[120:123], v[140:143], v[172:175], v[120:123]
	v_mfma_f32_16x16x32_bf16 v[116:119], v[132:135], v[180:183], v[116:119]
	v_mfma_f32_16x16x32_bf16 v[108:111], v[140:143], v[180:183], v[108:111]
	v_mfma_f32_16x16x32_bf16 v[92:95], v[132:135], v[208:211], v[92:95]
	v_mfma_f32_16x16x32_bf16 v[88:91], v[140:143], v[208:211], v[88:91]
	v_mfma_f32_16x16x32_bf16 v[84:87], v[132:135], v[216:219], v[84:87]
	v_mfma_f32_16x16x32_bf16 v[76:79], v[140:143], v[216:219], v[76:79]
	v_mfma_f32_16x16x32_bf16 v[124:127], v[136:139], v[176:179], v[124:127]
	v_mfma_f32_16x16x32_bf16 v[120:123], v[168:171], v[176:179], v[120:123]
	v_mfma_f32_16x16x32_bf16 v[116:119], v[136:139], v[204:207], v[116:119]
	v_mfma_f32_16x16x32_bf16 v[108:111], v[168:171], v[204:207], v[108:111]
	v_mfma_f32_16x16x32_bf16 v[92:95], v[136:139], v[212:215], v[92:95]
	v_mfma_f32_16x16x32_bf16 v[88:91], v[168:171], v[212:215], v[88:91]
	v_mfma_f32_16x16x32_bf16 v[84:87], v[136:139], v[220:223], v[84:87]
	v_mfma_f32_16x16x32_bf16 v[76:79], v[168:171], v[220:223], v[76:79]
	s_setprio 0
	s_barrier
	s_add_i32 s94, 0, 0x14000
	v_add_u32_e32 v154, s94, v157
	s_add_i32 s10, s93, s52
	ds_read_b128 v[224:227], v154
	ds_read_b128 v[228:231], v154 offset:1024
	ds_read_b128 v[232:235], v154 offset:2048
	ds_read_b128 v[236:239], v154 offset:3072
	v_lshl_add_u64 v[154:155], s[14:15], 0, v[146:147]
	s_mov_b32 m0, s10
	v_lshl_add_u64 v[184:185], s[14:15], 0, v[144:145]
	global_load_lds_dwordx4 v[154:155], off
	s_add_i32 m0, s10, 0x2000
	s_nop 0
	global_load_lds_dwordx4 v[184:185], off
	s_waitcnt vmcnt(10)
	s_barrier
	s_waitcnt lgkmcnt(0)
	s_setprio 1
	s_waitcnt lgkmcnt(0)
	v_mfma_f32_16x16x32_bf16 v[112:115], v[224:227], v[172:175], v[112:115]
	v_mfma_f32_16x16x32_bf16 v[104:107], v[232:235], v[172:175], v[104:107]
	v_mfma_f32_16x16x32_bf16 v[100:103], v[224:227], v[180:183], v[100:103]
	v_mfma_f32_16x16x32_bf16 v[96:99], v[232:235], v[180:183], v[96:99]
	v_mfma_f32_16x16x32_bf16 v[80:83], v[224:227], v[208:211], v[80:83]
	v_mfma_f32_16x16x32_bf16 v[72:75], v[232:235], v[208:211], v[72:75]
	v_mfma_f32_16x16x32_bf16 v[68:71], v[224:227], v[216:219], v[68:71]
	v_mfma_f32_16x16x32_bf16 v[64:67], v[232:235], v[216:219], v[64:67]
	v_mfma_f32_16x16x32_bf16 v[112:115], v[228:231], v[176:179], v[112:115]
	v_mfma_f32_16x16x32_bf16 v[104:107], v[236:239], v[176:179], v[104:107]
	v_mfma_f32_16x16x32_bf16 v[100:103], v[228:231], v[204:207], v[100:103]
	v_mfma_f32_16x16x32_bf16 v[96:99], v[236:239], v[204:207], v[96:99]
	v_mfma_f32_16x16x32_bf16 v[80:83], v[228:231], v[212:215], v[80:83]
	v_mfma_f32_16x16x32_bf16 v[72:75], v[236:239], v[212:215], v[72:75]
	v_mfma_f32_16x16x32_bf16 v[68:71], v[228:231], v[220:223], v[68:71]
	v_mfma_f32_16x16x32_bf16 v[64:67], v[236:239], v[220:223], v[64:67]
	s_setprio 0
	s_mov_b32 m0, s1
	v_lshl_add_u64 v[190:191], s[20:21], 0, v[146:147]
	s_barrier
	ds_read_b128 v[172:175], v158 offset:16384
	ds_read_b128 v[176:179], v158 offset:17408
	ds_read_b128 v[180:183], v158 offset:18432
	ds_read_b128 v[204:207], v158 offset:19456
	ds_read_b128 v[208:211], v158 offset:20480
	ds_read_b128 v[212:215], v158 offset:21504
	ds_read_b128 v[216:219], v158 offset:22528
	ds_read_b128 v[220:223], v158 offset:23552
	global_load_lds_dwordx4 v[190:191], off
	v_lshl_add_u64 v[190:191], s[20:21], 0, v[144:145]
	s_mov_b32 m0, s53
	s_nop 0
	global_load_lds_dwordx4 v[190:191], off
	s_waitcnt vmcnt(10)
	s_barrier
	s_waitcnt lgkmcnt(0)
	s_setprio 1
	s_waitcnt lgkmcnt(0)
	v_mfma_f32_16x16x32_bf16 v[60:63], v[132:135], v[172:175], v[60:63]
	v_mfma_f32_16x16x32_bf16 v[56:59], v[140:143], v[172:175], v[56:59]
	v_mfma_f32_16x16x32_bf16 v[52:55], v[132:135], v[180:183], v[52:55]
	v_mfma_f32_16x16x32_bf16 v[44:47], v[140:143], v[180:183], v[44:47]
	v_mfma_f32_16x16x32_bf16 v[28:31], v[132:135], v[208:211], v[28:31]
	v_mfma_f32_16x16x32_bf16 v[24:27], v[140:143], v[208:211], v[24:27]
	v_mfma_f32_16x16x32_bf16 v[20:23], v[132:135], v[216:219], v[20:23]
	v_mfma_f32_16x16x32_bf16 v[12:15], v[140:143], v[216:219], v[12:15]
	v_mfma_f32_16x16x32_bf16 v[60:63], v[136:139], v[176:179], v[60:63]
	v_mfma_f32_16x16x32_bf16 v[56:59], v[168:171], v[176:179], v[56:59]
	v_mfma_f32_16x16x32_bf16 v[52:55], v[136:139], v[204:207], v[52:55]
	v_mfma_f32_16x16x32_bf16 v[44:47], v[168:171], v[204:207], v[44:47]
	v_mfma_f32_16x16x32_bf16 v[28:31], v[136:139], v[212:215], v[28:31]
	v_mfma_f32_16x16x32_bf16 v[24:27], v[168:171], v[212:215], v[24:27]
	v_mfma_f32_16x16x32_bf16 v[20:23], v[136:139], v[220:223], v[20:23]
	v_mfma_f32_16x16x32_bf16 v[12:15], v[168:171], v[220:223], v[12:15]
	s_setprio 0
	s_barrier
; #define PG8_STAGE(bufoff, gbase, voff) do { _Pragma("unroll") for (int _i = 0; _i < 2; ++_i) \
;         __builtin_amdgcn_global_load_lds((const unsigned*)((const char*)(gbase) + (voff)[_i]), (LAS unsigned*)(lds + (bufoff) + ldsw + _i * 8192), 16, 0, 0); } while (0)
; #define PG8_STAGE_A(bufoff, ptr, half, rev) do { if (REVA && (rev)) { const char* _p = (ptr) - ((half) ? hstepA : 0); PG8_STAGE(bufoff, _p, voffAr); } else { const char* _p = (ptr) + ((half) ? hstepA : 0); PG8_STAGE(bufoff, _p, voffA); } } while (0)
; #define PG8_LDA(dst, b, h) do { _Pragma("unroll") for (int m = 0; m < 4; ++m) _Pragma("unroll") for (int k = 0; k < 2; ++k) dst[m][k] = *(const LAS bf16x8*)(lds + PG8_SA(b, h) + aoff + m * 2048 + k * 1024); } while (0)
; #define PG8_LDB(dst, b, h) do { _Pragma("unroll") for (int n = 0; n < 2; ++n) _Pragma("unroll") for (int k = 0; k < 2; ++k) dst[n][k] = *(const LAS bf16x8*)(lds + PG8_SB(b, h) + boff + n * 2048 + k * 1024); } while (0)
; #define PG8_MMA(ai, bj, At, Bt) do { __builtin_amdgcn_s_setprio(1); _Pragma("unroll") for (int m = 0; m < 4; ++m) _Pragma("unroll") for (int n = 0; n < 2; ++n) _Pragma("unroll") for (int k = 0; k < 2; ++k) \
;         acc[ai][bj][m][n] = __builtin_amdgcn_mfma_f32_16x16x32_bf16(Bt[n][k], At[m][k], acc[ai][bj][m][n], 0, 0, 0); __builtin_amdgcn_s_setprio(0); } while (0)
; #define PG8_WAIT_V(n) asm volatile("s_waitcnt vmcnt(" #n ")" ::: "memory")
; #define PG8_WAIT_L(n) asm volatile("s_waitcnt lgkmcnt(" #n ")" ::: "memory")
; #define PG8_BAR __builtin_amdgcn_s_barrier()
; #define PG8_SCHED __builtin_amdgcn_sched_barrier(0)
;     ...
;             PG8_WAIT_V(6); PG8_BAR; PG8_MMA(1, 1, At, B1); PG8_BAR;
;             PG8_LDB(B0, 1, 0); PG8_SCHED; PG8_LDA(At, 1, 0); PG8_STAGE_A(PG8_SA(0, 1), a2, 1, r2);
;             PG8_WAIT_L(8); PG8_BAR; PG8_WAIT_L(0); PG8_MMA(0, 0, At, B0); PG8_BAR; PG8_SCHED;
;             PG8_LDB(B1, 1, 1); PG8_STAGE(PG8_SB(1, 0), b3, voffB);
;             PG8_BAR; PG8_WAIT_L(0); PG8_MMA(0, 1, At, B1); PG8_BAR;
;             PG8_LDA(At, 1, 1); PG8_STAGE_A(PG8_SA(1, 0), a3, 0, r3);
;             PG8_BAR; PG8_WAIT_L(0); PG8_MMA(1, 0, At, B0); PG8_BAR; PG8_SCHED;
	s_add_u32 s10, s14, 0x100000
	s_addc_u32 s11, s15, 0
	s_add_i32 s93, s94, s52
	v_lshl_add_u64 v[132:133], s[10:11], 0, v[146:147]
	s_mov_b32 m0, s93
	s_nop 0
	global_load_lds_dwordx4 v[132:133], off
	v_lshl_add_u64 v[132:133], s[10:11], 0, v[144:145]
	s_add_i32 m0, s93, 0x2000
	s_nop 0
	global_load_lds_dwordx4 v[132:133], off
	v_add_u32_e32 v159, 0x18000, v157
	ds_read_b128 v[132:135], v159
	ds_read_b128 v[136:139], v159 offset:1024
	ds_read_b128 v[140:143], v159 offset:2048
	ds_read_b128 v[168:171], v159 offset:3072
	s_waitcnt vmcnt(10)
	s_barrier
	s_setprio 1
	v_mfma_f32_16x16x32_bf16 v[48:51], v[224:227], v[172:175], v[48:51]
	v_mfma_f32_16x16x32_bf16 v[40:43], v[232:235], v[172:175], v[40:43]
	v_mfma_f32_16x16x32_bf16 v[36:39], v[224:227], v[180:183], v[36:39]
	v_mfma_f32_16x16x32_bf16 v[32:35], v[232:235], v[180:183], v[32:35]
	v_mfma_f32_16x16x32_bf16 v[16:19], v[224:227], v[208:211], v[16:19]
	v_mfma_f32_16x16x32_bf16 v[8:11], v[232:235], v[208:211], v[8:11]
	v_mfma_f32_16x16x32_bf16 v[4:7], v[224:227], v[216:219], v[4:7]
	v_mfma_f32_16x16x32_bf16 v[0:3], v[232:235], v[216:219], v[0:3]
	v_mfma_f32_16x16x32_bf16 v[48:51], v[228:231], v[176:179], v[48:51]
	v_mfma_f32_16x16x32_bf16 v[40:43], v[236:239], v[176:179], v[40:43]
	v_mfma_f32_16x16x32_bf16 v[36:39], v[228:231], v[204:207], v[36:39]
	v_mfma_f32_16x16x32_bf16 v[32:35], v[236:239], v[204:207], v[32:35]
	v_mfma_f32_16x16x32_bf16 v[16:19], v[228:231], v[212:215], v[16:19]
	v_mfma_f32_16x16x32_bf16 v[8:11], v[236:239], v[212:215], v[8:11]
	v_mfma_f32_16x16x32_bf16 v[4:7], v[228:231], v[220:223], v[4:7]
	v_mfma_f32_16x16x32_bf16 v[0:3], v[236:239], v[220:223], v[0:3]
	s_setprio 0
	s_add_i32 s93, 0, 0x18000
	s_barrier
	s_add_u32 s10, s20, 0x100000
	s_addc_u32 s11, s21, 0
	s_mov_b32 m0, s6
	v_lshl_add_u64 v[190:191], s[10:11], 0, v[146:147]
	ds_read_b128 v[172:175], v158 offset:32768
	ds_read_b128 v[176:179], v158 offset:33792
	ds_read_b128 v[180:183], v158 offset:34816
	ds_read_b128 v[204:207], v158 offset:35840
	ds_read_b128 v[208:211], v158 offset:36864
	ds_read_b128 v[212:215], v158 offset:37888
	ds_read_b128 v[216:219], v158 offset:38912
	ds_read_b128 v[220:223], v158 offset:39936
	global_load_lds_dwordx4 v[190:191], off
	v_lshl_add_u64 v[190:191], s[10:11], 0, v[144:145]
	s_mov_b32 m0, s7
	s_nop 0
	global_load_lds_dwordx4 v[190:191], off
	s_waitcnt lgkmcnt(8)
	s_waitcnt vmcnt(10)
	s_barrier
	s_waitcnt lgkmcnt(0)
	s_setprio 1
	s_waitcnt lgkmcnt(0)
	v_mfma_f32_16x16x32_bf16 v[124:127], v[132:135], v[172:175], v[124:127]
	v_mfma_f32_16x16x32_bf16 v[120:123], v[140:143], v[172:175], v[120:123]
	v_mfma_f32_16x16x32_bf16 v[116:119], v[132:135], v[180:183], v[116:119]
	v_mfma_f32_16x16x32_bf16 v[108:111], v[140:143], v[180:183], v[108:111]
	v_mfma_f32_16x16x32_bf16 v[92:95], v[132:135], v[208:211], v[92:95]
	v_mfma_f32_16x16x32_bf16 v[88:91], v[140:143], v[208:211], v[88:91]
	v_mfma_f32_16x16x32_bf16 v[84:87], v[132:135], v[216:219], v[84:87]
	v_mfma_f32_16x16x32_bf16 v[76:79], v[140:143], v[216:219], v[76:79]
	v_mfma_f32_16x16x32_bf16 v[124:127], v[136:139], v[176:179], v[124:127]
	v_mfma_f32_16x16x32_bf16 v[120:123], v[168:171], v[176:179], v[120:123]
	v_mfma_f32_16x16x32_bf16 v[116:119], v[136:139], v[204:207], v[116:119]
	v_mfma_f32_16x16x32_bf16 v[108:111], v[168:171], v[204:207], v[108:111]
	v_mfma_f32_16x16x32_bf16 v[92:95], v[136:139], v[212:215], v[92:95]
	v_mfma_f32_16x16x32_bf16 v[88:91], v[168:171], v[212:215], v[88:91]
	v_mfma_f32_16x16x32_bf16 v[84:87], v[136:139], v[220:223], v[84:87]
	v_mfma_f32_16x16x32_bf16 v[76:79], v[168:171], v[220:223], v[76:79]
	s_setprio 0
	s_barrier
	s_add_i32 s20, 0, 0x1c000
	s_add_i32 s10, s93, s52
	v_add_u32_e32 v159, s20, v157
	v_lshl_add_u64 v[154:155], v[154:155], 0, s[28:29]
	s_mov_b32 m0, s10
	ds_read_b128 v[224:227], v159
	ds_read_b128 v[228:231], v159 offset:1024
	ds_read_b128 v[232:235], v159 offset:2048
	ds_read_b128 v[236:239], v159 offset:3072
	global_load_lds_dwordx4 v[154:155], off
	v_lshl_add_u64 v[154:155], v[184:185], 0, s[28:29]
	s_add_i32 m0, s10, 0x2000
	s_nop 0
	global_load_lds_dwordx4 v[154:155], off
	s_waitcnt vmcnt(10)
	s_barrier
	s_waitcnt lgkmcnt(0)
	s_setprio 1
	s_waitcnt lgkmcnt(0)
	v_mfma_f32_16x16x32_bf16 v[112:115], v[224:227], v[172:175], v[112:115]
	v_mfma_f32_16x16x32_bf16 v[104:107], v[232:235], v[172:175], v[104:107]
	v_mfma_f32_16x16x32_bf16 v[100:103], v[224:227], v[180:183], v[100:103]
	v_mfma_f32_16x16x32_bf16 v[96:99], v[232:235], v[180:183], v[96:99]
	v_mfma_f32_16x16x32_bf16 v[80:83], v[224:227], v[208:211], v[80:83]
	v_mfma_f32_16x16x32_bf16 v[72:75], v[232:235], v[208:211], v[72:75]
	v_mfma_f32_16x16x32_bf16 v[68:71], v[224:227], v[216:219], v[68:71]
	v_mfma_f32_16x16x32_bf16 v[64:67], v[232:235], v[216:219], v[64:67]
	v_mfma_f32_16x16x32_bf16 v[112:115], v[228:231], v[176:179], v[112:115]
	v_mfma_f32_16x16x32_bf16 v[104:107], v[236:239], v[176:179], v[104:107]
	v_mfma_f32_16x16x32_bf16 v[100:103], v[228:231], v[204:207], v[100:103]
	v_mfma_f32_16x16x32_bf16 v[96:99], v[236:239], v[204:207], v[96:99]
	v_mfma_f32_16x16x32_bf16 v[80:83], v[228:231], v[212:215], v[80:83]
	v_mfma_f32_16x16x32_bf16 v[72:75], v[236:239], v[212:215], v[72:75]
	v_mfma_f32_16x16x32_bf16 v[68:71], v[228:231], v[220:223], v[68:71]
	v_mfma_f32_16x16x32_bf16 v[64:67], v[236:239], v[220:223], v[64:67]
	s_setprio 0
	s_mov_b32 m0, s70
	v_lshl_add_u64 v[154:155], s[16:17], 0, v[146:147]
	s_barrier
; #define PG8_STAGE(bufoff, gbase, voff) do { _Pragma("unroll") for (int _i = 0; _i < 2; ++_i) \
;         __builtin_amdgcn_global_load_lds((const unsigned*)((const char*)(gbase) + (voff)[_i]), (LAS unsigned*)(lds + (bufoff) + ldsw + _i * 8192), 16, 0, 0); } while (0)
; #define PG8_STAGE_A(bufoff, ptr, half, rev) do { if (REVA && (rev)) { const char* _p = (ptr) - ((half) ? hstepA : 0); PG8_STAGE(bufoff, _p, voffAr); } else { const char* _p = (ptr) + ((half) ? hstepA : 0); PG8_STAGE(bufoff, _p, voffA); } } while (0)
; #define PG8_LDA(dst, b, h) do { _Pragma("unroll") for (int m = 0; m < 4; ++m) _Pragma("unroll") for (int k = 0; k < 2; ++k) dst[m][k] = *(const LAS bf16x8*)(lds + PG8_SA(b, h) + aoff + m * 2048 + k * 1024); } while (0)
; #define PG8_WAIT_V(n) asm volatile("s_waitcnt vmcnt(" #n ")" ::: "memory")
;     ...
;             PG8_LDA(At, 1, 1); PG8_STAGE_A(PG8_SA(1, 0), a3, 0, r3);
;             PG8_BAR; PG8_WAIT_L(0); PG8_MMA(1, 0, At, B0); PG8_BAR; PG8_SCHED;
;             PG8_STAGE(PG8_SB(1, 1), b3 + hb2, voffB);
;             PG8_WAIT_V(6); PG8_BAR; PG8_MMA(1, 1, At, B1); PG8_BAR;
;         }
;     __device__ __forceinline__ void operator()(const f32x4 (&acc)[2][2][4][2], const Unit& u, int wr, int wc, int fr, int fq, int lane) const {
;         const bool lat = u.pm < 128;
;         const int s = lat ? (u.pm >> 4) : 8;
;         const float* gate = modi + s * 6144 + 4096 + u.pn * BM + wc * 32 + 4 * fq;
;         const size_t r0 = lat ? (size_t)u.pm * BM : (size_t)(u.pm - 128) * BM;
;         const float* base = (lat ? baseL : baseC) + u.pn * BM + wc * 32 + 4 * fq;
;         float* out = (lat ? outL : outC) + u.pn * BM + wc * 32 + 4 * fq;
;         f32x4 gv[2][2];
; #pragma unroll
;         for (int bj = 0; bj < 2; ++bj)
; #pragma unroll
;             for (int n = 0; n < 2; ++n) gv[bj][n] = *(const f32x4*)(gate + bj * HALF + n * 16);
; #pragma unroll
;         for (int ai = 0; ai < 2; ++ai)
; #pragma unroll
;           for (int mh = 0; mh < 2; ++mh) {
;             f32x4 bs[2][2][2];
; #pragma unroll
;             for (int m2 = 0; m2 < 2; ++m2) {
;                 const size_t ro = (r0 + ai * HALF + wr * 64 + (mh * 2 + m2) * 16 + fr) * (size_t)D;
; #pragma unroll
;                 for (int bj = 0; bj < 2; ++bj)
; #pragma unroll
;                     for (int n = 0; n < 2; ++n) bs[m2][bj][n] = *(const f32x4*)(base + ro + bj * HALF + n * 16);
	ds_read_b128 v[172:175], v158 offset:49152
	ds_read_b128 v[176:179], v158 offset:50176
	ds_read_b128 v[180:183], v158 offset:51200
	ds_read_b128 v[204:207], v158 offset:52224
	ds_read_b128 v[208:211], v158 offset:53248
	ds_read_b128 v[212:215], v158 offset:54272
	ds_read_b128 v[216:219], v158 offset:55296
	ds_read_b128 v[220:223], v158 offset:56320
	global_load_lds_dwordx4 v[154:155], off
	v_lshl_add_u64 v[154:155], s[16:17], 0, v[144:145]
	s_mov_b32 m0, s71
	s_nop 0
	global_load_lds_dwordx4 v[154:155], off
	s_waitcnt vmcnt(10)
	s_barrier
	s_waitcnt lgkmcnt(0)
	s_setprio 1
	s_waitcnt lgkmcnt(0)
	v_mfma_f32_16x16x32_bf16 v[60:63], v[132:135], v[172:175], v[60:63]
	v_mfma_f32_16x16x32_bf16 v[56:59], v[140:143], v[172:175], v[56:59]
	v_mfma_f32_16x16x32_bf16 v[52:55], v[132:135], v[180:183], v[52:55]
	v_mfma_f32_16x16x32_bf16 v[44:47], v[140:143], v[180:183], v[44:47]
	v_mfma_f32_16x16x32_bf16 v[28:31], v[132:135], v[208:211], v[28:31]
	v_mfma_f32_16x16x32_bf16 v[24:27], v[140:143], v[208:211], v[24:27]
	v_mfma_f32_16x16x32_bf16 v[20:23], v[132:135], v[216:219], v[20:23]
	v_mfma_f32_16x16x32_bf16 v[12:15], v[140:143], v[216:219], v[12:15]
	v_mfma_f32_16x16x32_bf16 v[60:63], v[136:139], v[176:179], v[60:63]
	v_mfma_f32_16x16x32_bf16 v[56:59], v[168:171], v[176:179], v[56:59]
	v_mfma_f32_16x16x32_bf16 v[52:55], v[136:139], v[204:207], v[52:55]
	v_mfma_f32_16x16x32_bf16 v[44:47], v[168:171], v[204:207], v[44:47]
	v_mfma_f32_16x16x32_bf16 v[28:31], v[136:139], v[212:215], v[28:31]
	v_mfma_f32_16x16x32_bf16 v[24:27], v[168:171], v[212:215], v[24:27]
	v_mfma_f32_16x16x32_bf16 v[20:23], v[136:139], v[220:223], v[20:23]
	v_mfma_f32_16x16x32_bf16 v[12:15], v[168:171], v[220:223], v[12:15]
	s_setprio 0
	s_barrier
	s_add_u32 s10, s14, 0x100080
	s_addc_u32 s11, s15, 0
	s_add_i32 s14, s20, s52
	v_lshl_add_u64 v[132:133], s[10:11], 0, v[146:147]
	s_mov_b32 m0, s14
	s_nop 0
	global_load_lds_dwordx4 v[132:133], off
	v_lshl_add_u64 v[132:133], s[10:11], 0, v[144:145]
	s_add_i32 m0, s14, 0x2000
	s_nop 0
	global_load_lds_dwordx4 v[132:133], off
	v_add_u32_e32 v154, 0x10000, v157
	ds_read_b128 v[132:135], v154
	ds_read_b128 v[136:139], v154 offset:1024
	ds_read_b128 v[140:143], v154 offset:2048
	ds_read_b128 v[168:171], v154 offset:3072
	s_waitcnt vmcnt(10)
	s_barrier
	s_setprio 1
	v_mfma_f32_16x16x32_bf16 v[48:51], v[224:227], v[172:175], v[48:51]
	v_mfma_f32_16x16x32_bf16 v[40:43], v[232:235], v[172:175], v[40:43]
	v_mfma_f32_16x16x32_bf16 v[36:39], v[224:227], v[180:183], v[36:39]
	v_mfma_f32_16x16x32_bf16 v[32:35], v[232:235], v[180:183], v[32:35]
	v_mfma_f32_16x16x32_bf16 v[16:19], v[224:227], v[208:211], v[16:19]
	v_mfma_f32_16x16x32_bf16 v[8:11], v[232:235], v[208:211], v[8:11]
	v_mfma_f32_16x16x32_bf16 v[4:7], v[224:227], v[216:219], v[4:7]
	v_mfma_f32_16x16x32_bf16 v[0:3], v[232:235], v[216:219], v[0:3]
	v_mfma_f32_16x16x32_bf16 v[48:51], v[228:231], v[176:179], v[48:51]
	v_mfma_f32_16x16x32_bf16 v[40:43], v[236:239], v[176:179], v[40:43]
	v_mfma_f32_16x16x32_bf16 v[36:39], v[228:231], v[204:207], v[36:39]
	v_mfma_f32_16x16x32_bf16 v[32:35], v[236:239], v[204:207], v[32:35]
	v_mfma_f32_16x16x32_bf16 v[16:19], v[228:231], v[212:215], v[16:19]
	v_mfma_f32_16x16x32_bf16 v[8:11], v[236:239], v[212:215], v[8:11]
	v_mfma_f32_16x16x32_bf16 v[4:7], v[228:231], v[220:223], v[4:7]
	v_mfma_f32_16x16x32_bf16 v[0:3], v[236:239], v[220:223], v[0:3]
	s_setprio 0
	s_add_i32 s92, s92, 2
	s_add_u32 s46, s46, 0x100
	s_addc_u32 s47, s47, 0
	s_cmp_gt_u32 s92, 61
	s_barrier
	s_cbranch_scc0 .LBB0_335
	s_waitcnt lgkmcnt(0)
	s_cmpk_lt_i32 s0, 0x80
	s_cselect_b32 s3, s61, s67
	s_cselect_b32 s16, s60, s66
	s_add_i32 s9, s0, 0xffffff80
	s_cmpk_lt_i32 s0, 0x80
	s_cselect_b32 s10, s0, s9
	s_lshr_b32 s9, s0, 4
	s_cmpk_lt_i32 s0, 0x80
	s_mulk_i32 s9, 0x1800
	s_cselect_b32 s14, s9, 0xc000
	s_ashr_i32 s15, s14, 31
	s_lshl_b64 s[14:15], s[14:15], 2
	s_add_u32 s0, s68, s14
	s_addc_u32 s11, s69, s15
	s_lshl_b32 s8, s8, 8
	s_ashr_i32 s9, s8, 31
	s_lshl_b64 s[8:9], s[8:9], 2
	s_add_u32 s0, s0, s8
	s_addc_u32 s11, s11, s9
	s_add_u32 s14, s0, s90
	s_addc_u32 s15, s11, 0
	s_ashr_i32 s11, s10, 31
	s_add_u32 s0, s16, s8
	s_addc_u32 s3, s3, s9
	s_add_u32 s8, s0, s90
	s_addc_u32 s9, s3, 0
	v_lshl_add_u64 v[128:129], s[14:15], 0, v[160:161]
	s_mov_b64 s[14:15], 0x704000
	s_mov_b32 s0, 0x704000
	v_lshl_add_u64 v[154:155], s[8:9], 0, v[160:161]
	s_lshl_b64 s[8:9], s[10:11], 21
	v_lshl_add_u64 v[130:131], v[128:129], 0, s[14:15]
	v_add_co_u32_e32 v128, vcc, s0, v128
	v_lshl_add_u64 v[154:155], v[154:155], 0, s[8:9]
	s_nop 0
	v_addc_co_u32_e32 v129, vcc, 0, v129, vcc
	v_lshl_add_u64 v[154:155], v[154:155], 0, v[148:149]
	s_mov_b32 s0, 0x20000
	v_add_co_u32_e32 v184, vcc, s0, v154
	global_load_dwordx4 v[136:139], v[130:131], off offset:64
	global_load_dwordx4 v[132:135], v[130:131], off offset:512
	global_load_dwordx4 v[140:143], v[128:129], off
	s_nop 0
	global_load_dwordx4 v[128:131], v[130:131], off offset:576
	v_addc_co_u32_e32 v185, vcc, 0, v155, vcc
	global_load_dwordx4 v[168:171], v[154:155], off
	global_load_dwordx4 v[172:175], v[154:155], off offset:64
	global_load_dwordx4 v[176:179], v[154:155], off offset:512
	global_load_dwordx4 v[180:183], v[154:155], off offset:576
	global_load_dwordx4 v[204:207], v[184:185], off
	global_load_dwordx4 v[208:211], v[184:185], off offset:64
	global_load_dwordx4 v[212:215], v[184:185], off offset:512
	global_load_dwordx4 v[216:219], v[184:185], off offset:576
	s_waitcnt vmcnt(0)
;     __device__ __forceinline__ void operator()(const f32x4 (&acc)[2][2][4][2], const Unit& u, int wr, int wc, int fr, int fq, int lane) const {
;     ...
;         for (int ai = 0; ai < 2; ++ai)
; #pragma unroll
;           for (int mh = 0; mh < 2; ++mh) {
;             f32x4 bs[2][2][2];
; #pragma unroll
;             for (int m2 = 0; m2 < 2; ++m2) {
;                 const size_t ro = (r0 + ai * HALF + wr * 64 + (mh * 2 + m2) * 16 + fr) * (size_t)D;
; #pragma unroll
;                 for (int bj = 0; bj < 2; ++bj)
; #pragma unroll
;                     for (int n = 0; n < 2; ++n) bs[m2][bj][n] = *(const f32x4*)(base + ro + bj * HALF + n * 16);
;             }
;             __builtin_amdgcn_sched_barrier(0);
; #pragma unroll
;             for (int m2 = 0; m2 < 2; ++m2) {
;                 const size_t ro = (r0 + ai * HALF + wr * 64 + (mh * 2 + m2) * 16 + fr) * (size_t)D;
; #pragma unroll
;                 for (int bj = 0; bj < 2; ++bj)
; #pragma unroll
;                     for (int n = 0; n < 2; ++n) *(f32x4*)(out + ro + bj * HALF + n * 16) = bs[m2][bj][n] + gv[bj][n] * acc[ai][bj][mh * 2 + m2][n];
;             }
;             __builtin_amdgcn_sched_barrier(0);
;           }
	v_pk_fma_f32 v[106:107], v[106:107], v[130:131], v[182:183]
	v_pk_fma_f32 v[104:105], v[104:105], v[128:129], v[180:181]
	global_store_dwordx4 v[154:155], v[104:107], off offset:576
	v_pk_fma_f32 v[126:127], v[126:127], v[142:143], v[170:171]
	v_pk_fma_f32 v[124:125], v[124:125], v[140:141], v[168:169]
	v_pk_fma_f32 v[106:107], v[118:119], v[142:143], v[206:207]
	v_pk_fma_f32 v[104:105], v[116:117], v[140:141], v[204:205]
	v_pk_fma_f32 v[122:123], v[122:123], v[138:139], v[174:175]
	v_pk_fma_f32 v[120:121], v[120:121], v[136:137], v[172:173]
	v_pk_fma_f32 v[114:115], v[114:115], v[134:135], v[178:179]
	v_pk_fma_f32 v[112:113], v[112:113], v[132:133], v[176:177]
	global_store_dwordx4 v[184:185], v[104:107], off
	v_pk_fma_f32 v[102:103], v[102:103], v[134:135], v[214:215]
	v_pk_fma_f32 v[100:101], v[100:101], v[132:133], v[212:213]
	v_pk_fma_f32 v[106:107], v[110:111], v[138:139], v[210:211]
	v_pk_fma_f32 v[104:105], v[108:109], v[136:137], v[208:209]
	v_pk_fma_f32 v[98:99], v[98:99], v[130:131], v[218:219]
	v_pk_fma_f32 v[96:97], v[96:97], v[128:129], v[216:217]
	global_store_dwordx4 v[154:155], v[124:127], off
	global_store_dwordx4 v[154:155], v[120:123], off offset:64
	global_store_dwordx4 v[154:155], v[112:115], off offset:512
	global_store_dwordx4 v[184:185], v[104:107], off offset:64
	global_store_dwordx4 v[184:185], v[100:103], off offset:512
	global_store_dwordx4 v[184:185], v[96:99], off offset:576
	s_mov_b32 s0, 0x40000
	v_add_co_u32_e32 v168, vcc, s0, v154
	s_mov_b32 s0, 0x60000
	s_nop 0
	v_addc_co_u32_e32 v169, vcc, 0, v155, vcc
	v_add_co_u32_e32 v170, vcc, s0, v154
	global_load_dwordx4 v[96:99], v[168:169], off
	global_load_dwordx4 v[100:103], v[168:169], off offset:64
	global_load_dwordx4 v[104:107], v[168:169], off offset:512
	global_load_dwordx4 v[108:111], v[168:169], off offset:576
	v_addc_co_u32_e32 v171, vcc, 0, v155, vcc
	global_load_dwordx4 v[112:115], v[170:171], off
	global_load_dwordx4 v[116:119], v[170:171], off offset:64
	global_load_dwordx4 v[120:123], v[170:171], off offset:512
	global_load_dwordx4 v[124:127], v[170:171], off offset:576
	s_waitcnt vmcnt(0)
	v_pk_fma_f32 v[74:75], v[74:75], v[130:131], v[110:111]
	v_pk_fma_f32 v[72:73], v[72:73], v[128:129], v[108:109]
	global_store_dwordx4 v[168:169], v[72:75], off offset:576
	v_pk_fma_f32 v[94:95], v[94:95], v[142:143], v[98:99]
	v_pk_fma_f32 v[92:93], v[92:93], v[140:141], v[96:97]
	v_pk_fma_f32 v[74:75], v[86:87], v[142:143], v[114:115]
	v_pk_fma_f32 v[72:73], v[84:85], v[140:141], v[112:113]
	v_pk_fma_f32 v[90:91], v[90:91], v[138:139], v[102:103]
	v_pk_fma_f32 v[88:89], v[88:89], v[136:137], v[100:101]
	v_pk_fma_f32 v[82:83], v[82:83], v[134:135], v[106:107]
	v_pk_fma_f32 v[80:81], v[80:81], v[132:133], v[104:105]
	global_store_dwordx4 v[170:171], v[72:75], off
	v_pk_fma_f32 v[70:71], v[70:71], v[134:135], v[122:123]
	v_pk_fma_f32 v[68:69], v[68:69], v[132:133], v[120:121]
	v_pk_fma_f32 v[74:75], v[78:79], v[138:139], v[118:119]
	v_pk_fma_f32 v[72:73], v[76:77], v[136:137], v[116:117]
	v_pk_fma_f32 v[66:67], v[66:67], v[130:131], v[126:127]
	v_pk_fma_f32 v[64:65], v[64:65], v[128:129], v[124:125]
	global_store_dwordx4 v[168:169], v[92:95], off
	global_store_dwordx4 v[168:169], v[88:91], off offset:64
	global_store_dwordx4 v[168:169], v[80:83], off offset:512
	global_store_dwordx4 v[170:171], v[72:75], off offset:64
	global_store_dwordx4 v[170:171], v[68:71], off offset:512
	global_store_dwordx4 v[170:171], v[64:67], off offset:576
	v_add_co_u32_e32 v96, vcc, s76, v154
	s_nop 1
	v_addc_co_u32_e32 v97, vcc, 0, v155, vcc
	v_add_co_u32_e32 v98, vcc, s77, v154
	global_load_dwordx4 v[64:67], v[96:97], off
	global_load_dwordx4 v[68:71], v[96:97], off offset:64
	global_load_dwordx4 v[72:75], v[96:97], off offset:512
	global_load_dwordx4 v[76:79], v[96:97], off offset:576
	v_addc_co_u32_e32 v99, vcc, 0, v155, vcc
	global_load_dwordx4 v[80:83], v[98:99], off
	global_load_dwordx4 v[84:87], v[98:99], off offset:64
	global_load_dwordx4 v[88:91], v[98:99], off offset:512
	global_load_dwordx4 v[92:95], v[98:99], off offset:576
	s_waitcnt vmcnt(0)
; #define PG8_WAIT_V(n) asm volatile("s_waitcnt vmcnt(" #n ")" ::: "memory")
; #define PG8_BAR __builtin_amdgcn_s_barrier()
;     ...
;         cur = nxt; cA = nA; cB = nB; cAr = nAr; cHb = nHb; ++ui;
;     }
;     PG8_WAIT_V(0);
;     if (wr == 0) PG8_BAR;
;     PG8_BAR;
;     __device__ __forceinline__ void operator()(const f32x4 (&acc)[2][2][4][2], const Unit& u, int wr, int wc, int fr, int fq, int lane) const {
;     ...
;         for (int ai = 0; ai < 2; ++ai)
; #pragma unroll
;           for (int mh = 0; mh < 2; ++mh) {
;             f32x4 bs[2][2][2];
; #pragma unroll
;             for (int m2 = 0; m2 < 2; ++m2) {
;                 const size_t ro = (r0 + ai * HALF + wr * 64 + (mh * 2 + m2) * 16 + fr) * (size_t)D;
; #pragma unroll
;                 for (int bj = 0; bj < 2; ++bj)
; #pragma unroll
;                     for (int n = 0; n < 2; ++n) bs[m2][bj][n] = *(const f32x4*)(base + ro + bj * HALF + n * 16);
;             }
;             __builtin_amdgcn_sched_barrier(0);
; #pragma unroll
;             for (int m2 = 0; m2 < 2; ++m2) {
;                 const size_t ro = (r0 + ai * HALF + wr * 64 + (mh * 2 + m2) * 16 + fr) * (size_t)D;
; #pragma unroll
;                 for (int bj = 0; bj < 2; ++bj)
; #pragma unroll
;                     for (int n = 0; n < 2; ++n) *(f32x4*)(out + ro + bj * HALF + n * 16) = bs[m2][bj][n] + gv[bj][n] * acc[ai][bj][mh * 2 + m2][n];
;             }
;             __builtin_amdgcn_sched_barrier(0);
;           }
	v_pk_fma_f32 v[42:43], v[42:43], v[130:131], v[78:79]
	v_pk_fma_f32 v[40:41], v[40:41], v[128:129], v[76:77]
	global_store_dwordx4 v[96:97], v[40:43], off offset:576
	v_pk_fma_f32 v[62:63], v[62:63], v[142:143], v[66:67]
	v_pk_fma_f32 v[60:61], v[60:61], v[140:141], v[64:65]
	v_pk_fma_f32 v[42:43], v[54:55], v[142:143], v[82:83]
	v_pk_fma_f32 v[40:41], v[52:53], v[140:141], v[80:81]
	v_pk_fma_f32 v[58:59], v[58:59], v[138:139], v[70:71]
	v_pk_fma_f32 v[56:57], v[56:57], v[136:137], v[68:69]
	v_pk_fma_f32 v[50:51], v[50:51], v[134:135], v[74:75]
	v_pk_fma_f32 v[48:49], v[48:49], v[132:133], v[72:73]
	global_store_dwordx4 v[98:99], v[40:43], off
	v_pk_fma_f32 v[38:39], v[38:39], v[134:135], v[90:91]
	v_pk_fma_f32 v[36:37], v[36:37], v[132:133], v[88:89]
	v_pk_fma_f32 v[42:43], v[46:47], v[138:139], v[86:87]
	v_pk_fma_f32 v[40:41], v[44:45], v[136:137], v[84:85]
	v_pk_fma_f32 v[34:35], v[34:35], v[130:131], v[94:95]
	v_pk_fma_f32 v[32:33], v[32:33], v[128:129], v[92:93]
	global_store_dwordx4 v[96:97], v[60:63], off
	global_store_dwordx4 v[96:97], v[56:59], off offset:64
	global_store_dwordx4 v[96:97], v[48:51], off offset:512
	global_store_dwordx4 v[98:99], v[40:43], off offset:64
	global_store_dwordx4 v[98:99], v[36:39], off offset:512
	global_store_dwordx4 v[98:99], v[32:35], off offset:576
	v_add_co_u32_e32 v64, vcc, s18, v154
	s_nop 1
	v_addc_co_u32_e32 v65, vcc, 0, v155, vcc
	v_add_co_u32_e32 v66, vcc, s54, v154
	global_load_dwordx4 v[32:35], v[64:65], off
	global_load_dwordx4 v[36:39], v[64:65], off offset:64
	global_load_dwordx4 v[40:43], v[64:65], off offset:512
	global_load_dwordx4 v[44:47], v[64:65], off offset:576
	v_addc_co_u32_e32 v67, vcc, 0, v155, vcc
	global_load_dwordx4 v[48:51], v[66:67], off
	global_load_dwordx4 v[52:55], v[66:67], off offset:64
	global_load_dwordx4 v[56:59], v[66:67], off offset:512
	global_load_dwordx4 v[60:63], v[66:67], off offset:576
	s_waitcnt vmcnt(0)
	v_pk_fma_f32 v[10:11], v[10:11], v[130:131], v[46:47]
	v_pk_fma_f32 v[8:9], v[8:9], v[128:129], v[44:45]
	global_store_dwordx4 v[64:65], v[8:11], off offset:576
	v_pk_fma_f32 v[30:31], v[30:31], v[142:143], v[34:35]
	v_pk_fma_f32 v[28:29], v[28:29], v[140:141], v[32:33]
	v_pk_fma_f32 v[10:11], v[22:23], v[142:143], v[50:51]
	v_pk_fma_f32 v[8:9], v[20:21], v[140:141], v[48:49]
	v_pk_fma_f32 v[26:27], v[26:27], v[138:139], v[38:39]
	v_pk_fma_f32 v[24:25], v[24:25], v[136:137], v[36:37]
	v_pk_fma_f32 v[18:19], v[18:19], v[134:135], v[42:43]
	v_pk_fma_f32 v[16:17], v[16:17], v[132:133], v[40:41]
	global_store_dwordx4 v[66:67], v[8:11], off
	v_pk_fma_f32 v[6:7], v[6:7], v[134:135], v[58:59]
	v_pk_fma_f32 v[4:5], v[4:5], v[132:133], v[56:57]
	v_pk_fma_f32 v[10:11], v[14:15], v[138:139], v[54:55]
	v_pk_fma_f32 v[8:9], v[12:13], v[136:137], v[52:53]
	v_pk_fma_f32 v[2:3], v[2:3], v[130:131], v[62:63]
	v_pk_fma_f32 v[0:1], v[0:1], v[128:129], v[60:61]
	global_store_dwordx4 v[64:65], v[28:31], off
	global_store_dwordx4 v[64:65], v[24:27], off offset:64
	global_store_dwordx4 v[64:65], v[16:19], off offset:512
	global_store_dwordx4 v[66:67], v[8:11], off offset:64
	global_store_dwordx4 v[66:67], v[4:7], off offset:512
	global_store_dwordx4 v[66:67], v[0:3], off offset:576
	s_and_b64 vcc, exec, s[42:43]
	s_mov_b32 s8, s2
	s_mov_b32 s0, s26
	s_mov_b64 s[20:21], s[38:39]
	s_mov_b64 s[44:45], s[36:37]
	s_cbranch_vccz .LBB0_332
	s_waitcnt vmcnt(0)
	s_cmpk_gt_u32 s5, 0xff
	s_cbranch_scc1 .LBB0_339
	s_barrier

; #define PG8_STAGE(bufoff, gbase, voff) do { _Pragma("unroll") for (int _i = 0; _i < 2; ++_i) \
;         __builtin_amdgcn_global_load_lds((const unsigned*)((const char*)(gbase) + (voff)[_i]), (LAS unsigned*)(lds + (bufoff) + ldsw + _i * 8192), 16, 0, 0); } while (0)
; #define PG8_STAGE_A(bufoff, ptr, half, rev) do { if (REVA && (rev)) { const char* _p = (ptr) - ((half) ? hstepA : 0); PG8_STAGE(bufoff, _p, voffAr); } else { const char* _p = (ptr) + ((half) ? hstepA : 0); PG8_STAGE(bufoff, _p, voffA); } } while (0)
; #define PG8_LDA(dst, b, h) do { _Pragma("unroll") for (int m = 0; m < 4; ++m) _Pragma("unroll") for (int k = 0; k < 2; ++k) dst[m][k] = *(const LAS bf16x8*)(lds + PG8_SA(b, h) + aoff + m * 2048 + k * 1024); } while (0)
; #define PG8_LDB(dst, b, h) do { _Pragma("unroll") for (int n = 0; n < 2; ++n) _Pragma("unroll") for (int k = 0; k < 2; ++k) dst[n][k] = *(const LAS bf16x8*)(lds + PG8_SB(b, h) + boff + n * 2048 + k * 1024); } while (0)
; #define PG8_MMA(ai, bj, At, Bt) do { __builtin_amdgcn_s_setprio(1); _Pragma("unroll") for (int m = 0; m < 4; ++m) _Pragma("unroll") for (int n = 0; n < 2; ++n) _Pragma("unroll") for (int k = 0; k < 2; ++k) \
;         acc[ai][bj][m][n] = __builtin_amdgcn_mfma_f32_16x16x32_bf16(Bt[n][k], At[m][k], acc[ai][bj][m][n], 0, 0, 0); __builtin_amdgcn_s_setprio(0); } while (0)
;     ...
;         for (int t = 0; t < nt; t += 2) {
;             const bool last = (t == nt - 2);
;             const char* a1 = PG8_APTR(cA, cAr, t + 1); const bool r1 = REVA && ((t + 1) & 4);
;             const char* a2 = last ? nA : PG8_APTR(cA, cAr, t + 2); const bool r2 = REVA && !last && ((t + 2) & 4);
;             const char* a3 = last ? nA + kstep : PG8_APTR(cA, cAr, t + 3); const bool r3 = REVA && !last && ((t + 3) & 4);
;             const char* b2 = last ? nB : cB + (size_t)(t + 2) * kstep; const char* b3 = b2 + kstep; const size_t hb2 = last ? nHb : cHb;
;             PG8_LDB(B0, 0, 0); PG8_SCHED; PG8_LDA(At, 0, 0); PG8_STAGE_A(PG8_SA(1, 1), a1, 1, r1);
;             PG8_WAIT_L(8); PG8_BAR; PG8_WAIT_L(0); PG8_MMA(0, 0, At, B0); PG8_BAR; PG8_SCHED;
;             PG8_LDB(B1, 0, 1); PG8_STAGE(PG8_SB(0, 0), b2, voffB);
;             PG8_BAR; PG8_WAIT_L(0); PG8_MMA(0, 1, At, B1); PG8_BAR;
;             PG8_LDA(At, 0, 1); PG8_STAGE_A(PG8_SA(0, 0), a2, 0, r2);
;             PG8_BAR; PG8_WAIT_L(0); PG8_MMA(1, 0, At, B0); PG8_BAR; PG8_SCHED;
.LBB0_522:
	s_add_u32 s10, s44, s0
	s_addc_u32 s11, s45, s1
	s_add_u32 s14, s10, 0x100
	s_addc_u32 s15, s11, 0
	s_add_u32 s10, s10, 0x180
	s_addc_u32 s11, s11, 0
	s_add_u32 s16, s8, s0
	s_addc_u32 s17, s9, s1
	s_add_i32 s27, 0, 0x10000
	s_cmpk_eq_i32 s0, 0xf00
	s_cselect_b32 s21, s47, s17
	s_cselect_b32 s20, s46, s16
	s_cselect_b32 s17, s39, s15
	s_cselect_b32 s16, s38, s14
	s_cselect_b32 s90, s37, s3
	s_cselect_b32 s91, s36, s2
	s_cselect_b32 s15, s7, s11
	s_cselect_b32 s14, s6, s10
	v_lshl_add_u64 v[184:185], v[144:145], 0, s[0:1]
	s_add_i32 m0, s66, 0xc000
	ds_read_b128 v[180:183], v155
	ds_read_b128 v[204:207], v155 offset:1024
	ds_read_b128 v[208:211], v155 offset:2048
	ds_read_b128 v[212:215], v155 offset:3072
	ds_read_b128 v[216:219], v155 offset:4096
	ds_read_b128 v[220:223], v155 offset:5120
	ds_read_b128 v[224:227], v155 offset:6144
	ds_read_b128 v[228:231], v155 offset:7168
	global_load_lds_dwordx4 v[184:185], off
	v_lshl_add_u64 v[184:185], v[146:147], 0, s[0:1]
	s_add_i32 m0, s66, 0xe000
	s_nop 0
	global_load_lds_dwordx4 v[184:185], off
	s_waitcnt lgkmcnt(8)
	s_waitcnt vmcnt(10)
	s_barrier
	s_waitcnt lgkmcnt(0)
	s_setprio 1
	s_waitcnt lgkmcnt(0)
	v_mfma_f32_16x16x32_bf16 v[124:127], v[156:159], v[180:183], v[124:127]
	v_mfma_f32_16x16x32_bf16 v[120:123], v[172:175], v[180:183], v[120:123]
	v_mfma_f32_16x16x32_bf16 v[108:111], v[156:159], v[208:211], v[108:111]
	v_mfma_f32_16x16x32_bf16 v[104:107], v[172:175], v[208:211], v[104:107]
	v_mfma_f32_16x16x32_bf16 v[92:95], v[156:159], v[216:219], v[92:95]
	v_mfma_f32_16x16x32_bf16 v[88:91], v[172:175], v[216:219], v[88:91]
	v_mfma_f32_16x16x32_bf16 v[76:79], v[156:159], v[224:227], v[76:79]
	v_mfma_f32_16x16x32_bf16 v[72:75], v[172:175], v[224:227], v[72:75]
	v_mfma_f32_16x16x32_bf16 v[124:127], v[168:171], v[204:207], v[124:127]
	v_mfma_f32_16x16x32_bf16 v[120:123], v[176:179], v[204:207], v[120:123]
	v_mfma_f32_16x16x32_bf16 v[108:111], v[168:171], v[212:215], v[108:111]
	v_mfma_f32_16x16x32_bf16 v[104:107], v[176:179], v[212:215], v[104:107]
	v_mfma_f32_16x16x32_bf16 v[92:95], v[168:171], v[220:223], v[92:95]
	v_mfma_f32_16x16x32_bf16 v[88:91], v[176:179], v[220:223], v[88:91]
	v_mfma_f32_16x16x32_bf16 v[76:79], v[168:171], v[228:231], v[76:79]
	v_mfma_f32_16x16x32_bf16 v[72:75], v[176:179], v[228:231], v[72:75]
	s_setprio 0
	s_barrier
	s_add_i32 s10, 0, 0x14000
	s_add_i32 s11, s27, s53
	v_add_u32_e32 v160, s10, v139
	v_lshl_add_u64 v[184:185], s[20:21], 0, v[130:131]
	s_mov_b32 m0, s11
	ds_read_b128 v[232:235], v160
	ds_read_b128 v[236:239], v160 offset:1024
	ds_read_b128 v[240:243], v160 offset:2048
	ds_read_b128 v[244:247], v160 offset:3072
	global_load_lds_dwordx4 v[184:185], off
	v_lshl_add_u64 v[248:249], s[20:21], 0, v[134:135]
	s_add_i32 m0, s11, 0x2000
	s_nop 0
	global_load_lds_dwordx4 v[248:249], off
	s_waitcnt vmcnt(10)
	s_barrier
	s_waitcnt lgkmcnt(0)
	s_setprio 1
	s_waitcnt lgkmcnt(0)
	v_mfma_f32_16x16x32_bf16 v[116:119], v[232:235], v[180:183], v[116:119]
	v_mfma_f32_16x16x32_bf16 v[112:115], v[240:243], v[180:183], v[112:115]
	v_mfma_f32_16x16x32_bf16 v[100:103], v[232:235], v[208:211], v[100:103]
	v_mfma_f32_16x16x32_bf16 v[96:99], v[240:243], v[208:211], v[96:99]
	v_mfma_f32_16x16x32_bf16 v[84:87], v[232:235], v[216:219], v[84:87]
	v_mfma_f32_16x16x32_bf16 v[80:83], v[240:243], v[216:219], v[80:83]
	v_mfma_f32_16x16x32_bf16 v[68:71], v[232:235], v[224:227], v[68:71]
	v_mfma_f32_16x16x32_bf16 v[64:67], v[240:243], v[224:227], v[64:67]
	v_mfma_f32_16x16x32_bf16 v[116:119], v[236:239], v[204:207], v[116:119]
	v_mfma_f32_16x16x32_bf16 v[112:115], v[244:247], v[204:207], v[112:115]
	v_mfma_f32_16x16x32_bf16 v[100:103], v[236:239], v[212:215], v[100:103]
	v_mfma_f32_16x16x32_bf16 v[96:99], v[244:247], v[212:215], v[96:99]
	v_mfma_f32_16x16x32_bf16 v[84:87], v[236:239], v[220:223], v[84:87]
	v_mfma_f32_16x16x32_bf16 v[80:83], v[244:247], v[220:223], v[80:83]
	v_mfma_f32_16x16x32_bf16 v[68:71], v[236:239], v[228:231], v[68:71]
	v_mfma_f32_16x16x32_bf16 v[64:67], v[244:247], v[228:231], v[64:67]
	s_setprio 0
	s_mov_b32 m0, s66
	v_lshl_add_u64 v[250:251], s[16:17], 0, v[128:129]
	s_barrier
	ds_read_b128 v[180:183], v155 offset:16384
	ds_read_b128 v[204:207], v155 offset:17408
	ds_read_b128 v[208:211], v155 offset:18432
	ds_read_b128 v[212:215], v155 offset:19456
	ds_read_b128 v[216:219], v155 offset:20480
	ds_read_b128 v[220:223], v155 offset:21504
	ds_read_b128 v[224:227], v155 offset:22528
	ds_read_b128 v[228:231], v155 offset:23552
	global_load_lds_dwordx4 v[250:251], off
	v_lshl_add_u64 v[250:251], s[16:17], 0, v[132:133]
	s_mov_b32 m0, s67
	s_nop 0
	global_load_lds_dwordx4 v[250:251], off
	s_waitcnt vmcnt(10)
	s_barrier
	s_waitcnt lgkmcnt(0)
	s_setprio 1
	s_waitcnt lgkmcnt(0)
	v_mfma_f32_16x16x32_bf16 v[60:63], v[156:159], v[180:183], v[60:63]
	v_mfma_f32_16x16x32_bf16 v[56:59], v[172:175], v[180:183], v[56:59]
	v_mfma_f32_16x16x32_bf16 v[44:47], v[156:159], v[208:211], v[44:47]
	v_mfma_f32_16x16x32_bf16 v[40:43], v[172:175], v[208:211], v[40:43]
	v_mfma_f32_16x16x32_bf16 v[28:31], v[156:159], v[216:219], v[28:31]
	v_mfma_f32_16x16x32_bf16 v[24:27], v[172:175], v[216:219], v[24:27]
	v_mfma_f32_16x16x32_bf16 v[12:15], v[156:159], v[224:227], v[12:15]
	v_mfma_f32_16x16x32_bf16 v[8:11], v[172:175], v[224:227], v[8:11]
	v_mfma_f32_16x16x32_bf16 v[60:63], v[168:171], v[204:207], v[60:63]
	v_mfma_f32_16x16x32_bf16 v[56:59], v[176:179], v[204:207], v[56:59]
	v_mfma_f32_16x16x32_bf16 v[44:47], v[168:171], v[212:215], v[44:47]
	v_mfma_f32_16x16x32_bf16 v[40:43], v[176:179], v[212:215], v[40:43]
	v_mfma_f32_16x16x32_bf16 v[28:31], v[168:171], v[220:223], v[28:31]
	v_mfma_f32_16x16x32_bf16 v[24:27], v[176:179], v[220:223], v[24:27]
	v_mfma_f32_16x16x32_bf16 v[12:15], v[168:171], v[228:231], v[12:15]
	v_mfma_f32_16x16x32_bf16 v[8:11], v[176:179], v[228:231], v[8:11]
	s_setprio 0
	s_barrier
; #define PG8_STAGE(bufoff, gbase, voff) do { _Pragma("unroll") for (int _i = 0; _i < 2; ++_i) \
;         __builtin_amdgcn_global_load_lds((const unsigned*)((const char*)(gbase) + (voff)[_i]), (LAS unsigned*)(lds + (bufoff) + ldsw + _i * 8192), 16, 0, 0); } while (0)
; #define PG8_STAGE_A(bufoff, ptr, half, rev) do { if (REVA && (rev)) { const char* _p = (ptr) - ((half) ? hstepA : 0); PG8_STAGE(bufoff, _p, voffAr); } else { const char* _p = (ptr) + ((half) ? hstepA : 0); PG8_STAGE(bufoff, _p, voffA); } } while (0)
; #define PG8_LDA(dst, b, h) do { _Pragma("unroll") for (int m = 0; m < 4; ++m) _Pragma("unroll") for (int k = 0; k < 2; ++k) dst[m][k] = *(const LAS bf16x8*)(lds + PG8_SA(b, h) + aoff + m * 2048 + k * 1024); } while (0)
; #define PG8_LDB(dst, b, h) do { _Pragma("unroll") for (int n = 0; n < 2; ++n) _Pragma("unroll") for (int k = 0; k < 2; ++k) dst[n][k] = *(const LAS bf16x8*)(lds + PG8_SB(b, h) + boff + n * 2048 + k * 1024); } while (0)
; #define PG8_MMA(ai, bj, At, Bt) do { __builtin_amdgcn_s_setprio(1); _Pragma("unroll") for (int m = 0; m < 4; ++m) _Pragma("unroll") for (int n = 0; n < 2; ++n) _Pragma("unroll") for (int k = 0; k < 2; ++k) \
;         acc[ai][bj][m][n] = __builtin_amdgcn_mfma_f32_16x16x32_bf16(Bt[n][k], At[m][k], acc[ai][bj][m][n], 0, 0, 0); __builtin_amdgcn_s_setprio(0); } while (0)
; #define PG8_WAIT_V(n) asm volatile("s_waitcnt vmcnt(" #n ")" ::: "memory")
; #define PG8_WAIT_L(n) asm volatile("s_waitcnt lgkmcnt(" #n ")" ::: "memory")
; #define PG8_BAR __builtin_amdgcn_s_barrier()
; #define PG8_SCHED __builtin_amdgcn_sched_barrier(0)
;     ...
;             PG8_STAGE(PG8_SB(0, 1), b2 + hb2, voffB);
;             PG8_WAIT_V(6); PG8_BAR; PG8_MMA(1, 1, At, B1); PG8_BAR;
;             PG8_LDB(B0, 1, 0); PG8_SCHED; PG8_LDA(At, 1, 0); PG8_STAGE_A(PG8_SA(0, 1), a2, 1, r2);
;             PG8_WAIT_L(8); PG8_BAR; PG8_WAIT_L(0); PG8_MMA(0, 0, At, B0); PG8_BAR; PG8_SCHED;
;             PG8_LDB(B1, 1, 1); PG8_STAGE(PG8_SB(1, 0), b3, voffB);
;             PG8_BAR; PG8_WAIT_L(0); PG8_MMA(0, 1, At, B1); PG8_BAR;
	s_add_u32 s20, s20, s91
	s_addc_u32 s21, s21, s90
	s_add_i32 s10, s10, s53
	v_lshl_add_u64 v[250:251], s[20:21], 0, v[130:131]
	s_mov_b32 m0, s10
	v_lshl_add_u64 v[190:191], s[20:21], 0, v[134:135]
	global_load_lds_dwordx4 v[250:251], off
	s_add_i32 m0, s10, 0x2000
	s_nop 0
	global_load_lds_dwordx4 v[190:191], off
	v_add_u32_e32 v160, 0x18000, v139
	ds_read_b128 v[156:159], v160
	ds_read_b128 v[168:171], v160 offset:1024
	ds_read_b128 v[172:175], v160 offset:2048
	ds_read_b128 v[176:179], v160 offset:3072
	s_waitcnt vmcnt(10)
	s_barrier
	s_setprio 1
	v_mfma_f32_16x16x32_bf16 v[52:55], v[232:235], v[180:183], v[52:55]
	v_mfma_f32_16x16x32_bf16 v[48:51], v[240:243], v[180:183], v[48:51]
	v_mfma_f32_16x16x32_bf16 v[36:39], v[232:235], v[208:211], v[36:39]
	v_mfma_f32_16x16x32_bf16 v[32:35], v[240:243], v[208:211], v[32:35]
	v_mfma_f32_16x16x32_bf16 v[20:23], v[232:235], v[216:219], v[20:23]
	v_mfma_f32_16x16x32_bf16 v[16:19], v[240:243], v[216:219], v[16:19]
	v_mfma_f32_16x16x32_bf16 v[4:7], v[232:235], v[224:227], v[4:7]
	v_mfma_f32_16x16x32_bf16 v[0:3], v[240:243], v[224:227], v[0:3]
	v_mfma_f32_16x16x32_bf16 v[52:55], v[236:239], v[204:207], v[52:55]
	v_mfma_f32_16x16x32_bf16 v[48:51], v[244:247], v[204:207], v[48:51]
	v_mfma_f32_16x16x32_bf16 v[36:39], v[236:239], v[212:215], v[36:39]
	v_mfma_f32_16x16x32_bf16 v[32:35], v[244:247], v[212:215], v[32:35]
	v_mfma_f32_16x16x32_bf16 v[20:23], v[236:239], v[220:223], v[20:23]
	v_mfma_f32_16x16x32_bf16 v[16:19], v[244:247], v[220:223], v[16:19]
	v_mfma_f32_16x16x32_bf16 v[4:7], v[236:239], v[228:231], v[4:7]
	v_mfma_f32_16x16x32_bf16 v[0:3], v[244:247], v[228:231], v[0:3]
	s_setprio 0
	s_add_i32 s10, 0, 0x18000
	s_barrier
	s_add_u32 s16, s16, 0x80000
	s_addc_u32 s17, s17, 0
	s_mov_b32 m0, s68
	v_lshl_add_u64 v[232:233], s[16:17], 0, v[128:129]
	ds_read_b128 v[180:183], v155 offset:32768
	ds_read_b128 v[204:207], v155 offset:33792
	ds_read_b128 v[208:211], v155 offset:34816
	ds_read_b128 v[212:215], v155 offset:35840
	ds_read_b128 v[216:219], v155 offset:36864
	ds_read_b128 v[220:223], v155 offset:37888
	ds_read_b128 v[224:227], v155 offset:38912
	ds_read_b128 v[228:231], v155 offset:39936
	global_load_lds_dwordx4 v[232:233], off
	v_lshl_add_u64 v[232:233], s[16:17], 0, v[132:133]
	s_mov_b32 m0, s69
	s_nop 0
	global_load_lds_dwordx4 v[232:233], off
	s_waitcnt lgkmcnt(8)
	s_waitcnt vmcnt(10)
	s_barrier
	s_waitcnt lgkmcnt(0)
	s_setprio 1
	s_waitcnt lgkmcnt(0)
	v_mfma_f32_16x16x32_bf16 v[124:127], v[156:159], v[180:183], v[124:127]
	v_mfma_f32_16x16x32_bf16 v[120:123], v[172:175], v[180:183], v[120:123]
	v_mfma_f32_16x16x32_bf16 v[108:111], v[156:159], v[208:211], v[108:111]
	v_mfma_f32_16x16x32_bf16 v[104:107], v[172:175], v[208:211], v[104:107]
	v_mfma_f32_16x16x32_bf16 v[92:95], v[156:159], v[216:219], v[92:95]
	v_mfma_f32_16x16x32_bf16 v[88:91], v[172:175], v[216:219], v[88:91]
	v_mfma_f32_16x16x32_bf16 v[76:79], v[156:159], v[224:227], v[76:79]
	v_mfma_f32_16x16x32_bf16 v[72:75], v[172:175], v[224:227], v[72:75]
	v_mfma_f32_16x16x32_bf16 v[124:127], v[168:171], v[204:207], v[124:127]
	v_mfma_f32_16x16x32_bf16 v[120:123], v[176:179], v[204:207], v[120:123]
	v_mfma_f32_16x16x32_bf16 v[108:111], v[168:171], v[212:215], v[108:111]
	v_mfma_f32_16x16x32_bf16 v[104:107], v[176:179], v[212:215], v[104:107]
	v_mfma_f32_16x16x32_bf16 v[92:95], v[168:171], v[220:223], v[92:95]
	v_mfma_f32_16x16x32_bf16 v[88:91], v[176:179], v[220:223], v[88:91]
	v_mfma_f32_16x16x32_bf16 v[76:79], v[168:171], v[228:231], v[76:79]
	v_mfma_f32_16x16x32_bf16 v[72:75], v[176:179], v[228:231], v[72:75]
	s_setprio 0
	s_barrier
	s_add_i32 s11, 0, 0x1c000
	s_add_i32 s10, s10, s53
	v_add_u32_e32 v160, s11, v139
	v_lshl_add_u64 v[184:185], v[184:185], 0, s[28:29]
	s_mov_b32 m0, s10
	ds_read_b128 v[232:235], v160
	ds_read_b128 v[236:239], v160 offset:1024
	ds_read_b128 v[240:243], v160 offset:2048
	ds_read_b128 v[244:247], v160 offset:3072
	global_load_lds_dwordx4 v[184:185], off
	v_lshl_add_u64 v[184:185], v[248:249], 0, s[28:29]
	s_add_i32 m0, s10, 0x2000
	s_nop 0
	global_load_lds_dwordx4 v[184:185], off
	s_waitcnt vmcnt(10)
	s_barrier
	s_waitcnt lgkmcnt(0)
	s_setprio 1
	s_waitcnt lgkmcnt(0)
	v_mfma_f32_16x16x32_bf16 v[116:119], v[232:235], v[180:183], v[116:119]
	v_mfma_f32_16x16x32_bf16 v[112:115], v[240:243], v[180:183], v[112:115]
	v_mfma_f32_16x16x32_bf16 v[100:103], v[232:235], v[208:211], v[100:103]
	v_mfma_f32_16x16x32_bf16 v[96:99], v[240:243], v[208:211], v[96:99]
	v_mfma_f32_16x16x32_bf16 v[84:87], v[232:235], v[216:219], v[84:87]
	v_mfma_f32_16x16x32_bf16 v[80:83], v[240:243], v[216:219], v[80:83]
	v_mfma_f32_16x16x32_bf16 v[68:71], v[232:235], v[224:227], v[68:71]
	v_mfma_f32_16x16x32_bf16 v[64:67], v[240:243], v[224:227], v[64:67]
	v_mfma_f32_16x16x32_bf16 v[116:119], v[236:239], v[204:207], v[116:119]
	v_mfma_f32_16x16x32_bf16 v[112:115], v[244:247], v[204:207], v[112:115]
	v_mfma_f32_16x16x32_bf16 v[100:103], v[236:239], v[212:215], v[100:103]
	v_mfma_f32_16x16x32_bf16 v[96:99], v[244:247], v[212:215], v[96:99]
	v_mfma_f32_16x16x32_bf16 v[84:87], v[236:239], v[220:223], v[84:87]
	v_mfma_f32_16x16x32_bf16 v[80:83], v[244:247], v[220:223], v[80:83]
	v_mfma_f32_16x16x32_bf16 v[68:71], v[236:239], v[228:231], v[68:71]
	v_mfma_f32_16x16x32_bf16 v[64:67], v[244:247], v[228:231], v[64:67]
	s_setprio 0
	s_mov_b32 m0, s70
	v_lshl_add_u64 v[184:185], s[14:15], 0, v[128:129]
	s_barrier
; __device__ __forceinline__ unsigned cvt_pk_bf16(float lo, float hi) { unsigned r; asm volatile("v_cvt_pk_bf16_f32 %0, %1, %2" : "=v"(r) : "v"(lo), "v"(hi)); return r; }
; #define PG8_STAGE(bufoff, gbase, voff) do { _Pragma("unroll") for (int _i = 0; _i < 2; ++_i) \
;         __builtin_amdgcn_global_load_lds((const unsigned*)((const char*)(gbase) + (voff)[_i]), (LAS unsigned*)(lds + (bufoff) + ldsw + _i * 8192), 16, 0, 0); } while (0)
; #define PG8_STAGE_A(bufoff, ptr, half, rev) do { if (REVA && (rev)) { const char* _p = (ptr) - ((half) ? hstepA : 0); PG8_STAGE(bufoff, _p, voffAr); } else { const char* _p = (ptr) + ((half) ? hstepA : 0); PG8_STAGE(bufoff, _p, voffA); } } while (0)
; #define PG8_LDA(dst, b, h) do { _Pragma("unroll") for (int m = 0; m < 4; ++m) _Pragma("unroll") for (int k = 0; k < 2; ++k) dst[m][k] = *(const LAS bf16x8*)(lds + PG8_SA(b, h) + aoff + m * 2048 + k * 1024); } while (0)
; #define PG8_MMA(ai, bj, At, Bt) do { __builtin_amdgcn_s_setprio(1); _Pragma("unroll") for (int m = 0; m < 4; ++m) _Pragma("unroll") for (int n = 0; n < 2; ++n) _Pragma("unroll") for (int k = 0; k < 2; ++k) \
;         acc[ai][bj][m][n] = __builtin_amdgcn_mfma_f32_16x16x32_bf16(Bt[n][k], At[m][k], acc[ai][bj][m][n], 0, 0, 0); __builtin_amdgcn_s_setprio(0); } while (0)
; #define PG8_WAIT_V(n) asm volatile("s_waitcnt vmcnt(" #n ")" ::: "memory")
; #define PG8_WAIT_L(n) asm volatile("s_waitcnt lgkmcnt(" #n ")" ::: "memory")
; #define PG8_BAR __builtin_amdgcn_s_barrier()
; #define PG8_SCHED __builtin_amdgcn_sched_barrier(0)
;     ...
;             PG8_LDA(At, 1, 1); PG8_STAGE_A(PG8_SA(1, 0), a3, 0, r3);
;             PG8_BAR; PG8_WAIT_L(0); PG8_MMA(1, 0, At, B0); PG8_BAR; PG8_SCHED;
;             PG8_STAGE(PG8_SB(1, 1), b3 + hb2, voffB);
;             PG8_WAIT_V(6); PG8_BAR; PG8_MMA(1, 1, At, B1); PG8_BAR;
;     __device__ __forceinline__ void generic(const f32x4 (&acc)[2][2][4][2], const Unit& u, int wr, int wc, int fr, int fq) const {
;     ...
;                         } else {
;                             u32x4 w; w.x = cvt_pk_bf16(v0[0], v0[1]); w.y = cvt_pk_bf16(v0[2], v0[3]); w.z = cvt_pk_bf16(v1[0], v1[1]); w.w = cvt_pk_bf16(v1[2], v1[3]);
;                             *(u32x4*)(O + (size_t)(u.pm * BM + rt) * T + u.pn * BM + ct) = w;
	ds_read_b128 v[180:183], v155 offset:49152
	ds_read_b128 v[204:207], v155 offset:50176
	ds_read_b128 v[208:211], v155 offset:51200
	ds_read_b128 v[212:215], v155 offset:52224
	ds_read_b128 v[216:219], v155 offset:53248
	ds_read_b128 v[220:223], v155 offset:54272
	ds_read_b128 v[224:227], v155 offset:55296
	ds_read_b128 v[228:231], v155 offset:56320
	global_load_lds_dwordx4 v[184:185], off
	v_lshl_add_u64 v[184:185], s[14:15], 0, v[132:133]
	s_mov_b32 m0, s71
	s_nop 0
	global_load_lds_dwordx4 v[184:185], off
	s_waitcnt vmcnt(10)
	s_barrier
	s_waitcnt lgkmcnt(0)
	s_setprio 1
	s_waitcnt lgkmcnt(0)
	v_mfma_f32_16x16x32_bf16 v[60:63], v[156:159], v[180:183], v[60:63]
	v_mfma_f32_16x16x32_bf16 v[56:59], v[172:175], v[180:183], v[56:59]
	v_mfma_f32_16x16x32_bf16 v[44:47], v[156:159], v[208:211], v[44:47]
	v_mfma_f32_16x16x32_bf16 v[40:43], v[172:175], v[208:211], v[40:43]
	v_mfma_f32_16x16x32_bf16 v[28:31], v[156:159], v[216:219], v[28:31]
	v_mfma_f32_16x16x32_bf16 v[24:27], v[172:175], v[216:219], v[24:27]
	v_mfma_f32_16x16x32_bf16 v[12:15], v[156:159], v[224:227], v[12:15]
	v_mfma_f32_16x16x32_bf16 v[8:11], v[172:175], v[224:227], v[8:11]
	v_mfma_f32_16x16x32_bf16 v[60:63], v[168:171], v[204:207], v[60:63]
	v_mfma_f32_16x16x32_bf16 v[56:59], v[176:179], v[204:207], v[56:59]
	v_mfma_f32_16x16x32_bf16 v[44:47], v[168:171], v[212:215], v[44:47]
	v_mfma_f32_16x16x32_bf16 v[40:43], v[176:179], v[212:215], v[40:43]
	v_mfma_f32_16x16x32_bf16 v[28:31], v[168:171], v[220:223], v[28:31]
	v_mfma_f32_16x16x32_bf16 v[24:27], v[176:179], v[220:223], v[24:27]
	v_mfma_f32_16x16x32_bf16 v[12:15], v[168:171], v[228:231], v[12:15]
	v_mfma_f32_16x16x32_bf16 v[8:11], v[176:179], v[228:231], v[8:11]
	s_setprio 0
	s_barrier
	s_add_i32 s10, s11, s53
	v_lshl_add_u64 v[156:157], v[250:251], 0, s[28:29]
	s_mov_b32 m0, s10
	s_nop 0
	global_load_lds_dwordx4 v[156:157], off
	v_lshl_add_u64 v[156:157], v[190:191], 0, s[28:29]
	s_add_i32 m0, s10, 0x2000
	s_nop 0
	global_load_lds_dwordx4 v[156:157], off
	v_add_u32_e32 v160, 0x10000, v139
	ds_read_b128 v[156:159], v160
	ds_read_b128 v[168:171], v160 offset:1024
	ds_read_b128 v[172:175], v160 offset:2048
	ds_read_b128 v[176:179], v160 offset:3072
	s_waitcnt vmcnt(10)
	s_barrier
	s_setprio 1
	v_mfma_f32_16x16x32_bf16 v[52:55], v[232:235], v[180:183], v[52:55]
	v_mfma_f32_16x16x32_bf16 v[48:51], v[240:243], v[180:183], v[48:51]
	v_mfma_f32_16x16x32_bf16 v[36:39], v[232:235], v[208:211], v[36:39]
	v_mfma_f32_16x16x32_bf16 v[32:35], v[240:243], v[208:211], v[32:35]
	v_mfma_f32_16x16x32_bf16 v[20:23], v[232:235], v[216:219], v[20:23]
	v_mfma_f32_16x16x32_bf16 v[16:19], v[240:243], v[216:219], v[16:19]
	v_mfma_f32_16x16x32_bf16 v[4:7], v[232:235], v[224:227], v[4:7]
	v_mfma_f32_16x16x32_bf16 v[0:3], v[240:243], v[224:227], v[0:3]
	v_mfma_f32_16x16x32_bf16 v[52:55], v[236:239], v[204:207], v[52:55]
	v_mfma_f32_16x16x32_bf16 v[48:51], v[244:247], v[204:207], v[48:51]
	v_mfma_f32_16x16x32_bf16 v[36:39], v[236:239], v[212:215], v[36:39]
	v_mfma_f32_16x16x32_bf16 v[32:35], v[244:247], v[212:215], v[32:35]
	v_mfma_f32_16x16x32_bf16 v[20:23], v[236:239], v[220:223], v[20:23]
	v_mfma_f32_16x16x32_bf16 v[16:19], v[244:247], v[220:223], v[16:19]
	v_mfma_f32_16x16x32_bf16 v[4:7], v[236:239], v[228:231], v[4:7]
	v_mfma_f32_16x16x32_bf16 v[0:3], v[244:247], v[228:231], v[0:3]
	s_setprio 0
	s_add_i32 s22, s22, 2
	s_add_u32 s0, s0, 0x100
	s_addc_u32 s1, s1, 0
	s_cmp_gt_u32 s22, 29
	s_barrier
	s_cbranch_scc0 .LBB0_522
	s_waitcnt lgkmcnt(0)
	s_cmp_gt_i32 s89, 7
	s_cselect_b64 s[0:1], -1, 0
	s_cmpk_gt_i32 s5, 0x7f
	s_cselect_b64 s[2:3], -1, 0
	s_or_b64 s[0:1], s[0:1], s[2:3]
	s_mov_b64 s[2:3], -1
	s_and_b64 vcc, exec, s[0:1]
	v_lshl_add_u32 v146, s89, 8, v137
	v_lshlrev_b32_e32 v144, 1, v138
	s_cbranch_vccz .LBB0_525
	v_mov_b64_e32 v[168:169], s[24:25]
	v_mad_i64_i32 v[168:169], s[2:3], v146, s80, v[168:169]
	s_lshl_b32 s2, s5, 8
	s_ashr_i32 s3, s2, 31
	v_lshl_add_u64 v[168:169], s[2:3], 1, v[168:169]
	v_mov_b32_e32 v145, v161
	v_lshl_add_u64 v[168:169], v[168:169], 0, v[144:145]
	v_cvt_pk_bf16_f32 v156, v124, v125
	v_cvt_pk_bf16_f32 v157, v126, v127
	v_cvt_pk_bf16_f32 v158, v120, v121
	v_cvt_pk_bf16_f32 v159, v122, v123
	global_store_dwordx4 v[168:169], v[156:159], off
	s_mov_b64 s[2:3], 0

; #define PG8_STAGE(bufoff, gbase, voff) do { _Pragma("unroll") for (int _i = 0; _i < 2; ++_i) \
;         __builtin_amdgcn_global_load_lds((const unsigned*)((const char*)(gbase) + (voff)[_i]), (LAS unsigned*)(lds + (bufoff) + ldsw + _i * 8192), 16, 0, 0); } while (0)
; #define PG8_STAGE_A(bufoff, ptr, half, rev) do { if (REVA && (rev)) { const char* _p = (ptr) - ((half) ? hstepA : 0); PG8_STAGE(bufoff, _p, voffAr); } else { const char* _p = (ptr) + ((half) ? hstepA : 0); PG8_STAGE(bufoff, _p, voffA); } } while (0)
; #define PG8_LDA(dst, b, h) do { _Pragma("unroll") for (int m = 0; m < 4; ++m) _Pragma("unroll") for (int k = 0; k < 2; ++k) dst[m][k] = *(const LAS bf16x8*)(lds + PG8_SA(b, h) + aoff + m * 2048 + k * 1024); } while (0)
; #define PG8_LDB(dst, b, h) do { _Pragma("unroll") for (int n = 0; n < 2; ++n) _Pragma("unroll") for (int k = 0; k < 2; ++k) dst[n][k] = *(const LAS bf16x8*)(lds + PG8_SB(b, h) + boff + n * 2048 + k * 1024); } while (0)
; #define PG8_MMA(ai, bj, At, Bt) do { __builtin_amdgcn_s_setprio(1); _Pragma("unroll") for (int m = 0; m < 4; ++m) _Pragma("unroll") for (int n = 0; n < 2; ++n) _Pragma("unroll") for (int k = 0; k < 2; ++k) \
;         acc[ai][bj][m][n] = __builtin_amdgcn_mfma_f32_16x16x32_bf16(Bt[n][k], At[m][k], acc[ai][bj][m][n], 0, 0, 0); __builtin_amdgcn_s_setprio(0); } while (0)
;     ...
;         for (int t = 0; t < nt; t += 2) {
;             const bool last = (t == nt - 2);
;             const char* a1 = PG8_APTR(cA, cAr, t + 1); const bool r1 = REVA && ((t + 1) & 4);
;             const char* a2 = last ? nA : PG8_APTR(cA, cAr, t + 2); const bool r2 = REVA && !last && ((t + 2) & 4);
;             const char* a3 = last ? nA + kstep : PG8_APTR(cA, cAr, t + 3); const bool r3 = REVA && !last && ((t + 3) & 4);
;             const char* b2 = last ? nB : cB + (size_t)(t + 2) * kstep; const char* b3 = b2 + kstep; const size_t hb2 = last ? nHb : cHb;
;             PG8_LDB(B0, 0, 0); PG8_SCHED; PG8_LDA(At, 0, 0); PG8_STAGE_A(PG8_SA(1, 1), a1, 1, r1);
;             PG8_WAIT_L(8); PG8_BAR; PG8_WAIT_L(0); PG8_MMA(0, 0, At, B0); PG8_BAR; PG8_SCHED;
;             PG8_LDB(B1, 0, 1); PG8_STAGE(PG8_SB(0, 0), b2, voffB);
;             PG8_BAR; PG8_WAIT_L(0); PG8_MMA(0, 1, At, B1); PG8_BAR;
;             PG8_LDA(At, 0, 1); PG8_STAGE_A(PG8_SA(0, 0), a2, 0, r2);
;             PG8_BAR; PG8_WAIT_L(0); PG8_MMA(1, 0, At, B0); PG8_BAR; PG8_SCHED;
.LBB0_567:
	s_add_u32 s10, s38, s0
	s_addc_u32 s11, s39, s1
	s_add_u32 s16, s10, 0x100
	s_addc_u32 s17, s11, 0
	s_add_u32 s10, s10, 0x180
	s_addc_u32 s11, s11, 0
	s_add_u32 s14, s52, s0
	s_addc_u32 s15, s53, s1
	s_add_i32 s67, 0, 0x10000
	s_cmpk_eq_i32 s0, 0xf00
	s_cselect_b32 s15, s45, s15
	s_cselect_b32 s14, s44, s14
	s_cselect_b32 s21, s37, s17
	s_cselect_b32 s20, s36, s16
	s_cselect_b32 s17, s27, s11
	s_cselect_b32 s16, s25, s10
	v_lshl_add_u64 v[158:159], v[140:141], 0, s[0:1]
	s_add_i32 m0, s22, 0xc000
	ds_read_b128 v[176:179], v149
	ds_read_b128 v[180:183], v149 offset:1024
	ds_read_b128 v[204:207], v149 offset:2048
	ds_read_b128 v[208:211], v149 offset:3072
	ds_read_b128 v[212:215], v149 offset:4096
	ds_read_b128 v[216:219], v149 offset:5120
	ds_read_b128 v[220:223], v149 offset:6144
	ds_read_b128 v[224:227], v149 offset:7168
	global_load_lds_dwordx4 v[158:159], off
	v_lshl_add_u64 v[158:159], v[142:143], 0, s[0:1]
	s_add_i32 m0, s22, 0xe000
	s_nop 0
	global_load_lds_dwordx4 v[158:159], off
	s_waitcnt lgkmcnt(8)
	s_waitcnt vmcnt(10)
	s_barrier
	s_waitcnt lgkmcnt(0)
	s_setprio 1
	s_waitcnt lgkmcnt(0)
	v_mfma_f32_16x16x32_bf16 v[124:127], v[150:153], v[176:179], v[124:127]
	v_mfma_f32_16x16x32_bf16 v[120:123], v[168:171], v[176:179], v[120:123]
	v_mfma_f32_16x16x32_bf16 v[116:119], v[150:153], v[204:207], v[116:119]
	v_mfma_f32_16x16x32_bf16 v[108:111], v[168:171], v[204:207], v[108:111]
	v_mfma_f32_16x16x32_bf16 v[100:103], v[150:153], v[212:215], v[100:103]
	v_mfma_f32_16x16x32_bf16 v[92:95], v[168:171], v[212:215], v[92:95]
	v_mfma_f32_16x16x32_bf16 v[84:87], v[150:153], v[220:223], v[84:87]
	v_mfma_f32_16x16x32_bf16 v[76:79], v[168:171], v[220:223], v[76:79]
	v_mfma_f32_16x16x32_bf16 v[124:127], v[154:157], v[180:183], v[124:127]
	v_mfma_f32_16x16x32_bf16 v[120:123], v[172:175], v[180:183], v[120:123]
	v_mfma_f32_16x16x32_bf16 v[116:119], v[154:157], v[208:211], v[116:119]
	v_mfma_f32_16x16x32_bf16 v[108:111], v[172:175], v[208:211], v[108:111]
	v_mfma_f32_16x16x32_bf16 v[100:103], v[154:157], v[216:219], v[100:103]
	v_mfma_f32_16x16x32_bf16 v[92:95], v[172:175], v[216:219], v[92:95]
	v_mfma_f32_16x16x32_bf16 v[84:87], v[154:157], v[224:227], v[84:87]
	v_mfma_f32_16x16x32_bf16 v[76:79], v[172:175], v[224:227], v[76:79]
	s_setprio 0
	s_barrier
	s_add_i32 s10, 0, 0x14000
	v_add_u32_e32 v158, s10, v145
	s_add_i32 s11, s67, s5
	ds_read_b128 v[228:231], v158
	ds_read_b128 v[232:235], v158 offset:1024
	ds_read_b128 v[236:239], v158 offset:2048
	ds_read_b128 v[240:243], v158 offset:3072
	v_lshl_add_u64 v[158:159], s[14:15], 0, v[132:133]
	s_mov_b32 m0, s11
	v_lshl_add_u64 v[184:185], s[14:15], 0, v[128:129]
	global_load_lds_dwordx4 v[158:159], off
	s_add_i32 m0, s11, 0x2000
	s_nop 0
	global_load_lds_dwordx4 v[184:185], off
	s_waitcnt vmcnt(10)
	s_barrier
	s_waitcnt lgkmcnt(0)
	s_setprio 1
	s_waitcnt lgkmcnt(0)
	v_mfma_f32_16x16x32_bf16 v[112:115], v[228:231], v[176:179], v[112:115]
	v_mfma_f32_16x16x32_bf16 v[104:107], v[236:239], v[176:179], v[104:107]
	v_mfma_f32_16x16x32_bf16 v[96:99], v[228:231], v[204:207], v[96:99]
	v_mfma_f32_16x16x32_bf16 v[88:91], v[236:239], v[204:207], v[88:91]
	v_mfma_f32_16x16x32_bf16 v[80:83], v[228:231], v[212:215], v[80:83]
	v_mfma_f32_16x16x32_bf16 v[72:75], v[236:239], v[212:215], v[72:75]
	v_mfma_f32_16x16x32_bf16 v[68:71], v[228:231], v[220:223], v[68:71]
	v_mfma_f32_16x16x32_bf16 v[64:67], v[236:239], v[220:223], v[64:67]
	v_mfma_f32_16x16x32_bf16 v[112:115], v[232:235], v[180:183], v[112:115]
	v_mfma_f32_16x16x32_bf16 v[104:107], v[240:243], v[180:183], v[104:107]
	v_mfma_f32_16x16x32_bf16 v[96:99], v[232:235], v[208:211], v[96:99]
	v_mfma_f32_16x16x32_bf16 v[88:91], v[240:243], v[208:211], v[88:91]
	v_mfma_f32_16x16x32_bf16 v[80:83], v[232:235], v[216:219], v[80:83]
	v_mfma_f32_16x16x32_bf16 v[72:75], v[240:243], v[216:219], v[72:75]
	v_mfma_f32_16x16x32_bf16 v[68:71], v[232:235], v[224:227], v[68:71]
	v_mfma_f32_16x16x32_bf16 v[64:67], v[240:243], v[224:227], v[64:67]
	s_setprio 0
	s_mov_b32 m0, s22
	v_lshl_add_u64 v[190:191], s[20:21], 0, v[134:135]
	s_barrier
	ds_read_b128 v[176:179], v149 offset:16384
	ds_read_b128 v[180:183], v149 offset:17408
	ds_read_b128 v[204:207], v149 offset:18432
	ds_read_b128 v[208:211], v149 offset:19456
	ds_read_b128 v[212:215], v149 offset:20480
	ds_read_b128 v[216:219], v149 offset:21504
	ds_read_b128 v[220:223], v149 offset:22528
	ds_read_b128 v[224:227], v149 offset:23552
	global_load_lds_dwordx4 v[190:191], off
	v_lshl_add_u64 v[190:191], s[20:21], 0, v[130:131]
	s_mov_b32 m0, s46
	s_nop 0
	global_load_lds_dwordx4 v[190:191], off
	s_waitcnt vmcnt(10)
	s_barrier
	s_waitcnt lgkmcnt(0)
	s_setprio 1
	s_waitcnt lgkmcnt(0)
	v_mfma_f32_16x16x32_bf16 v[60:63], v[150:153], v[176:179], v[60:63]
	v_mfma_f32_16x16x32_bf16 v[56:59], v[168:171], v[176:179], v[56:59]
	v_mfma_f32_16x16x32_bf16 v[52:55], v[150:153], v[204:207], v[52:55]
	v_mfma_f32_16x16x32_bf16 v[44:47], v[168:171], v[204:207], v[44:47]
	v_mfma_f32_16x16x32_bf16 v[36:39], v[150:153], v[212:215], v[36:39]
	v_mfma_f32_16x16x32_bf16 v[28:31], v[168:171], v[212:215], v[28:31]
	v_mfma_f32_16x16x32_bf16 v[20:23], v[150:153], v[220:223], v[20:23]
	v_mfma_f32_16x16x32_bf16 v[12:15], v[168:171], v[220:223], v[12:15]
	v_mfma_f32_16x16x32_bf16 v[60:63], v[154:157], v[180:183], v[60:63]
	v_mfma_f32_16x16x32_bf16 v[56:59], v[172:175], v[180:183], v[56:59]
	v_mfma_f32_16x16x32_bf16 v[52:55], v[154:157], v[208:211], v[52:55]
	v_mfma_f32_16x16x32_bf16 v[44:47], v[172:175], v[208:211], v[44:47]
	v_mfma_f32_16x16x32_bf16 v[36:39], v[154:157], v[216:219], v[36:39]
	v_mfma_f32_16x16x32_bf16 v[28:31], v[172:175], v[216:219], v[28:31]
	v_mfma_f32_16x16x32_bf16 v[20:23], v[154:157], v[224:227], v[20:23]
	v_mfma_f32_16x16x32_bf16 v[12:15], v[172:175], v[224:227], v[12:15]
	s_setprio 0
	s_barrier
; #define PG8_STAGE(bufoff, gbase, voff) do { _Pragma("unroll") for (int _i = 0; _i < 2; ++_i) \
;         __builtin_amdgcn_global_load_lds((const unsigned*)((const char*)(gbase) + (voff)[_i]), (LAS unsigned*)(lds + (bufoff) + ldsw + _i * 8192), 16, 0, 0); } while (0)
; #define PG8_STAGE_A(bufoff, ptr, half, rev) do { if (REVA && (rev)) { const char* _p = (ptr) - ((half) ? hstepA : 0); PG8_STAGE(bufoff, _p, voffAr); } else { const char* _p = (ptr) + ((half) ? hstepA : 0); PG8_STAGE(bufoff, _p, voffA); } } while (0)
; #define PG8_LDA(dst, b, h) do { _Pragma("unroll") for (int m = 0; m < 4; ++m) _Pragma("unroll") for (int k = 0; k < 2; ++k) dst[m][k] = *(const LAS bf16x8*)(lds + PG8_SA(b, h) + aoff + m * 2048 + k * 1024); } while (0)
; #define PG8_LDB(dst, b, h) do { _Pragma("unroll") for (int n = 0; n < 2; ++n) _Pragma("unroll") for (int k = 0; k < 2; ++k) dst[n][k] = *(const LAS bf16x8*)(lds + PG8_SB(b, h) + boff + n * 2048 + k * 1024); } while (0)
; #define PG8_MMA(ai, bj, At, Bt) do { __builtin_amdgcn_s_setprio(1); _Pragma("unroll") for (int m = 0; m < 4; ++m) _Pragma("unroll") for (int n = 0; n < 2; ++n) _Pragma("unroll") for (int k = 0; k < 2; ++k) \
;         acc[ai][bj][m][n] = __builtin_amdgcn_mfma_f32_16x16x32_bf16(Bt[n][k], At[m][k], acc[ai][bj][m][n], 0, 0, 0); __builtin_amdgcn_s_setprio(0); } while (0)
; #define PG8_WAIT_V(n) asm volatile("s_waitcnt vmcnt(" #n ")" ::: "memory")
; #define PG8_WAIT_L(n) asm volatile("s_waitcnt lgkmcnt(" #n ")" ::: "memory")
; #define PG8_BAR __builtin_amdgcn_s_barrier()
; #define PG8_SCHED __builtin_amdgcn_sched_barrier(0)
;     ...
;             PG8_STAGE(PG8_SB(0, 1), b2 + hb2, voffB);
;             PG8_WAIT_V(6); PG8_BAR; PG8_MMA(1, 1, At, B1); PG8_BAR;
;             PG8_LDB(B0, 1, 0); PG8_SCHED; PG8_LDA(At, 1, 0); PG8_STAGE_A(PG8_SA(0, 1), a2, 1, r2);
;             PG8_WAIT_L(8); PG8_BAR; PG8_WAIT_L(0); PG8_MMA(0, 0, At, B0); PG8_BAR; PG8_SCHED;
;             PG8_LDB(B1, 1, 1); PG8_STAGE(PG8_SB(1, 0), b3, voffB);
;             PG8_BAR; PG8_WAIT_L(0); PG8_MMA(0, 1, At, B1); PG8_BAR;
	s_add_u32 s68, s14, 0x80000
	s_addc_u32 s69, s15, 0
	s_add_i32 s10, s10, s5
	v_lshl_add_u64 v[150:151], s[68:69], 0, v[132:133]
	s_mov_b32 m0, s10
	s_nop 0
	global_load_lds_dwordx4 v[150:151], off
	v_lshl_add_u64 v[150:151], s[68:69], 0, v[128:129]
	s_add_i32 m0, s10, 0x2000
	s_nop 0
	global_load_lds_dwordx4 v[150:151], off
	v_add_u32_e32 v172, 0x18000, v145
	ds_read_b128 v[150:153], v172
	ds_read_b128 v[154:157], v172 offset:1024
	ds_read_b128 v[168:171], v172 offset:2048
	ds_read_b128 v[172:175], v172 offset:3072
	s_waitcnt vmcnt(10)
	s_barrier
	s_setprio 1
	v_mfma_f32_16x16x32_bf16 v[48:51], v[228:231], v[176:179], v[48:51]
	v_mfma_f32_16x16x32_bf16 v[40:43], v[236:239], v[176:179], v[40:43]
	v_mfma_f32_16x16x32_bf16 v[32:35], v[228:231], v[204:207], v[32:35]
	v_mfma_f32_16x16x32_bf16 v[24:27], v[236:239], v[204:207], v[24:27]
	v_mfma_f32_16x16x32_bf16 v[16:19], v[228:231], v[212:215], v[16:19]
	v_mfma_f32_16x16x32_bf16 v[8:11], v[236:239], v[212:215], v[8:11]
	v_mfma_f32_16x16x32_bf16 v[4:7], v[228:231], v[220:223], v[4:7]
	v_mfma_f32_16x16x32_bf16 v[0:3], v[236:239], v[220:223], v[0:3]
	v_mfma_f32_16x16x32_bf16 v[48:51], v[232:235], v[180:183], v[48:51]
	v_mfma_f32_16x16x32_bf16 v[40:43], v[240:243], v[180:183], v[40:43]
	v_mfma_f32_16x16x32_bf16 v[32:35], v[232:235], v[208:211], v[32:35]
	v_mfma_f32_16x16x32_bf16 v[24:27], v[240:243], v[208:211], v[24:27]
	v_mfma_f32_16x16x32_bf16 v[16:19], v[232:235], v[216:219], v[16:19]
	v_mfma_f32_16x16x32_bf16 v[8:11], v[240:243], v[216:219], v[8:11]
	v_mfma_f32_16x16x32_bf16 v[4:7], v[232:235], v[224:227], v[4:7]
	v_mfma_f32_16x16x32_bf16 v[0:3], v[240:243], v[224:227], v[0:3]
	s_setprio 0
	s_add_i32 s10, 0, 0x18000
	s_barrier
	s_add_u32 s20, s20, 0x80000
	s_addc_u32 s21, s21, 0
	s_mov_b32 m0, s47
	v_lshl_add_u64 v[190:191], s[20:21], 0, v[134:135]
	ds_read_b128 v[176:179], v149 offset:32768
	ds_read_b128 v[180:183], v149 offset:33792
	ds_read_b128 v[204:207], v149 offset:34816
	ds_read_b128 v[208:211], v149 offset:35840
	ds_read_b128 v[212:215], v149 offset:36864
	ds_read_b128 v[216:219], v149 offset:37888
	ds_read_b128 v[220:223], v149 offset:38912
	ds_read_b128 v[224:227], v149 offset:39936
	global_load_lds_dwordx4 v[190:191], off
	v_lshl_add_u64 v[190:191], s[20:21], 0, v[130:131]
	s_mov_b32 m0, s50
	s_nop 0
	global_load_lds_dwordx4 v[190:191], off
	s_waitcnt lgkmcnt(8)
	s_waitcnt vmcnt(10)
	s_barrier
	s_waitcnt lgkmcnt(0)
	s_setprio 1
	s_waitcnt lgkmcnt(0)
	v_mfma_f32_16x16x32_bf16 v[124:127], v[150:153], v[176:179], v[124:127]
	v_mfma_f32_16x16x32_bf16 v[120:123], v[168:171], v[176:179], v[120:123]
	v_mfma_f32_16x16x32_bf16 v[116:119], v[150:153], v[204:207], v[116:119]
	v_mfma_f32_16x16x32_bf16 v[108:111], v[168:171], v[204:207], v[108:111]
	v_mfma_f32_16x16x32_bf16 v[100:103], v[150:153], v[212:215], v[100:103]
	v_mfma_f32_16x16x32_bf16 v[92:95], v[168:171], v[212:215], v[92:95]
	v_mfma_f32_16x16x32_bf16 v[84:87], v[150:153], v[220:223], v[84:87]
	v_mfma_f32_16x16x32_bf16 v[76:79], v[168:171], v[220:223], v[76:79]
	v_mfma_f32_16x16x32_bf16 v[124:127], v[154:157], v[180:183], v[124:127]
	v_mfma_f32_16x16x32_bf16 v[120:123], v[172:175], v[180:183], v[120:123]
	v_mfma_f32_16x16x32_bf16 v[116:119], v[154:157], v[208:211], v[116:119]
	v_mfma_f32_16x16x32_bf16 v[108:111], v[172:175], v[208:211], v[108:111]
	v_mfma_f32_16x16x32_bf16 v[100:103], v[154:157], v[216:219], v[100:103]
	v_mfma_f32_16x16x32_bf16 v[92:95], v[172:175], v[216:219], v[92:95]
	v_mfma_f32_16x16x32_bf16 v[84:87], v[154:157], v[224:227], v[84:87]
	v_mfma_f32_16x16x32_bf16 v[76:79], v[172:175], v[224:227], v[76:79]
	s_setprio 0
	s_barrier
	s_add_i32 s11, 0, 0x1c000
	s_add_i32 s10, s10, s5
	v_add_u32_e32 v190, s11, v145
	v_lshl_add_u64 v[158:159], v[158:159], 0, s[28:29]
	s_mov_b32 m0, s10
	ds_read_b128 v[228:231], v190
	ds_read_b128 v[232:235], v190 offset:1024
	ds_read_b128 v[236:239], v190 offset:2048
	ds_read_b128 v[240:243], v190 offset:3072
	global_load_lds_dwordx4 v[158:159], off
	v_lshl_add_u64 v[158:159], v[184:185], 0, s[28:29]
	s_add_i32 m0, s10, 0x2000
	s_nop 0
	global_load_lds_dwordx4 v[158:159], off
	s_waitcnt vmcnt(10)
	s_barrier
	s_waitcnt lgkmcnt(0)
	s_setprio 1
	s_waitcnt lgkmcnt(0)
	v_mfma_f32_16x16x32_bf16 v[112:115], v[228:231], v[176:179], v[112:115]
	v_mfma_f32_16x16x32_bf16 v[104:107], v[236:239], v[176:179], v[104:107]
	v_mfma_f32_16x16x32_bf16 v[96:99], v[228:231], v[204:207], v[96:99]
	v_mfma_f32_16x16x32_bf16 v[88:91], v[236:239], v[204:207], v[88:91]
	v_mfma_f32_16x16x32_bf16 v[80:83], v[228:231], v[212:215], v[80:83]
	v_mfma_f32_16x16x32_bf16 v[72:75], v[236:239], v[212:215], v[72:75]
	v_mfma_f32_16x16x32_bf16 v[68:71], v[228:231], v[220:223], v[68:71]
	v_mfma_f32_16x16x32_bf16 v[64:67], v[236:239], v[220:223], v[64:67]
	v_mfma_f32_16x16x32_bf16 v[112:115], v[232:235], v[180:183], v[112:115]
	v_mfma_f32_16x16x32_bf16 v[104:107], v[240:243], v[180:183], v[104:107]
	v_mfma_f32_16x16x32_bf16 v[96:99], v[232:235], v[208:211], v[96:99]
	v_mfma_f32_16x16x32_bf16 v[88:91], v[240:243], v[208:211], v[88:91]
	v_mfma_f32_16x16x32_bf16 v[80:83], v[232:235], v[216:219], v[80:83]
	v_mfma_f32_16x16x32_bf16 v[72:75], v[240:243], v[216:219], v[72:75]
	v_mfma_f32_16x16x32_bf16 v[68:71], v[232:235], v[224:227], v[68:71]
	v_mfma_f32_16x16x32_bf16 v[64:67], v[240:243], v[224:227], v[64:67]
	s_setprio 0
	s_mov_b32 m0, s48
	v_lshl_add_u64 v[158:159], s[16:17], 0, v[134:135]
	s_barrier
; #define PG8_STAGE(bufoff, gbase, voff) do { _Pragma("unroll") for (int _i = 0; _i < 2; ++_i) \
;         __builtin_amdgcn_global_load_lds((const unsigned*)((const char*)(gbase) + (voff)[_i]), (LAS unsigned*)(lds + (bufoff) + ldsw + _i * 8192), 16, 0, 0); } while (0)
; #define PG8_STAGE_A(bufoff, ptr, half, rev) do { if (REVA && (rev)) { const char* _p = (ptr) - ((half) ? hstepA : 0); PG8_STAGE(bufoff, _p, voffAr); } else { const char* _p = (ptr) + ((half) ? hstepA : 0); PG8_STAGE(bufoff, _p, voffA); } } while (0)
; #define PG8_LDA(dst, b, h) do { _Pragma("unroll") for (int m = 0; m < 4; ++m) _Pragma("unroll") for (int k = 0; k < 2; ++k) dst[m][k] = *(const LAS bf16x8*)(lds + PG8_SA(b, h) + aoff + m * 2048 + k * 1024); } while (0)
; #define PG8_MMA(ai, bj, At, Bt) do { __builtin_amdgcn_s_setprio(1); _Pragma("unroll") for (int m = 0; m < 4; ++m) _Pragma("unroll") for (int n = 0; n < 2; ++n) _Pragma("unroll") for (int k = 0; k < 2; ++k) \
;         acc[ai][bj][m][n] = __builtin_amdgcn_mfma_f32_16x16x32_bf16(Bt[n][k], At[m][k], acc[ai][bj][m][n], 0, 0, 0); __builtin_amdgcn_s_setprio(0); } while (0)
; #define PG8_WAIT_V(n) asm volatile("s_waitcnt vmcnt(" #n ")" ::: "memory")
; #define PG8_WAIT_L(n) asm volatile("s_waitcnt lgkmcnt(" #n ")" ::: "memory")
; #define PG8_BAR __builtin_amdgcn_s_barrier()
; #define PG8_SCHED __builtin_amdgcn_sched_barrier(0)
;     ...
;             PG8_LDA(At, 1, 1); PG8_STAGE_A(PG8_SA(1, 0), a3, 0, r3);
;             PG8_BAR; PG8_WAIT_L(0); PG8_MMA(1, 0, At, B0); PG8_BAR; PG8_SCHED;
;             PG8_STAGE(PG8_SB(1, 1), b3 + hb2, voffB);
;             PG8_WAIT_V(6); PG8_BAR; PG8_MMA(1, 1, At, B1); PG8_BAR;
	ds_read_b128 v[176:179], v149 offset:49152
	ds_read_b128 v[180:183], v149 offset:50176
	ds_read_b128 v[204:207], v149 offset:51200
	ds_read_b128 v[208:211], v149 offset:52224
	ds_read_b128 v[212:215], v149 offset:53248
	ds_read_b128 v[216:219], v149 offset:54272
	ds_read_b128 v[220:223], v149 offset:55296
	ds_read_b128 v[224:227], v149 offset:56320
	global_load_lds_dwordx4 v[158:159], off
	v_lshl_add_u64 v[158:159], s[16:17], 0, v[130:131]
	s_mov_b32 m0, s49
	s_nop 0
	global_load_lds_dwordx4 v[158:159], off
	s_waitcnt vmcnt(10)
	s_barrier
	s_waitcnt lgkmcnt(0)
	s_setprio 1
	s_waitcnt lgkmcnt(0)
	v_mfma_f32_16x16x32_bf16 v[60:63], v[150:153], v[176:179], v[60:63]
	v_mfma_f32_16x16x32_bf16 v[56:59], v[168:171], v[176:179], v[56:59]
	v_mfma_f32_16x16x32_bf16 v[52:55], v[150:153], v[204:207], v[52:55]
	v_mfma_f32_16x16x32_bf16 v[44:47], v[168:171], v[204:207], v[44:47]
	v_mfma_f32_16x16x32_bf16 v[36:39], v[150:153], v[212:215], v[36:39]
	v_mfma_f32_16x16x32_bf16 v[28:31], v[168:171], v[212:215], v[28:31]
	v_mfma_f32_16x16x32_bf16 v[20:23], v[150:153], v[220:223], v[20:23]
	v_mfma_f32_16x16x32_bf16 v[12:15], v[168:171], v[220:223], v[12:15]
	v_mfma_f32_16x16x32_bf16 v[60:63], v[154:157], v[180:183], v[60:63]
	v_mfma_f32_16x16x32_bf16 v[56:59], v[172:175], v[180:183], v[56:59]
	v_mfma_f32_16x16x32_bf16 v[52:55], v[154:157], v[208:211], v[52:55]
	v_mfma_f32_16x16x32_bf16 v[44:47], v[172:175], v[208:211], v[44:47]
	v_mfma_f32_16x16x32_bf16 v[36:39], v[154:157], v[216:219], v[36:39]
	v_mfma_f32_16x16x32_bf16 v[28:31], v[172:175], v[216:219], v[28:31]
	v_mfma_f32_16x16x32_bf16 v[20:23], v[154:157], v[224:227], v[20:23]
	v_mfma_f32_16x16x32_bf16 v[12:15], v[172:175], v[224:227], v[12:15]
	s_setprio 0
	s_barrier
	s_add_u32 s14, s14, 0x80080
	s_addc_u32 s15, s15, 0
	s_add_i32 s10, s11, s5
	v_lshl_add_u64 v[150:151], s[14:15], 0, v[132:133]
	s_mov_b32 m0, s10
	s_nop 0
	global_load_lds_dwordx4 v[150:151], off
	v_lshl_add_u64 v[150:151], s[14:15], 0, v[128:129]
	s_add_i32 m0, s10, 0x2000
	s_nop 0
	global_load_lds_dwordx4 v[150:151], off
	v_add_u32_e32 v158, 0x10000, v145
	ds_read_b128 v[150:153], v158
	ds_read_b128 v[154:157], v158 offset:1024
	ds_read_b128 v[168:171], v158 offset:2048
	ds_read_b128 v[172:175], v158 offset:3072
	s_waitcnt vmcnt(10)
	s_barrier
	s_setprio 1
	v_mfma_f32_16x16x32_bf16 v[48:51], v[228:231], v[176:179], v[48:51]
	v_mfma_f32_16x16x32_bf16 v[40:43], v[236:239], v[176:179], v[40:43]
	v_mfma_f32_16x16x32_bf16 v[32:35], v[228:231], v[204:207], v[32:35]
	v_mfma_f32_16x16x32_bf16 v[24:27], v[236:239], v[204:207], v[24:27]
	v_mfma_f32_16x16x32_bf16 v[16:19], v[228:231], v[212:215], v[16:19]
	v_mfma_f32_16x16x32_bf16 v[8:11], v[236:239], v[212:215], v[8:11]
	v_mfma_f32_16x16x32_bf16 v[4:7], v[228:231], v[220:223], v[4:7]
	v_mfma_f32_16x16x32_bf16 v[0:3], v[236:239], v[220:223], v[0:3]
	v_mfma_f32_16x16x32_bf16 v[48:51], v[232:235], v[180:183], v[48:51]
	v_mfma_f32_16x16x32_bf16 v[40:43], v[240:243], v[180:183], v[40:43]
	v_mfma_f32_16x16x32_bf16 v[32:35], v[232:235], v[208:211], v[32:35]
	v_mfma_f32_16x16x32_bf16 v[24:27], v[240:243], v[208:211], v[24:27]
	v_mfma_f32_16x16x32_bf16 v[16:19], v[232:235], v[216:219], v[16:19]
	v_mfma_f32_16x16x32_bf16 v[8:11], v[240:243], v[216:219], v[8:11]
	v_mfma_f32_16x16x32_bf16 v[4:7], v[232:235], v[224:227], v[4:7]
	v_mfma_f32_16x16x32_bf16 v[0:3], v[240:243], v[224:227], v[0:3]
	s_setprio 0
	s_add_i32 s66, s66, 2
	s_add_u32 s0, s0, 0x100
	s_addc_u32 s1, s1, 0
	s_cmp_gt_u32 s66, 29
	s_barrier
	s_cbranch_scc0 .LBB0_567
; #define PG8_WAIT_V(n) asm volatile("s_waitcnt vmcnt(" #n ")" ::: "memory")
;     ...
;         cur = nxt; cA = nA; cB = nB; cAr = nAr; cHb = nHb; ++ui;
;     }
;     PG8_WAIT_V(0);
;     if (wr == 0) PG8_BAR;
;     PG8_BAR;
;     __device__ __forceinline__ void generic(const f32x4 (&acc)[2][2][4][2], const Unit& u, int wr, int wc, int fr, int fq) const {
;     ...
;         for (int ai = 0; ai < 2; ++ai)
; #pragma unroll
;             for (int m = 0; m < 4; ++m) {
;                 const int rt = ai * HALF + wr * 64 + m * 16 + fr;
; #pragma unroll
;                 for (int bj = 0; bj < 2; ++bj) {
;                     const int ct = bj * HALF + wc * 32 + 8 * fq;
;                     f32x4 v0 = acc[ai][bj][m][0], v1 = acc[ai][bj][m][1];
;                     if (MODE == 4) {
;                         if (u.pm < 8 && u.pn < 128) {
;                             if (bj == 0) {
;                                 const f32x4 a0 = acc[ai][0][m][0], a1 = acc[ai][0][m][1], b0 = acc[ai][1][m][0], b1 = acc[ai][1][m][1];
;                                 const f32x4 e0 = a0 + b0, e1 = a1 + b1, o0 = a0 - b0, o1 = a1 - b1;
;                                 bf16_t* p = O + (size_t)(u.pm * BM + rt) * T + (u.pn >> 4) * 4096 + (u.pn & 15) * 128 + wc * 32 + 8 * fq;
;                                 u32x4 w; w.x = cvt_pk_bf16(e0[0], e0[1]); w.y = cvt_pk_bf16(e0[2], e0[3]); w.z = cvt_pk_bf16(e1[0], e1[1]); w.w = cvt_pk_bf16(e1[2], e1[3]);
;                                 *(u32x4*)p = w;
;                                 w.x = cvt_pk_bf16(o0[0], o0[1]); w.y = cvt_pk_bf16(o0[2], o0[3]); w.z = cvt_pk_bf16(o1[0], o1[1]); w.w = cvt_pk_bf16(o1[2], o1[3]);
;                                 *(u32x4*)(p + 2048) = w;
;                             }
;                         } else {
;                             u32x4 w; w.x = cvt_pk_bf16(v0[0], v0[1]); w.y = cvt_pk_bf16(v0[2], v0[3]); w.z = cvt_pk_bf16(v1[0], v1[1]); w.w = cvt_pk_bf16(v1[2], v1[3]);
;                             *(u32x4*)(O + (size_t)(u.pm * BM + rt) * T + u.pn * BM + ct) = w;
;                         }
;                     } else if (MODE == 0) {
;                         u32x4 w; w.x = cvt_pk_bf16(v0[0], v0[1]); w.y = cvt_pk_bf16(v0[2], v0[3]); w.z = cvt_pk_bf16(v1[0], v1[1]); w.w = cvt_pk_bf16(v1[2], v1[3]);
;                         *(u32x4*)(O + (size_t)(u.pm * BM + rt) * ldc + u.pn * BM + ct) = w;
	s_waitcnt lgkmcnt(0)
	s_lshl_b32 s9, s9, 8
	v_cvt_pk_bf16_f32 v124, v124, v125
	v_cvt_pk_bf16_f32 v125, v126, v127
	v_cvt_pk_bf16_f32 v126, v120, v121
	v_add_u32_e32 v120, s9, v144
	v_ashrrev_i32_e32 v121, 31, v120
	s_lshl_b32 s0, s8, 8
	v_cvt_pk_bf16_f32 v127, v122, v123
	v_lshlrev_b64 v[122:123], 12, v[120:121]
	s_ashr_i32 s1, s0, 31
	v_lshl_add_u64 v[122:123], s[2:3], 0, v[122:123]
	s_lshl_b64 s[0:1], s[0:1], 1
	v_lshl_add_u64 v[122:123], v[122:123], 0, s[0:1]
	v_lshl_add_u64 v[122:123], v[122:123], 0, v[160:161]
	global_store_dwordx4 v[122:123], v[124:127], off
	v_cvt_pk_bf16_f32 v112, v112, v113
	v_cvt_pk_bf16_f32 v113, v114, v115
	v_cvt_pk_bf16_f32 v114, v104, v105
	v_cvt_pk_bf16_f32 v115, v106, v107
	global_store_dwordx4 v[122:123], v[112:115], off offset:256
	v_cvt_pk_bf16_f32 v104, v116, v117
	v_cvt_pk_bf16_f32 v105, v118, v119
	v_cvt_pk_bf16_f32 v106, v108, v109
	v_add_u32_e32 v108, s9, v146
	v_ashrrev_i32_e32 v109, 31, v108
	v_lshlrev_b64 v[108:109], 12, v[108:109]
	v_lshl_add_u64 v[108:109], s[2:3], 0, v[108:109]
	v_lshl_add_u64 v[108:109], v[108:109], 0, s[0:1]
	v_lshl_add_u64 v[108:109], v[108:109], 0, v[160:161]
	v_cvt_pk_bf16_f32 v107, v110, v111
	global_store_dwordx4 v[108:109], v[104:107], off
	v_cvt_pk_bf16_f32 v96, v96, v97
	v_cvt_pk_bf16_f32 v97, v98, v99
	v_cvt_pk_bf16_f32 v98, v88, v89
	v_cvt_pk_bf16_f32 v99, v90, v91
	global_store_dwordx4 v[108:109], v[96:99], off offset:256
	v_cvt_pk_bf16_f32 v88, v100, v101
	v_cvt_pk_bf16_f32 v89, v102, v103
	v_cvt_pk_bf16_f32 v90, v92, v93
	v_add_u32_e32 v92, s9, v147
	v_ashrrev_i32_e32 v93, 31, v92
	v_lshlrev_b64 v[92:93], 12, v[92:93]
	v_lshl_add_u64 v[92:93], s[2:3], 0, v[92:93]
	v_lshl_add_u64 v[92:93], v[92:93], 0, s[0:1]
	v_lshl_add_u64 v[92:93], v[92:93], 0, v[160:161]
	v_cvt_pk_bf16_f32 v91, v94, v95
	global_store_dwordx4 v[92:93], v[88:91], off
	v_cvt_pk_bf16_f32 v80, v80, v81
	v_cvt_pk_bf16_f32 v81, v82, v83
	v_cvt_pk_bf16_f32 v82, v72, v73
	v_cvt_pk_bf16_f32 v83, v74, v75
	global_store_dwordx4 v[92:93], v[80:83], off offset:256
	v_cvt_pk_bf16_f32 v72, v84, v85
	v_cvt_pk_bf16_f32 v73, v86, v87
	v_cvt_pk_bf16_f32 v74, v76, v77
	v_add_u32_e32 v76, s9, v148
	v_ashrrev_i32_e32 v77, 31, v76
	v_lshlrev_b64 v[76:77], 12, v[76:77]
	v_lshl_add_u64 v[76:77], s[2:3], 0, v[76:77]
	v_lshl_add_u64 v[76:77], v[76:77], 0, s[0:1]
	v_lshl_add_u64 v[76:77], v[76:77], 0, v[160:161]
	v_cvt_pk_bf16_f32 v75, v78, v79
	global_store_dwordx4 v[76:77], v[72:75], off
	v_cvt_pk_bf16_f32 v68, v68, v69
	v_cvt_pk_bf16_f32 v69, v70, v71
	v_cvt_pk_bf16_f32 v70, v64, v65
	v_cvt_pk_bf16_f32 v71, v66, v67
	global_store_dwordx4 v[76:77], v[68:71], off offset:256
	v_cvt_pk_bf16_f32 v60, v60, v61
	v_cvt_pk_bf16_f32 v61, v62, v63
	v_cvt_pk_bf16_f32 v62, v56, v57
	v_add_u32_e32 v56, 0x80, v120
	v_ashrrev_i32_e32 v57, 31, v56
	v_lshlrev_b64 v[56:57], 12, v[56:57]
	v_lshl_add_u64 v[56:57], s[2:3], 0, v[56:57]
	v_lshl_add_u64 v[56:57], v[56:57], 0, s[0:1]
	v_lshl_add_u64 v[56:57], v[56:57], 0, v[160:161]
	v_cvt_pk_bf16_f32 v63, v58, v59
	global_store_dwordx4 v[56:57], v[60:63], off
	v_cvt_pk_bf16_f32 v48, v48, v49
	v_cvt_pk_bf16_f32 v49, v50, v51
	v_cvt_pk_bf16_f32 v50, v40, v41
	v_cvt_pk_bf16_f32 v51, v42, v43
	global_store_dwordx4 v[56:57], v[48:51], off offset:256
	v_cvt_pk_bf16_f32 v40, v52, v53
	v_cvt_pk_bf16_f32 v41, v54, v55
	v_cvt_pk_bf16_f32 v42, v44, v45
	v_add_u32_e32 v44, 0x90, v120
	v_ashrrev_i32_e32 v45, 31, v44
	v_lshlrev_b64 v[44:45], 12, v[44:45]
	v_lshl_add_u64 v[44:45], s[2:3], 0, v[44:45]
	v_lshl_add_u64 v[44:45], v[44:45], 0, s[0:1]
	v_lshl_add_u64 v[44:45], v[44:45], 0, v[160:161]
	v_cvt_pk_bf16_f32 v43, v46, v47
	global_store_dwordx4 v[44:45], v[40:43], off
	v_cvt_pk_bf16_f32 v32, v32, v33
	v_cvt_pk_bf16_f32 v33, v34, v35
	v_cvt_pk_bf16_f32 v34, v24, v25
	v_cvt_pk_bf16_f32 v35, v26, v27
	global_store_dwordx4 v[44:45], v[32:35], off offset:256
	v_cvt_pk_bf16_f32 v24, v36, v37
	v_cvt_pk_bf16_f32 v25, v38, v39
	v_cvt_pk_bf16_f32 v26, v28, v29
	v_add_u32_e32 v28, 0xa0, v120
	v_ashrrev_i32_e32 v29, 31, v28
	v_lshlrev_b64 v[28:29], 12, v[28:29]
	v_lshl_add_u64 v[28:29], s[2:3], 0, v[28:29]
	v_lshl_add_u64 v[28:29], v[28:29], 0, s[0:1]
	v_lshl_add_u64 v[28:29], v[28:29], 0, v[160:161]
	v_cvt_pk_bf16_f32 v27, v30, v31
	global_store_dwordx4 v[28:29], v[24:27], off
	v_cvt_pk_bf16_f32 v16, v16, v17
	v_cvt_pk_bf16_f32 v17, v18, v19
	v_cvt_pk_bf16_f32 v18, v8, v9
	v_cvt_pk_bf16_f32 v19, v10, v11
	global_store_dwordx4 v[28:29], v[16:19], off offset:256
	v_cvt_pk_bf16_f32 v8, v20, v21
	v_cvt_pk_bf16_f32 v9, v22, v23
	v_cvt_pk_bf16_f32 v10, v12, v13
	v_add_u32_e32 v12, 0xb0, v120
	v_ashrrev_i32_e32 v13, 31, v12
	v_lshlrev_b64 v[12:13], 12, v[12:13]
	v_lshl_add_u64 v[12:13], s[2:3], 0, v[12:13]
	v_lshl_add_u64 v[12:13], v[12:13], 0, s[0:1]
	v_lshl_add_u64 v[12:13], v[12:13], 0, v[160:161]
	s_and_b64 vcc, exec, s[42:43]
	s_mov_b32 s8, s24
	s_mov_b32 s9, s26
	s_mov_b64 s[0:1], s[44:45]
	s_mov_b64 s[38:39], s[36:37]
	v_cvt_pk_bf16_f32 v11, v14, v15
	global_store_dwordx4 v[12:13], v[8:11], off
	v_cvt_pk_bf16_f32 v4, v4, v5
	v_cvt_pk_bf16_f32 v5, v6, v7
	v_cvt_pk_bf16_f32 v6, v0, v1
	v_cvt_pk_bf16_f32 v7, v2, v3
	global_store_dwordx4 v[12:13], v[4:7], off offset:256
	s_cbranch_vccz .LBB0_564
	s_waitcnt vmcnt(0)
	s_cmpk_gt_u32 s4, 0xff
	s_cbranch_scc1 .LBB0_571
	s_barrier

; #define PG8_STAGE(bufoff, gbase, voff) do { _Pragma("unroll") for (int _i = 0; _i < 2; ++_i) \
;         __builtin_amdgcn_global_load_lds((const unsigned*)((const char*)(gbase) + (voff)[_i]), (LAS unsigned*)(lds + (bufoff) + ldsw + _i * 8192), 16, 0, 0); } while (0)
; #define PG8_STAGE_A(bufoff, ptr, half, rev) do { if (REVA && (rev)) { const char* _p = (ptr) - ((half) ? hstepA : 0); PG8_STAGE(bufoff, _p, voffAr); } else { const char* _p = (ptr) + ((half) ? hstepA : 0); PG8_STAGE(bufoff, _p, voffA); } } while (0)
; #define PG8_LDA(dst, b, h) do { _Pragma("unroll") for (int m = 0; m < 4; ++m) _Pragma("unroll") for (int k = 0; k < 2; ++k) dst[m][k] = *(const LAS bf16x8*)(lds + PG8_SA(b, h) + aoff + m * 2048 + k * 1024); } while (0)
; #define PG8_LDB(dst, b, h) do { _Pragma("unroll") for (int n = 0; n < 2; ++n) _Pragma("unroll") for (int k = 0; k < 2; ++k) dst[n][k] = *(const LAS bf16x8*)(lds + PG8_SB(b, h) + boff + n * 2048 + k * 1024); } while (0)
; #define PG8_MMA(ai, bj, At, Bt) do { __builtin_amdgcn_s_setprio(1); _Pragma("unroll") for (int m = 0; m < 4; ++m) _Pragma("unroll") for (int n = 0; n < 2; ++n) _Pragma("unroll") for (int k = 0; k < 2; ++k) \
;         acc[ai][bj][m][n] = __builtin_amdgcn_mfma_f32_16x16x32_bf16(Bt[n][k], At[m][k], acc[ai][bj][m][n], 0, 0, 0); __builtin_amdgcn_s_setprio(0); } while (0)
;     ...
;         for (int t = 0; t < nt; t += 2) {
;             const bool last = (t == nt - 2);
;             const char* a1 = PG8_APTR(cA, cAr, t + 1); const bool r1 = REVA && ((t + 1) & 4);
;             const char* a2 = last ? nA : PG8_APTR(cA, cAr, t + 2); const bool r2 = REVA && !last && ((t + 2) & 4);
;             const char* a3 = last ? nA + kstep : PG8_APTR(cA, cAr, t + 3); const bool r3 = REVA && !last && ((t + 3) & 4);
;             const char* b2 = last ? nB : cB + (size_t)(t + 2) * kstep; const char* b3 = b2 + kstep; const size_t hb2 = last ? nHb : cHb;
;             PG8_LDB(B0, 0, 0); PG8_SCHED; PG8_LDA(At, 0, 0); PG8_STAGE_A(PG8_SA(1, 1), a1, 1, r1);
;             PG8_WAIT_L(8); PG8_BAR; PG8_WAIT_L(0); PG8_MMA(0, 0, At, B0); PG8_BAR; PG8_SCHED;
;             PG8_LDB(B1, 0, 1); PG8_STAGE(PG8_SB(0, 0), b2, voffB);
;             PG8_BAR; PG8_WAIT_L(0); PG8_MMA(0, 1, At, B1); PG8_BAR;
;             PG8_LDA(At, 0, 1); PG8_STAGE_A(PG8_SA(0, 0), a2, 0, r2);
;             PG8_BAR; PG8_WAIT_L(0); PG8_MMA(1, 0, At, B0); PG8_BAR; PG8_SCHED;
.LBB0_903:
	s_add_u32 s10, s38, s0
	s_addc_u32 s11, s39, s1
	s_add_u32 s20, s10, 0x100
	s_addc_u32 s21, s11, 0
	s_add_u32 s10, s10, 0x180
	s_addc_u32 s11, s11, 0
	s_add_u32 s14, s22, s0
	s_addc_u32 s15, s27, s1
	s_add_i32 s45, 0, 0x10000
	s_cmpk_eq_i32 s0, 0xf00
	s_cselect_b32 s15, s37, s15
	s_cselect_b32 s14, s36, s14
	s_cselect_b32 s17, s9, s11
	s_cselect_b32 s16, s8, s10
	s_cselect_b32 s21, s3, s21
	s_cselect_b32 s20, s2, s20
	v_lshl_add_u64 v[158:159], v[140:141], 0, s[0:1]
	s_add_i32 m0, s48, 0xc000
	ds_read_b128 v[180:183], v153
	ds_read_b128 v[204:207], v153 offset:1024
	ds_read_b128 v[208:211], v153 offset:2048
	ds_read_b128 v[212:215], v153 offset:3072
	ds_read_b128 v[216:219], v153 offset:4096
	ds_read_b128 v[220:223], v153 offset:5120
	ds_read_b128 v[224:227], v153 offset:6144
	ds_read_b128 v[228:231], v153 offset:7168
	global_load_lds_dwordx4 v[158:159], off
	v_lshl_add_u64 v[158:159], v[142:143], 0, s[0:1]
	s_add_i32 m0, s48, 0xe000
	s_nop 0
	global_load_lds_dwordx4 v[158:159], off
	s_waitcnt lgkmcnt(8)
	s_waitcnt vmcnt(10)
	s_barrier
	s_waitcnt lgkmcnt(0)
	s_setprio 1
	s_waitcnt lgkmcnt(0)
	v_mfma_f32_16x16x32_bf16 v[124:127], v[154:157], v[180:183], v[124:127]
	v_mfma_f32_16x16x32_bf16 v[120:123], v[172:175], v[180:183], v[120:123]
	v_mfma_f32_16x16x32_bf16 v[108:111], v[154:157], v[208:211], v[108:111]
	v_mfma_f32_16x16x32_bf16 v[104:107], v[172:175], v[208:211], v[104:107]
	v_mfma_f32_16x16x32_bf16 v[92:95], v[154:157], v[216:219], v[92:95]
	v_mfma_f32_16x16x32_bf16 v[88:91], v[172:175], v[216:219], v[88:91]
	v_mfma_f32_16x16x32_bf16 v[76:79], v[154:157], v[224:227], v[76:79]
	v_mfma_f32_16x16x32_bf16 v[72:75], v[172:175], v[224:227], v[72:75]
	v_mfma_f32_16x16x32_bf16 v[124:127], v[168:171], v[204:207], v[124:127]
	v_mfma_f32_16x16x32_bf16 v[120:123], v[176:179], v[204:207], v[120:123]
	v_mfma_f32_16x16x32_bf16 v[108:111], v[168:171], v[212:215], v[108:111]
	v_mfma_f32_16x16x32_bf16 v[104:107], v[176:179], v[212:215], v[104:107]
	v_mfma_f32_16x16x32_bf16 v[92:95], v[168:171], v[220:223], v[92:95]
	v_mfma_f32_16x16x32_bf16 v[88:91], v[176:179], v[220:223], v[88:91]
	v_mfma_f32_16x16x32_bf16 v[76:79], v[168:171], v[228:231], v[76:79]
	v_mfma_f32_16x16x32_bf16 v[72:75], v[176:179], v[228:231], v[72:75]
	s_setprio 0
	s_barrier
	s_add_i32 s10, 0, 0x14000
	v_add_u32_e32 v158, s10, v145
	s_add_i32 s11, s45, s47
	ds_read_b128 v[232:235], v158
	ds_read_b128 v[236:239], v158 offset:1024
	ds_read_b128 v[240:243], v158 offset:2048
	ds_read_b128 v[244:247], v158 offset:3072
	v_lshl_add_u64 v[158:159], s[14:15], 0, v[130:131]
	s_mov_b32 m0, s11
	v_lshl_add_u64 v[184:185], s[14:15], 0, v[134:135]
	global_load_lds_dwordx4 v[158:159], off
	s_add_i32 m0, s11, 0x2000
	s_nop 0
	global_load_lds_dwordx4 v[184:185], off
	s_waitcnt vmcnt(10)
	s_barrier
	s_waitcnt lgkmcnt(0)
	s_setprio 1
	s_waitcnt lgkmcnt(0)
	v_mfma_f32_16x16x32_bf16 v[116:119], v[232:235], v[180:183], v[116:119]
	v_mfma_f32_16x16x32_bf16 v[112:115], v[240:243], v[180:183], v[112:115]
	v_mfma_f32_16x16x32_bf16 v[100:103], v[232:235], v[208:211], v[100:103]
	v_mfma_f32_16x16x32_bf16 v[96:99], v[240:243], v[208:211], v[96:99]
	v_mfma_f32_16x16x32_bf16 v[84:87], v[232:235], v[216:219], v[84:87]
	v_mfma_f32_16x16x32_bf16 v[80:83], v[240:243], v[216:219], v[80:83]
	v_mfma_f32_16x16x32_bf16 v[68:71], v[232:235], v[224:227], v[68:71]
	v_mfma_f32_16x16x32_bf16 v[64:67], v[240:243], v[224:227], v[64:67]
	v_mfma_f32_16x16x32_bf16 v[116:119], v[236:239], v[204:207], v[116:119]
	v_mfma_f32_16x16x32_bf16 v[112:115], v[244:247], v[204:207], v[112:115]
	v_mfma_f32_16x16x32_bf16 v[100:103], v[236:239], v[212:215], v[100:103]
	v_mfma_f32_16x16x32_bf16 v[96:99], v[244:247], v[212:215], v[96:99]
	v_mfma_f32_16x16x32_bf16 v[84:87], v[236:239], v[220:223], v[84:87]
	v_mfma_f32_16x16x32_bf16 v[80:83], v[244:247], v[220:223], v[80:83]
	v_mfma_f32_16x16x32_bf16 v[68:71], v[236:239], v[228:231], v[68:71]
	v_mfma_f32_16x16x32_bf16 v[64:67], v[244:247], v[228:231], v[64:67]
	s_setprio 0
	s_mov_b32 m0, s48
	v_lshl_add_u64 v[190:191], s[20:21], 0, v[128:129]
	s_barrier
	ds_read_b128 v[180:183], v153 offset:16384
	ds_read_b128 v[204:207], v153 offset:17408
	ds_read_b128 v[208:211], v153 offset:18432
	ds_read_b128 v[212:215], v153 offset:19456
	ds_read_b128 v[216:219], v153 offset:20480
	ds_read_b128 v[220:223], v153 offset:21504
	ds_read_b128 v[224:227], v153 offset:22528
	ds_read_b128 v[228:231], v153 offset:23552
	global_load_lds_dwordx4 v[190:191], off
	v_lshl_add_u64 v[190:191], s[20:21], 0, v[132:133]
	s_mov_b32 m0, s49
	s_nop 0
	global_load_lds_dwordx4 v[190:191], off
	s_waitcnt vmcnt(10)
	s_barrier
	s_waitcnt lgkmcnt(0)
	s_setprio 1
	s_waitcnt lgkmcnt(0)
	v_mfma_f32_16x16x32_bf16 v[60:63], v[154:157], v[180:183], v[60:63]
	v_mfma_f32_16x16x32_bf16 v[56:59], v[172:175], v[180:183], v[56:59]
	v_mfma_f32_16x16x32_bf16 v[44:47], v[154:157], v[208:211], v[44:47]
	v_mfma_f32_16x16x32_bf16 v[40:43], v[172:175], v[208:211], v[40:43]
	v_mfma_f32_16x16x32_bf16 v[28:31], v[154:157], v[216:219], v[28:31]
	v_mfma_f32_16x16x32_bf16 v[24:27], v[172:175], v[216:219], v[24:27]
	v_mfma_f32_16x16x32_bf16 v[12:15], v[154:157], v[224:227], v[12:15]
	v_mfma_f32_16x16x32_bf16 v[8:11], v[172:175], v[224:227], v[8:11]
	v_mfma_f32_16x16x32_bf16 v[60:63], v[168:171], v[204:207], v[60:63]
	v_mfma_f32_16x16x32_bf16 v[56:59], v[176:179], v[204:207], v[56:59]
	v_mfma_f32_16x16x32_bf16 v[44:47], v[168:171], v[212:215], v[44:47]
	v_mfma_f32_16x16x32_bf16 v[40:43], v[176:179], v[212:215], v[40:43]
	v_mfma_f32_16x16x32_bf16 v[28:31], v[168:171], v[220:223], v[28:31]
	v_mfma_f32_16x16x32_bf16 v[24:27], v[176:179], v[220:223], v[24:27]
	v_mfma_f32_16x16x32_bf16 v[12:15], v[168:171], v[228:231], v[12:15]
	v_mfma_f32_16x16x32_bf16 v[8:11], v[176:179], v[228:231], v[8:11]
	s_setprio 0
	s_barrier
; #define PG8_STAGE(bufoff, gbase, voff) do { _Pragma("unroll") for (int _i = 0; _i < 2; ++_i) \
;         __builtin_amdgcn_global_load_lds((const unsigned*)((const char*)(gbase) + (voff)[_i]), (LAS unsigned*)(lds + (bufoff) + ldsw + _i * 8192), 16, 0, 0); } while (0)
; #define PG8_STAGE_A(bufoff, ptr, half, rev) do { if (REVA && (rev)) { const char* _p = (ptr) - ((half) ? hstepA : 0); PG8_STAGE(bufoff, _p, voffAr); } else { const char* _p = (ptr) + ((half) ? hstepA : 0); PG8_STAGE(bufoff, _p, voffA); } } while (0)
; #define PG8_LDA(dst, b, h) do { _Pragma("unroll") for (int m = 0; m < 4; ++m) _Pragma("unroll") for (int k = 0; k < 2; ++k) dst[m][k] = *(const LAS bf16x8*)(lds + PG8_SA(b, h) + aoff + m * 2048 + k * 1024); } while (0)
; #define PG8_LDB(dst, b, h) do { _Pragma("unroll") for (int n = 0; n < 2; ++n) _Pragma("unroll") for (int k = 0; k < 2; ++k) dst[n][k] = *(const LAS bf16x8*)(lds + PG8_SB(b, h) + boff + n * 2048 + k * 1024); } while (0)
; #define PG8_MMA(ai, bj, At, Bt) do { __builtin_amdgcn_s_setprio(1); _Pragma("unroll") for (int m = 0; m < 4; ++m) _Pragma("unroll") for (int n = 0; n < 2; ++n) _Pragma("unroll") for (int k = 0; k < 2; ++k) \
;         acc[ai][bj][m][n] = __builtin_amdgcn_mfma_f32_16x16x32_bf16(Bt[n][k], At[m][k], acc[ai][bj][m][n], 0, 0, 0); __builtin_amdgcn_s_setprio(0); } while (0)
; #define PG8_WAIT_V(n) asm volatile("s_waitcnt vmcnt(" #n ")" ::: "memory")
; #define PG8_WAIT_L(n) asm volatile("s_waitcnt lgkmcnt(" #n ")" ::: "memory")
; #define PG8_BAR __builtin_amdgcn_s_barrier()
; #define PG8_SCHED __builtin_amdgcn_sched_barrier(0)
;     ...
;             PG8_STAGE(PG8_SB(0, 1), b2 + hb2, voffB);
;             PG8_WAIT_V(6); PG8_BAR; PG8_MMA(1, 1, At, B1); PG8_BAR;
;             PG8_LDB(B0, 1, 0); PG8_SCHED; PG8_LDA(At, 1, 0); PG8_STAGE_A(PG8_SA(0, 1), a2, 1, r2);
;             PG8_WAIT_L(8); PG8_BAR; PG8_WAIT_L(0); PG8_MMA(0, 0, At, B0); PG8_BAR; PG8_SCHED;
;             PG8_LDB(B1, 1, 1); PG8_STAGE(PG8_SB(1, 0), b3, voffB);
;             PG8_BAR; PG8_WAIT_L(0); PG8_MMA(0, 1, At, B1); PG8_BAR;
	s_add_u32 s70, s14, 0x880000
	s_addc_u32 s71, s15, 0
	s_add_i32 s10, s10, s47
	v_lshl_add_u64 v[154:155], s[70:71], 0, v[130:131]
	s_mov_b32 m0, s10
	s_nop 0
	global_load_lds_dwordx4 v[154:155], off
	v_lshl_add_u64 v[154:155], s[70:71], 0, v[134:135]
	s_add_i32 m0, s10, 0x2000
	s_nop 0
	global_load_lds_dwordx4 v[154:155], off
	v_add_u32_e32 v176, 0x18000, v145
	ds_read_b128 v[154:157], v176
	ds_read_b128 v[168:171], v176 offset:1024
	ds_read_b128 v[172:175], v176 offset:2048
	ds_read_b128 v[176:179], v176 offset:3072
	s_waitcnt vmcnt(10)
	s_barrier
	s_setprio 1
	v_mfma_f32_16x16x32_bf16 v[52:55], v[232:235], v[180:183], v[52:55]
	v_mfma_f32_16x16x32_bf16 v[48:51], v[240:243], v[180:183], v[48:51]
	v_mfma_f32_16x16x32_bf16 v[36:39], v[232:235], v[208:211], v[36:39]
	v_mfma_f32_16x16x32_bf16 v[32:35], v[240:243], v[208:211], v[32:35]
	v_mfma_f32_16x16x32_bf16 v[20:23], v[232:235], v[216:219], v[20:23]
	v_mfma_f32_16x16x32_bf16 v[16:19], v[240:243], v[216:219], v[16:19]
	v_mfma_f32_16x16x32_bf16 v[4:7], v[232:235], v[224:227], v[4:7]
	v_mfma_f32_16x16x32_bf16 v[0:3], v[240:243], v[224:227], v[0:3]
	v_mfma_f32_16x16x32_bf16 v[52:55], v[236:239], v[204:207], v[52:55]
	v_mfma_f32_16x16x32_bf16 v[48:51], v[244:247], v[204:207], v[48:51]
	v_mfma_f32_16x16x32_bf16 v[36:39], v[236:239], v[212:215], v[36:39]
	v_mfma_f32_16x16x32_bf16 v[32:35], v[244:247], v[212:215], v[32:35]
	v_mfma_f32_16x16x32_bf16 v[20:23], v[236:239], v[220:223], v[20:23]
	v_mfma_f32_16x16x32_bf16 v[16:19], v[244:247], v[220:223], v[16:19]
	v_mfma_f32_16x16x32_bf16 v[4:7], v[236:239], v[228:231], v[4:7]
	v_mfma_f32_16x16x32_bf16 v[0:3], v[244:247], v[228:231], v[0:3]
	s_setprio 0
	s_add_i32 s10, 0, 0x18000
	s_barrier
	s_add_u32 s20, s20, 0x80000
	s_addc_u32 s21, s21, 0
	s_mov_b32 m0, s50
	v_lshl_add_u64 v[190:191], s[20:21], 0, v[128:129]
	ds_read_b128 v[180:183], v153 offset:32768
	ds_read_b128 v[204:207], v153 offset:33792
	ds_read_b128 v[208:211], v153 offset:34816
	ds_read_b128 v[212:215], v153 offset:35840
	ds_read_b128 v[216:219], v153 offset:36864
	ds_read_b128 v[220:223], v153 offset:37888
	ds_read_b128 v[224:227], v153 offset:38912
	ds_read_b128 v[228:231], v153 offset:39936
	global_load_lds_dwordx4 v[190:191], off
	v_lshl_add_u64 v[190:191], s[20:21], 0, v[132:133]
	s_mov_b32 m0, s51
	s_nop 0
	global_load_lds_dwordx4 v[190:191], off
	s_waitcnt lgkmcnt(8)
	s_waitcnt vmcnt(10)
	s_barrier
	s_waitcnt lgkmcnt(0)
	s_setprio 1
	s_waitcnt lgkmcnt(0)
	v_mfma_f32_16x16x32_bf16 v[124:127], v[154:157], v[180:183], v[124:127]
	v_mfma_f32_16x16x32_bf16 v[120:123], v[172:175], v[180:183], v[120:123]
	v_mfma_f32_16x16x32_bf16 v[108:111], v[154:157], v[208:211], v[108:111]
	v_mfma_f32_16x16x32_bf16 v[104:107], v[172:175], v[208:211], v[104:107]
	v_mfma_f32_16x16x32_bf16 v[92:95], v[154:157], v[216:219], v[92:95]
	v_mfma_f32_16x16x32_bf16 v[88:91], v[172:175], v[216:219], v[88:91]
	v_mfma_f32_16x16x32_bf16 v[76:79], v[154:157], v[224:227], v[76:79]
	v_mfma_f32_16x16x32_bf16 v[72:75], v[172:175], v[224:227], v[72:75]
	v_mfma_f32_16x16x32_bf16 v[124:127], v[168:171], v[204:207], v[124:127]
	v_mfma_f32_16x16x32_bf16 v[120:123], v[176:179], v[204:207], v[120:123]
	v_mfma_f32_16x16x32_bf16 v[108:111], v[168:171], v[212:215], v[108:111]
	v_mfma_f32_16x16x32_bf16 v[104:107], v[176:179], v[212:215], v[104:107]
	v_mfma_f32_16x16x32_bf16 v[92:95], v[168:171], v[220:223], v[92:95]
	v_mfma_f32_16x16x32_bf16 v[88:91], v[176:179], v[220:223], v[88:91]
	v_mfma_f32_16x16x32_bf16 v[76:79], v[168:171], v[228:231], v[76:79]
	v_mfma_f32_16x16x32_bf16 v[72:75], v[176:179], v[228:231], v[72:75]
	s_setprio 0
	s_barrier
	s_add_i32 s11, 0, 0x1c000
	s_add_i32 s10, s10, s47
	v_add_u32_e32 v190, s11, v145
	v_lshl_add_u64 v[158:159], v[158:159], 0, s[28:29]
	s_mov_b32 m0, s10
	ds_read_b128 v[232:235], v190
	ds_read_b128 v[236:239], v190 offset:1024
	ds_read_b128 v[240:243], v190 offset:2048
	ds_read_b128 v[244:247], v190 offset:3072
	global_load_lds_dwordx4 v[158:159], off
	v_lshl_add_u64 v[158:159], v[184:185], 0, s[28:29]
	s_add_i32 m0, s10, 0x2000
	s_nop 0
	global_load_lds_dwordx4 v[158:159], off
	s_waitcnt vmcnt(10)
	s_barrier
	s_waitcnt lgkmcnt(0)
	s_setprio 1
	s_waitcnt lgkmcnt(0)
	v_mfma_f32_16x16x32_bf16 v[116:119], v[232:235], v[180:183], v[116:119]
	v_mfma_f32_16x16x32_bf16 v[112:115], v[240:243], v[180:183], v[112:115]
	v_mfma_f32_16x16x32_bf16 v[100:103], v[232:235], v[208:211], v[100:103]
	v_mfma_f32_16x16x32_bf16 v[96:99], v[240:243], v[208:211], v[96:99]
	v_mfma_f32_16x16x32_bf16 v[84:87], v[232:235], v[216:219], v[84:87]
	v_mfma_f32_16x16x32_bf16 v[80:83], v[240:243], v[216:219], v[80:83]
	v_mfma_f32_16x16x32_bf16 v[68:71], v[232:235], v[224:227], v[68:71]
	v_mfma_f32_16x16x32_bf16 v[64:67], v[240:243], v[224:227], v[64:67]
	v_mfma_f32_16x16x32_bf16 v[116:119], v[236:239], v[204:207], v[116:119]
	v_mfma_f32_16x16x32_bf16 v[112:115], v[244:247], v[204:207], v[112:115]
	v_mfma_f32_16x16x32_bf16 v[100:103], v[236:239], v[212:215], v[100:103]
	v_mfma_f32_16x16x32_bf16 v[96:99], v[244:247], v[212:215], v[96:99]
	v_mfma_f32_16x16x32_bf16 v[84:87], v[236:239], v[220:223], v[84:87]
	v_mfma_f32_16x16x32_bf16 v[80:83], v[244:247], v[220:223], v[80:83]
	v_mfma_f32_16x16x32_bf16 v[68:71], v[236:239], v[228:231], v[68:71]
	v_mfma_f32_16x16x32_bf16 v[64:67], v[244:247], v[228:231], v[64:67]
	s_setprio 0
	s_mov_b32 m0, s66
	v_lshl_add_u64 v[158:159], s[16:17], 0, v[128:129]
	s_barrier
; __device__ __forceinline__ unsigned cvt_pk_bf16(float lo, float hi) { unsigned r; asm volatile("v_cvt_pk_bf16_f32 %0, %1, %2" : "=v"(r) : "v"(lo), "v"(hi)); return r; }
; #define PG8_STAGE(bufoff, gbase, voff) do { _Pragma("unroll") for (int _i = 0; _i < 2; ++_i) \
;         __builtin_amdgcn_global_load_lds((const unsigned*)((const char*)(gbase) + (voff)[_i]), (LAS unsigned*)(lds + (bufoff) + ldsw + _i * 8192), 16, 0, 0); } while (0)
; #define PG8_STAGE_A(bufoff, ptr, half, rev) do { if (REVA && (rev)) { const char* _p = (ptr) - ((half) ? hstepA : 0); PG8_STAGE(bufoff, _p, voffAr); } else { const char* _p = (ptr) + ((half) ? hstepA : 0); PG8_STAGE(bufoff, _p, voffA); } } while (0)
; #define PG8_LDA(dst, b, h) do { _Pragma("unroll") for (int m = 0; m < 4; ++m) _Pragma("unroll") for (int k = 0; k < 2; ++k) dst[m][k] = *(const LAS bf16x8*)(lds + PG8_SA(b, h) + aoff + m * 2048 + k * 1024); } while (0)
; #define PG8_MMA(ai, bj, At, Bt) do { __builtin_amdgcn_s_setprio(1); _Pragma("unroll") for (int m = 0; m < 4; ++m) _Pragma("unroll") for (int n = 0; n < 2; ++n) _Pragma("unroll") for (int k = 0; k < 2; ++k) \
;         acc[ai][bj][m][n] = __builtin_amdgcn_mfma_f32_16x16x32_bf16(Bt[n][k], At[m][k], acc[ai][bj][m][n], 0, 0, 0); __builtin_amdgcn_s_setprio(0); } while (0)
; #define PG8_WAIT_V(n) asm volatile("s_waitcnt vmcnt(" #n ")" ::: "memory")
; #define PG8_WAIT_L(n) asm volatile("s_waitcnt lgkmcnt(" #n ")" ::: "memory")
;     ...
;             PG8_LDA(At, 1, 1); PG8_STAGE_A(PG8_SA(1, 0), a3, 0, r3);
;             PG8_BAR; PG8_WAIT_L(0); PG8_MMA(1, 0, At, B0); PG8_BAR; PG8_SCHED;
;             PG8_STAGE(PG8_SB(1, 1), b3 + hb2, voffB);
;             PG8_WAIT_V(6); PG8_BAR; PG8_MMA(1, 1, At, B1); PG8_BAR;
;     __device__ __forceinline__ void generic(const f32x4 (&acc)[2][2][4][2], const Unit& u, int wr, int wc, int fr, int fq) const {
;     ...
;                         const int b = u.pn >> 3, g = u.pn & 7, k = (Lb == 4096) ? (2 * ((u.pm & 7) * BM + rt) + (u.pm >> 3)) : (u.pm * BM + rt), rb = rowbase0 + b * (Lb + 1);
;                         u32x4 w; w.x = cvt_pk_bf16(v0[0], v0[1]); w.y = cvt_pk_bf16(v0[2], v0[3]); w.z = cvt_pk_bf16(v1[0], v1[1]); w.w = cvt_pk_bf16(v1[2], v1[3]);
;                         *(u32x4*)(O + (size_t)(rb + k) * 2048 + g * 256 + ct) = w;
;                         if (k == 0) *(u32x4*)(O + (size_t)(rb + Lb) * 2048 + g * 256 + ct) = w;
	ds_read_b128 v[180:183], v153 offset:49152
	ds_read_b128 v[204:207], v153 offset:50176
	ds_read_b128 v[208:211], v153 offset:51200
	ds_read_b128 v[212:215], v153 offset:52224
	ds_read_b128 v[216:219], v153 offset:53248
	ds_read_b128 v[220:223], v153 offset:54272
	ds_read_b128 v[224:227], v153 offset:55296
	ds_read_b128 v[228:231], v153 offset:56320
	global_load_lds_dwordx4 v[158:159], off
	v_lshl_add_u64 v[158:159], s[16:17], 0, v[132:133]
	s_mov_b32 m0, s67
	s_nop 0
	global_load_lds_dwordx4 v[158:159], off
	s_waitcnt vmcnt(10)
	s_barrier
	s_waitcnt lgkmcnt(0)
	s_setprio 1
	s_waitcnt lgkmcnt(0)
	v_mfma_f32_16x16x32_bf16 v[60:63], v[154:157], v[180:183], v[60:63]
	v_mfma_f32_16x16x32_bf16 v[56:59], v[172:175], v[180:183], v[56:59]
	v_mfma_f32_16x16x32_bf16 v[44:47], v[154:157], v[208:211], v[44:47]
	v_mfma_f32_16x16x32_bf16 v[40:43], v[172:175], v[208:211], v[40:43]
	v_mfma_f32_16x16x32_bf16 v[28:31], v[154:157], v[216:219], v[28:31]
	v_mfma_f32_16x16x32_bf16 v[24:27], v[172:175], v[216:219], v[24:27]
	v_mfma_f32_16x16x32_bf16 v[12:15], v[154:157], v[224:227], v[12:15]
	v_mfma_f32_16x16x32_bf16 v[8:11], v[172:175], v[224:227], v[8:11]
	v_mfma_f32_16x16x32_bf16 v[60:63], v[168:171], v[204:207], v[60:63]
	v_mfma_f32_16x16x32_bf16 v[56:59], v[176:179], v[204:207], v[56:59]
	v_mfma_f32_16x16x32_bf16 v[44:47], v[168:171], v[212:215], v[44:47]
	v_mfma_f32_16x16x32_bf16 v[40:43], v[176:179], v[212:215], v[40:43]
	v_mfma_f32_16x16x32_bf16 v[28:31], v[168:171], v[220:223], v[28:31]
	v_mfma_f32_16x16x32_bf16 v[24:27], v[176:179], v[220:223], v[24:27]
	v_mfma_f32_16x16x32_bf16 v[12:15], v[168:171], v[228:231], v[12:15]
	v_mfma_f32_16x16x32_bf16 v[8:11], v[176:179], v[228:231], v[8:11]
	s_setprio 0
	s_barrier
	s_add_u32 s14, s14, 0x880080
	s_addc_u32 s15, s15, 0
	s_add_i32 s10, s11, s47
	v_lshl_add_u64 v[154:155], s[14:15], 0, v[130:131]
	s_mov_b32 m0, s10
	s_nop 0
	global_load_lds_dwordx4 v[154:155], off
	v_lshl_add_u64 v[154:155], s[14:15], 0, v[134:135]
	s_add_i32 m0, s10, 0x2000
	s_nop 0
	global_load_lds_dwordx4 v[154:155], off
	v_add_u32_e32 v158, 0x10000, v145
	ds_read_b128 v[154:157], v158
	ds_read_b128 v[168:171], v158 offset:1024
	ds_read_b128 v[172:175], v158 offset:2048
	ds_read_b128 v[176:179], v158 offset:3072
	s_waitcnt vmcnt(10)
	s_barrier
	s_setprio 1
	v_mfma_f32_16x16x32_bf16 v[52:55], v[232:235], v[180:183], v[52:55]
	v_mfma_f32_16x16x32_bf16 v[48:51], v[240:243], v[180:183], v[48:51]
	v_mfma_f32_16x16x32_bf16 v[36:39], v[232:235], v[208:211], v[36:39]
	v_mfma_f32_16x16x32_bf16 v[32:35], v[240:243], v[208:211], v[32:35]
	v_mfma_f32_16x16x32_bf16 v[20:23], v[232:235], v[216:219], v[20:23]
	v_mfma_f32_16x16x32_bf16 v[16:19], v[240:243], v[216:219], v[16:19]
	v_mfma_f32_16x16x32_bf16 v[4:7], v[232:235], v[224:227], v[4:7]
	v_mfma_f32_16x16x32_bf16 v[0:3], v[240:243], v[224:227], v[0:3]
	v_mfma_f32_16x16x32_bf16 v[52:55], v[236:239], v[204:207], v[52:55]
	v_mfma_f32_16x16x32_bf16 v[48:51], v[244:247], v[204:207], v[48:51]
	v_mfma_f32_16x16x32_bf16 v[36:39], v[236:239], v[212:215], v[36:39]
	v_mfma_f32_16x16x32_bf16 v[32:35], v[244:247], v[212:215], v[32:35]
	v_mfma_f32_16x16x32_bf16 v[20:23], v[236:239], v[220:223], v[20:23]
	v_mfma_f32_16x16x32_bf16 v[16:19], v[244:247], v[220:223], v[16:19]
	v_mfma_f32_16x16x32_bf16 v[4:7], v[236:239], v[228:231], v[4:7]
	v_mfma_f32_16x16x32_bf16 v[0:3], v[244:247], v[228:231], v[0:3]
	s_setprio 0
	s_add_i32 s44, s44, 2
	s_add_u32 s0, s0, 0x100
	s_addc_u32 s1, s1, 0
	s_cmp_gt_u32 s44, 29
	s_barrier
	s_cbranch_scc0 .LBB0_903
	s_waitcnt lgkmcnt(0)
	s_lshl_b32 s1, s7, 8
	s_and_b32 s8, s1, 0x700
	s_ashr_i32 s0, s6, 3
	v_add_u32_e32 v140, s8, v144
	s_ashr_i32 s7, s7, 3
	v_lshl_add_u32 v140, v140, 1, s7
	s_mulk_i32 s0, 0x1001
	v_cvt_pk_bf16_f32 v124, v124, v125
	v_cvt_pk_bf16_f32 v125, v126, v127
	v_cvt_pk_bf16_f32 v126, v120, v121
	v_add_u32_e32 v120, s0, v140
	v_ashrrev_i32_e32 v121, 31, v120
	s_lshl_b32 s1, s6, 8
	v_lshlrev_b64 v[120:121], 12, v[120:121]
	s_and_b32 s1, s1, 0x700
	v_lshl_add_u64 v[120:121], s[24:25], 0, v[120:121]
	s_lshl_b32 s22, s1, 1
	v_lshl_add_u64 v[120:121], v[120:121], 0, s[22:23]
	v_lshl_add_u64 v[120:121], v[120:121], 0, v[160:161]
	v_cmp_eq_u32_e64 s[44:45], 0, v140
	v_cvt_pk_bf16_f32 v127, v122, v123
	global_store_dwordx4 v[120:121], v[124:127], off
	s_and_saveexec_b64 s[14:15], s[44:45]
	s_cbranch_execz .LBB0_906
	s_ashr_i32 s1, s0, 31
	s_lshl_b64 s[16:17], s[0:1], 12
	s_add_u32 s1, s24, s16
	s_addc_u32 s6, s25, s17
	s_add_u32 s16, s1, s22
	s_addc_u32 s17, s6, 0
	v_lshl_add_u64 v[122:123], s[16:17], 0, v[160:161]
	v_add_co_u32_e32 v122, vcc, 0x1000000, v122
	s_nop 1
	v_addc_co_u32_e32 v123, vcc, 0, v123, vcc
	global_store_dwordx4 v[122:123], v[124:127], off

; #define PG8_STAGE(bufoff, gbase, voff) do { _Pragma("unroll") for (int _i = 0; _i < 2; ++_i) \
;         __builtin_amdgcn_global_load_lds((const unsigned*)((const char*)(gbase) + (voff)[_i]), (LAS unsigned*)(lds + (bufoff) + ldsw + _i * 8192), 16, 0, 0); } while (0)
; #define PG8_STAGE_A(bufoff, ptr, half, rev) do { if (REVA && (rev)) { const char* _p = (ptr) - ((half) ? hstepA : 0); PG8_STAGE(bufoff, _p, voffAr); } else { const char* _p = (ptr) + ((half) ? hstepA : 0); PG8_STAGE(bufoff, _p, voffA); } } while (0)
; #define PG8_LDA(dst, b, h) do { _Pragma("unroll") for (int m = 0; m < 4; ++m) _Pragma("unroll") for (int k = 0; k < 2; ++k) dst[m][k] = *(const LAS bf16x8*)(lds + PG8_SA(b, h) + aoff + m * 2048 + k * 1024); } while (0)
; #define PG8_LDB(dst, b, h) do { _Pragma("unroll") for (int n = 0; n < 2; ++n) _Pragma("unroll") for (int k = 0; k < 2; ++k) dst[n][k] = *(const LAS bf16x8*)(lds + PG8_SB(b, h) + boff + n * 2048 + k * 1024); } while (0)
; #define PG8_MMA(ai, bj, At, Bt) do { __builtin_amdgcn_s_setprio(1); _Pragma("unroll") for (int m = 0; m < 4; ++m) _Pragma("unroll") for (int n = 0; n < 2; ++n) _Pragma("unroll") for (int k = 0; k < 2; ++k) \
;         acc[ai][bj][m][n] = __builtin_amdgcn_mfma_f32_16x16x32_bf16(Bt[n][k], At[m][k], acc[ai][bj][m][n], 0, 0, 0); __builtin_amdgcn_s_setprio(0); } while (0)
;     ...
;         for (int t = 0; t < nt; t += 2) {
;             const bool last = (t == nt - 2);
;             const char* a1 = PG8_APTR(cA, cAr, t + 1); const bool r1 = REVA && ((t + 1) & 4);
;             const char* a2 = last ? nA : PG8_APTR(cA, cAr, t + 2); const bool r2 = REVA && !last && ((t + 2) & 4);
;             const char* a3 = last ? nA + kstep : PG8_APTR(cA, cAr, t + 3); const bool r3 = REVA && !last && ((t + 3) & 4);
;             const char* b2 = last ? nB : cB + (size_t)(t + 2) * kstep; const char* b3 = b2 + kstep; const size_t hb2 = last ? nHb : cHb;
;             PG8_LDB(B0, 0, 0); PG8_SCHED; PG8_LDA(At, 0, 0); PG8_STAGE_A(PG8_SA(1, 1), a1, 1, r1);
;             PG8_WAIT_L(8); PG8_BAR; PG8_WAIT_L(0); PG8_MMA(0, 0, At, B0); PG8_BAR; PG8_SCHED;
;             PG8_LDB(B1, 0, 1); PG8_STAGE(PG8_SB(0, 0), b2, voffB);
;             PG8_BAR; PG8_WAIT_L(0); PG8_MMA(0, 1, At, B1); PG8_BAR;
;             PG8_LDA(At, 0, 1); PG8_STAGE_A(PG8_SA(0, 0), a2, 0, r2);
;             PG8_BAR; PG8_WAIT_L(0); PG8_MMA(1, 0, At, B0); PG8_BAR; PG8_SCHED;
.LBB0_1132:
	s_add_u32 s10, s0, s2
	s_addc_u32 s11, s1, s3
	s_add_u32 s16, s10, 0x100
	s_addc_u32 s17, s11, 0
	s_add_u32 s10, s10, 0x180
	s_addc_u32 s11, s11, 0
	s_add_u32 s14, s8, s2
	s_addc_u32 s15, s9, s3
	s_add_i32 s27, 0, 0x10000
	s_cmpk_eq_i32 s2, 0xf00
	s_cselect_b32 s15, s25, s15
	s_cselect_b32 s14, s24, s14
	s_cselect_b32 s21, s79, s17
	s_cselect_b32 s20, s78, s16
	s_cselect_b32 s17, s7, s11
	s_cselect_b32 s16, s6, s10
	v_lshl_add_u64 v[184:185], v[96:97], 0, s[2:3]
	s_add_i32 m0, s70, 0xc000
	ds_read_b128 v[148:151], v209
	ds_read_b128 v[152:155], v209 offset:1024
	ds_read_b128 v[156:159], v209 offset:2048
	ds_read_b128 v[180:183], v209 offset:3072
	ds_read_b128 v[210:213], v209 offset:4096
	ds_read_b128 v[214:217], v209 offset:5120
	ds_read_b128 v[218:221], v209 offset:6144
	ds_read_b128 v[222:225], v209 offset:7168
	global_load_lds_dwordx4 v[184:185], off
	v_lshl_add_u64 v[184:185], v[98:99], 0, s[2:3]
	s_add_i32 m0, s70, 0xe000
	s_nop 0
	global_load_lds_dwordx4 v[184:185], off
	s_waitcnt lgkmcnt(8)
	s_waitcnt vmcnt(10)
	s_barrier
	s_waitcnt lgkmcnt(0)
	s_setprio 1
	s_waitcnt lgkmcnt(0)
	v_mfma_f32_16x16x32_bf16 v[144:147], v[108:111], v[148:151], v[144:147]
	v_mfma_f32_16x16x32_bf16 v[136:139], v[132:135], v[148:151], v[136:139]
	v_mfma_f32_16x16x32_bf16 v[116:119], v[108:111], v[156:159], v[116:119]
	v_mfma_f32_16x16x32_bf16 v[112:115], v[132:135], v[156:159], v[112:115]
	v_mfma_f32_16x16x32_bf16 v[92:95], v[108:111], v[210:213], v[92:95]
	v_mfma_f32_16x16x32_bf16 v[88:91], v[132:135], v[210:213], v[88:91]
	v_mfma_f32_16x16x32_bf16 v[76:79], v[108:111], v[218:221], v[76:79]
	v_mfma_f32_16x16x32_bf16 v[72:75], v[132:135], v[218:221], v[72:75]
	v_mfma_f32_16x16x32_bf16 v[144:147], v[120:123], v[152:155], v[144:147]
	v_mfma_f32_16x16x32_bf16 v[136:139], v[140:143], v[152:155], v[136:139]
	v_mfma_f32_16x16x32_bf16 v[116:119], v[120:123], v[180:183], v[116:119]
	v_mfma_f32_16x16x32_bf16 v[112:115], v[140:143], v[180:183], v[112:115]
	v_mfma_f32_16x16x32_bf16 v[92:95], v[120:123], v[214:217], v[92:95]
	v_mfma_f32_16x16x32_bf16 v[88:91], v[140:143], v[214:217], v[88:91]
	v_mfma_f32_16x16x32_bf16 v[76:79], v[120:123], v[222:225], v[76:79]
	v_mfma_f32_16x16x32_bf16 v[72:75], v[140:143], v[222:225], v[72:75]
	s_setprio 0
	s_barrier
	s_add_i32 s10, 0, 0x14000
	v_add_u32_e32 v184, s10, v205
	s_add_i32 s11, s27, s69
	ds_read_b128 v[226:229], v184
	ds_read_b128 v[230:233], v184 offset:1024
	ds_read_b128 v[234:237], v184 offset:2048
	ds_read_b128 v[238:241], v184 offset:3072
	v_lshl_add_u64 v[184:185], s[14:15], 0, v[172:173]
	s_mov_b32 m0, s11
	v_lshl_add_u64 v[190:191], s[14:15], 0, v[168:169]
	global_load_lds_dwordx4 v[184:185], off
	s_add_i32 m0, s11, 0x2000
	s_nop 0
	global_load_lds_dwordx4 v[190:191], off
	s_waitcnt vmcnt(10)
	s_barrier
	s_waitcnt lgkmcnt(0)
	s_setprio 1
	s_waitcnt lgkmcnt(0)
	v_mfma_f32_16x16x32_bf16 v[128:131], v[226:229], v[148:151], v[128:131]
	v_mfma_f32_16x16x32_bf16 v[124:127], v[234:237], v[148:151], v[124:127]
	v_mfma_f32_16x16x32_bf16 v[104:107], v[226:229], v[156:159], v[104:107]
	v_mfma_f32_16x16x32_bf16 v[100:103], v[234:237], v[156:159], v[100:103]
	v_mfma_f32_16x16x32_bf16 v[84:87], v[226:229], v[210:213], v[84:87]
	v_mfma_f32_16x16x32_bf16 v[80:83], v[234:237], v[210:213], v[80:83]
	v_mfma_f32_16x16x32_bf16 v[68:71], v[226:229], v[218:221], v[68:71]
	v_mfma_f32_16x16x32_bf16 v[64:67], v[234:237], v[218:221], v[64:67]
	v_mfma_f32_16x16x32_bf16 v[128:131], v[230:233], v[152:155], v[128:131]
	v_mfma_f32_16x16x32_bf16 v[124:127], v[238:241], v[152:155], v[124:127]
	v_mfma_f32_16x16x32_bf16 v[104:107], v[230:233], v[180:183], v[104:107]
	v_mfma_f32_16x16x32_bf16 v[100:103], v[238:241], v[180:183], v[100:103]
	v_mfma_f32_16x16x32_bf16 v[84:87], v[230:233], v[214:217], v[84:87]
	v_mfma_f32_16x16x32_bf16 v[80:83], v[238:241], v[214:217], v[80:83]
	v_mfma_f32_16x16x32_bf16 v[68:71], v[230:233], v[222:225], v[68:71]
	v_mfma_f32_16x16x32_bf16 v[64:67], v[238:241], v[222:225], v[64:67]
	s_setprio 0
	s_mov_b32 m0, s70
	v_lshl_add_u64 v[242:243], s[20:21], 0, v[174:175]
	s_barrier
	ds_read_b128 v[148:151], v209 offset:16384
	ds_read_b128 v[152:155], v209 offset:17408
	ds_read_b128 v[156:159], v209 offset:18432
	ds_read_b128 v[180:183], v209 offset:19456
	ds_read_b128 v[210:213], v209 offset:20480
	ds_read_b128 v[214:217], v209 offset:21504
	ds_read_b128 v[218:221], v209 offset:22528
	ds_read_b128 v[222:225], v209 offset:23552
	global_load_lds_dwordx4 v[242:243], off
	v_lshl_add_u64 v[242:243], s[20:21], 0, v[170:171]
	s_mov_b32 m0, s71
	s_nop 0
	global_load_lds_dwordx4 v[242:243], off
	s_waitcnt vmcnt(10)
	s_barrier
	s_waitcnt lgkmcnt(0)
	s_setprio 1
	s_waitcnt lgkmcnt(0)
	v_mfma_f32_16x16x32_bf16 v[60:63], v[108:111], v[148:151], v[60:63]
	v_mfma_f32_16x16x32_bf16 v[56:59], v[132:135], v[148:151], v[56:59]
	v_mfma_f32_16x16x32_bf16 v[44:47], v[108:111], v[156:159], v[44:47]
	v_mfma_f32_16x16x32_bf16 v[40:43], v[132:135], v[156:159], v[40:43]
	v_mfma_f32_16x16x32_bf16 v[28:31], v[108:111], v[210:213], v[28:31]
	v_mfma_f32_16x16x32_bf16 v[24:27], v[132:135], v[210:213], v[24:27]
	v_mfma_f32_16x16x32_bf16 v[12:15], v[108:111], v[218:221], v[12:15]
	v_mfma_f32_16x16x32_bf16 v[8:11], v[132:135], v[218:221], v[8:11]
	v_mfma_f32_16x16x32_bf16 v[60:63], v[120:123], v[152:155], v[60:63]
	v_mfma_f32_16x16x32_bf16 v[56:59], v[140:143], v[152:155], v[56:59]
	v_mfma_f32_16x16x32_bf16 v[44:47], v[120:123], v[180:183], v[44:47]
	v_mfma_f32_16x16x32_bf16 v[40:43], v[140:143], v[180:183], v[40:43]
	v_mfma_f32_16x16x32_bf16 v[28:31], v[120:123], v[214:217], v[28:31]
	v_mfma_f32_16x16x32_bf16 v[24:27], v[140:143], v[214:217], v[24:27]
	v_mfma_f32_16x16x32_bf16 v[12:15], v[120:123], v[222:225], v[12:15]
	v_mfma_f32_16x16x32_bf16 v[8:11], v[140:143], v[222:225], v[8:11]
	s_setprio 0
	s_barrier
; #define PG8_STAGE(bufoff, gbase, voff) do { _Pragma("unroll") for (int _i = 0; _i < 2; ++_i) \
;         __builtin_amdgcn_global_load_lds((const unsigned*)((const char*)(gbase) + (voff)[_i]), (LAS unsigned*)(lds + (bufoff) + ldsw + _i * 8192), 16, 0, 0); } while (0)
; #define PG8_STAGE_A(bufoff, ptr, half, rev) do { if (REVA && (rev)) { const char* _p = (ptr) - ((half) ? hstepA : 0); PG8_STAGE(bufoff, _p, voffAr); } else { const char* _p = (ptr) + ((half) ? hstepA : 0); PG8_STAGE(bufoff, _p, voffA); } } while (0)
; #define PG8_LDA(dst, b, h) do { _Pragma("unroll") for (int m = 0; m < 4; ++m) _Pragma("unroll") for (int k = 0; k < 2; ++k) dst[m][k] = *(const LAS bf16x8*)(lds + PG8_SA(b, h) + aoff + m * 2048 + k * 1024); } while (0)
; #define PG8_LDB(dst, b, h) do { _Pragma("unroll") for (int n = 0; n < 2; ++n) _Pragma("unroll") for (int k = 0; k < 2; ++k) dst[n][k] = *(const LAS bf16x8*)(lds + PG8_SB(b, h) + boff + n * 2048 + k * 1024); } while (0)
; #define PG8_MMA(ai, bj, At, Bt) do { __builtin_amdgcn_s_setprio(1); _Pragma("unroll") for (int m = 0; m < 4; ++m) _Pragma("unroll") for (int n = 0; n < 2; ++n) _Pragma("unroll") for (int k = 0; k < 2; ++k) \
;         acc[ai][bj][m][n] = __builtin_amdgcn_mfma_f32_16x16x32_bf16(Bt[n][k], At[m][k], acc[ai][bj][m][n], 0, 0, 0); __builtin_amdgcn_s_setprio(0); } while (0)
; #define PG8_WAIT_V(n) asm volatile("s_waitcnt vmcnt(" #n ")" ::: "memory")
; #define PG8_WAIT_L(n) asm volatile("s_waitcnt lgkmcnt(" #n ")" ::: "memory")
; #define PG8_BAR __builtin_amdgcn_s_barrier()
; #define PG8_SCHED __builtin_amdgcn_sched_barrier(0)
;     ...
;             PG8_STAGE(PG8_SB(0, 1), b2 + hb2, voffB);
;             PG8_WAIT_V(6); PG8_BAR; PG8_MMA(1, 1, At, B1); PG8_BAR;
;             PG8_LDB(B0, 1, 0); PG8_SCHED; PG8_LDA(At, 1, 0); PG8_STAGE_A(PG8_SA(0, 1), a2, 1, r2);
;             PG8_WAIT_L(8); PG8_BAR; PG8_WAIT_L(0); PG8_MMA(0, 0, At, B0); PG8_BAR; PG8_SCHED;
;             PG8_LDB(B1, 1, 1); PG8_STAGE(PG8_SB(1, 0), b3, voffB);
;             PG8_BAR; PG8_WAIT_L(0); PG8_MMA(0, 1, At, B1); PG8_BAR;
	s_add_u32 s36, s14, 0x80000
	s_addc_u32 s37, s15, 0
	s_add_i32 s10, s10, s69
	v_lshl_add_u64 v[108:109], s[36:37], 0, v[172:173]
	s_mov_b32 m0, s10
	s_nop 0
	global_load_lds_dwordx4 v[108:109], off
	v_lshl_add_u64 v[108:109], s[36:37], 0, v[168:169]
	s_add_i32 m0, s10, 0x2000
	s_nop 0
	global_load_lds_dwordx4 v[108:109], off
	v_add_u32_e32 v140, 0x18000, v205
	ds_read_b128 v[108:111], v140
	ds_read_b128 v[120:123], v140 offset:1024
	ds_read_b128 v[132:135], v140 offset:2048
	ds_read_b128 v[140:143], v140 offset:3072
	s_waitcnt vmcnt(10)
	s_barrier
	s_setprio 1
	v_mfma_f32_16x16x32_bf16 v[52:55], v[226:229], v[148:151], v[52:55]
	v_mfma_f32_16x16x32_bf16 v[48:51], v[234:237], v[148:151], v[48:51]
	v_mfma_f32_16x16x32_bf16 v[36:39], v[226:229], v[156:159], v[36:39]
	v_mfma_f32_16x16x32_bf16 v[32:35], v[234:237], v[156:159], v[32:35]
	v_mfma_f32_16x16x32_bf16 v[20:23], v[226:229], v[210:213], v[20:23]
	v_mfma_f32_16x16x32_bf16 v[16:19], v[234:237], v[210:213], v[16:19]
	v_mfma_f32_16x16x32_bf16 v[4:7], v[226:229], v[218:221], v[4:7]
	v_mfma_f32_16x16x32_bf16 v[0:3], v[234:237], v[218:221], v[0:3]
	v_mfma_f32_16x16x32_bf16 v[52:55], v[230:233], v[152:155], v[52:55]
	v_mfma_f32_16x16x32_bf16 v[48:51], v[238:241], v[152:155], v[48:51]
	v_mfma_f32_16x16x32_bf16 v[36:39], v[230:233], v[180:183], v[36:39]
	v_mfma_f32_16x16x32_bf16 v[32:35], v[238:241], v[180:183], v[32:35]
	v_mfma_f32_16x16x32_bf16 v[20:23], v[230:233], v[214:217], v[20:23]
	v_mfma_f32_16x16x32_bf16 v[16:19], v[238:241], v[214:217], v[16:19]
	v_mfma_f32_16x16x32_bf16 v[4:7], v[230:233], v[222:225], v[4:7]
	v_mfma_f32_16x16x32_bf16 v[0:3], v[238:241], v[222:225], v[0:3]
	s_setprio 0
	s_add_i32 s10, 0, 0x18000
	s_barrier
	s_add_u32 s20, s20, 0x80000
	s_addc_u32 s21, s21, 0
	s_mov_b32 m0, s89
	v_lshl_add_u64 v[226:227], s[20:21], 0, v[174:175]
	ds_read_b128 v[148:151], v209 offset:32768
	ds_read_b128 v[152:155], v209 offset:33792
	ds_read_b128 v[156:159], v209 offset:34816
	ds_read_b128 v[180:183], v209 offset:35840
	ds_read_b128 v[210:213], v209 offset:36864
	ds_read_b128 v[214:217], v209 offset:37888
	ds_read_b128 v[218:221], v209 offset:38912
	ds_read_b128 v[222:225], v209 offset:39936
	global_load_lds_dwordx4 v[226:227], off
	v_lshl_add_u64 v[226:227], s[20:21], 0, v[170:171]
	s_mov_b32 m0, s90
	s_nop 0
	global_load_lds_dwordx4 v[226:227], off
	s_waitcnt lgkmcnt(8)
	s_waitcnt vmcnt(10)
	s_barrier
	s_waitcnt lgkmcnt(0)
	s_setprio 1
	s_waitcnt lgkmcnt(0)
	v_mfma_f32_16x16x32_bf16 v[144:147], v[108:111], v[148:151], v[144:147]
	v_mfma_f32_16x16x32_bf16 v[136:139], v[132:135], v[148:151], v[136:139]
	v_mfma_f32_16x16x32_bf16 v[116:119], v[108:111], v[156:159], v[116:119]
	v_mfma_f32_16x16x32_bf16 v[112:115], v[132:135], v[156:159], v[112:115]
	v_mfma_f32_16x16x32_bf16 v[92:95], v[108:111], v[210:213], v[92:95]
	v_mfma_f32_16x16x32_bf16 v[88:91], v[132:135], v[210:213], v[88:91]
	v_mfma_f32_16x16x32_bf16 v[76:79], v[108:111], v[218:221], v[76:79]
	v_mfma_f32_16x16x32_bf16 v[72:75], v[132:135], v[218:221], v[72:75]
	v_mfma_f32_16x16x32_bf16 v[144:147], v[120:123], v[152:155], v[144:147]
	v_mfma_f32_16x16x32_bf16 v[136:139], v[140:143], v[152:155], v[136:139]
	v_mfma_f32_16x16x32_bf16 v[116:119], v[120:123], v[180:183], v[116:119]
	v_mfma_f32_16x16x32_bf16 v[112:115], v[140:143], v[180:183], v[112:115]
	v_mfma_f32_16x16x32_bf16 v[92:95], v[120:123], v[214:217], v[92:95]
	v_mfma_f32_16x16x32_bf16 v[88:91], v[140:143], v[214:217], v[88:91]
	v_mfma_f32_16x16x32_bf16 v[76:79], v[120:123], v[222:225], v[76:79]
	v_mfma_f32_16x16x32_bf16 v[72:75], v[140:143], v[222:225], v[72:75]
	s_setprio 0
	s_barrier
	s_add_i32 s11, 0, 0x1c000
	s_add_i32 s10, s10, s69
	v_add_u32_e32 v238, s11, v205
	v_lshl_add_u64 v[184:185], v[184:185], 0, s[28:29]
	s_mov_b32 m0, s10
	ds_read_b128 v[226:229], v238
	ds_read_b128 v[230:233], v238 offset:1024
	ds_read_b128 v[234:237], v238 offset:2048
	ds_read_b128 v[238:241], v238 offset:3072
	global_load_lds_dwordx4 v[184:185], off
	v_lshl_add_u64 v[184:185], v[190:191], 0, s[28:29]
	s_add_i32 m0, s10, 0x2000
	s_nop 0
	global_load_lds_dwordx4 v[184:185], off
	s_waitcnt vmcnt(10)
	s_barrier
	s_waitcnt lgkmcnt(0)
	s_setprio 1
	s_waitcnt lgkmcnt(0)
	v_mfma_f32_16x16x32_bf16 v[128:131], v[226:229], v[148:151], v[128:131]
	v_mfma_f32_16x16x32_bf16 v[124:127], v[234:237], v[148:151], v[124:127]
	v_mfma_f32_16x16x32_bf16 v[104:107], v[226:229], v[156:159], v[104:107]
	v_mfma_f32_16x16x32_bf16 v[100:103], v[234:237], v[156:159], v[100:103]
	v_mfma_f32_16x16x32_bf16 v[84:87], v[226:229], v[210:213], v[84:87]
	v_mfma_f32_16x16x32_bf16 v[80:83], v[234:237], v[210:213], v[80:83]
	v_mfma_f32_16x16x32_bf16 v[68:71], v[226:229], v[218:221], v[68:71]
	v_mfma_f32_16x16x32_bf16 v[64:67], v[234:237], v[218:221], v[64:67]
	v_mfma_f32_16x16x32_bf16 v[128:131], v[230:233], v[152:155], v[128:131]
	v_mfma_f32_16x16x32_bf16 v[124:127], v[238:241], v[152:155], v[124:127]
	v_mfma_f32_16x16x32_bf16 v[104:107], v[230:233], v[180:183], v[104:107]
	v_mfma_f32_16x16x32_bf16 v[100:103], v[238:241], v[180:183], v[100:103]
	v_mfma_f32_16x16x32_bf16 v[84:87], v[230:233], v[214:217], v[84:87]
	v_mfma_f32_16x16x32_bf16 v[80:83], v[238:241], v[214:217], v[80:83]
	v_mfma_f32_16x16x32_bf16 v[68:71], v[230:233], v[222:225], v[68:71]
	v_mfma_f32_16x16x32_bf16 v[64:67], v[238:241], v[222:225], v[64:67]
	s_setprio 0
	s_mov_b32 m0, s97
	v_lshl_add_u64 v[184:185], s[16:17], 0, v[174:175]
	s_barrier
; #define PG8_STAGE(bufoff, gbase, voff) do { _Pragma("unroll") for (int _i = 0; _i < 2; ++_i) \
;         __builtin_amdgcn_global_load_lds((const unsigned*)((const char*)(gbase) + (voff)[_i]), (LAS unsigned*)(lds + (bufoff) + ldsw + _i * 8192), 16, 0, 0); } while (0)
; #define PG8_STAGE_A(bufoff, ptr, half, rev) do { if (REVA && (rev)) { const char* _p = (ptr) - ((half) ? hstepA : 0); PG8_STAGE(bufoff, _p, voffAr); } else { const char* _p = (ptr) + ((half) ? hstepA : 0); PG8_STAGE(bufoff, _p, voffA); } } while (0)
; #define PG8_LDA(dst, b, h) do { _Pragma("unroll") for (int m = 0; m < 4; ++m) _Pragma("unroll") for (int k = 0; k < 2; ++k) dst[m][k] = *(const LAS bf16x8*)(lds + PG8_SA(b, h) + aoff + m * 2048 + k * 1024); } while (0)
; #define PG8_MMA(ai, bj, At, Bt) do { __builtin_amdgcn_s_setprio(1); _Pragma("unroll") for (int m = 0; m < 4; ++m) _Pragma("unroll") for (int n = 0; n < 2; ++n) _Pragma("unroll") for (int k = 0; k < 2; ++k) \
;         acc[ai][bj][m][n] = __builtin_amdgcn_mfma_f32_16x16x32_bf16(Bt[n][k], At[m][k], acc[ai][bj][m][n], 0, 0, 0); __builtin_amdgcn_s_setprio(0); } while (0)
; #define PG8_WAIT_V(n) asm volatile("s_waitcnt vmcnt(" #n ")" ::: "memory")
; #define PG8_BAR __builtin_amdgcn_s_barrier()
;     ...
;             PG8_LDA(At, 1, 1); PG8_STAGE_A(PG8_SA(1, 0), a3, 0, r3);
;             PG8_BAR; PG8_WAIT_L(0); PG8_MMA(1, 0, At, B0); PG8_BAR; PG8_SCHED;
;             PG8_STAGE(PG8_SB(1, 1), b3 + hb2, voffB);
;             PG8_WAIT_V(6); PG8_BAR; PG8_MMA(1, 1, At, B1); PG8_BAR;
;     __device__ __forceinline__ void gates(const f32x4 (&acc)[2][2][4][2], const Unit& u, int wr, int wc, int fr, int fq) const {
;         const bool ret = u.pn < 8;
;         const bf16_t* mulp = ret ? (OFp + u.pn * BM) : (Y + (u.pn - 8) * BM);
; #pragma unroll
;         for (int ai = 0; ai < 2; ++ai) {
;             u32x4 yv[4][2]; float rs[4];
; #pragma unroll
;             for (int m = 0; m < 4; ++m) {
;                 const size_t row = (size_t)(u.pm * BM + ai * HALF + wr * 64 + m * 16 + fr);
; #pragma unroll
;                 for (int bj = 0; bj < 2; ++bj) yv[m][bj] = *(const u32x4*)(mulp + row * 2048 + bj * HALF + wc * 32 + 8 * fq);
;                 rs[m] = 1.0f;
;                 if (ret) { const f32x4 sq = *(const f32x4*)(SSp + row * 32 + u.pn * 4); rs[m] = rsqrtf((sq[0] + sq[1] + sq[2] + sq[3]) * (1.0f / 256.0f) + 1e-6f); }
;             }
	ds_read_b128 v[148:151], v209 offset:49152
	ds_read_b128 v[152:155], v209 offset:50176
	ds_read_b128 v[156:159], v209 offset:51200
	ds_read_b128 v[180:183], v209 offset:52224
	ds_read_b128 v[210:213], v209 offset:53248
	ds_read_b128 v[214:217], v209 offset:54272
	ds_read_b128 v[218:221], v209 offset:55296
	ds_read_b128 v[222:225], v209 offset:56320
	global_load_lds_dwordx4 v[184:185], off
	v_lshl_add_u64 v[184:185], s[16:17], 0, v[170:171]
	s_mov_b32 m0, s52
	s_nop 0
	global_load_lds_dwordx4 v[184:185], off
	s_waitcnt vmcnt(10)
	s_barrier
	s_waitcnt lgkmcnt(0)
	s_setprio 1
	s_waitcnt lgkmcnt(0)
	v_mfma_f32_16x16x32_bf16 v[60:63], v[108:111], v[148:151], v[60:63]
	v_mfma_f32_16x16x32_bf16 v[56:59], v[132:135], v[148:151], v[56:59]
	v_mfma_f32_16x16x32_bf16 v[44:47], v[108:111], v[156:159], v[44:47]
	v_mfma_f32_16x16x32_bf16 v[40:43], v[132:135], v[156:159], v[40:43]
	v_mfma_f32_16x16x32_bf16 v[28:31], v[108:111], v[210:213], v[28:31]
	v_mfma_f32_16x16x32_bf16 v[24:27], v[132:135], v[210:213], v[24:27]
	v_mfma_f32_16x16x32_bf16 v[12:15], v[108:111], v[218:221], v[12:15]
	v_mfma_f32_16x16x32_bf16 v[8:11], v[132:135], v[218:221], v[8:11]
	v_mfma_f32_16x16x32_bf16 v[60:63], v[120:123], v[152:155], v[60:63]
	v_mfma_f32_16x16x32_bf16 v[56:59], v[140:143], v[152:155], v[56:59]
	v_mfma_f32_16x16x32_bf16 v[44:47], v[120:123], v[180:183], v[44:47]
	v_mfma_f32_16x16x32_bf16 v[40:43], v[140:143], v[180:183], v[40:43]
	v_mfma_f32_16x16x32_bf16 v[28:31], v[120:123], v[214:217], v[28:31]
	v_mfma_f32_16x16x32_bf16 v[24:27], v[140:143], v[214:217], v[24:27]
	v_mfma_f32_16x16x32_bf16 v[12:15], v[120:123], v[222:225], v[12:15]
	v_mfma_f32_16x16x32_bf16 v[8:11], v[140:143], v[222:225], v[8:11]
	s_setprio 0
	s_barrier
	s_add_u32 s14, s14, 0x80080
	s_addc_u32 s15, s15, 0
	s_add_i32 s10, s11, s69
	v_lshl_add_u64 v[108:109], s[14:15], 0, v[172:173]
	s_mov_b32 m0, s10
	s_nop 0
	global_load_lds_dwordx4 v[108:109], off
	v_lshl_add_u64 v[108:109], s[14:15], 0, v[168:169]
	s_add_i32 m0, s10, 0x2000
	s_nop 0
	global_load_lds_dwordx4 v[108:109], off
	v_add_u32_e32 v140, 0x10000, v205
	ds_read_b128 v[108:111], v140
	ds_read_b128 v[120:123], v140 offset:1024
	ds_read_b128 v[132:135], v140 offset:2048
	ds_read_b128 v[140:143], v140 offset:3072
	s_waitcnt vmcnt(10)
	s_barrier
	s_setprio 1
	v_mfma_f32_16x16x32_bf16 v[52:55], v[226:229], v[148:151], v[52:55]
	v_mfma_f32_16x16x32_bf16 v[48:51], v[234:237], v[148:151], v[48:51]
	v_mfma_f32_16x16x32_bf16 v[36:39], v[226:229], v[156:159], v[36:39]
	v_mfma_f32_16x16x32_bf16 v[32:35], v[234:237], v[156:159], v[32:35]
	v_mfma_f32_16x16x32_bf16 v[20:23], v[226:229], v[210:213], v[20:23]
	v_mfma_f32_16x16x32_bf16 v[16:19], v[234:237], v[210:213], v[16:19]
	v_mfma_f32_16x16x32_bf16 v[4:7], v[226:229], v[218:221], v[4:7]
	v_mfma_f32_16x16x32_bf16 v[0:3], v[234:237], v[218:221], v[0:3]
	v_mfma_f32_16x16x32_bf16 v[52:55], v[230:233], v[152:155], v[52:55]
	v_mfma_f32_16x16x32_bf16 v[48:51], v[238:241], v[152:155], v[48:51]
	v_mfma_f32_16x16x32_bf16 v[36:39], v[230:233], v[180:183], v[36:39]
	v_mfma_f32_16x16x32_bf16 v[32:35], v[238:241], v[180:183], v[32:35]
	v_mfma_f32_16x16x32_bf16 v[20:23], v[230:233], v[214:217], v[20:23]
	v_mfma_f32_16x16x32_bf16 v[16:19], v[238:241], v[214:217], v[16:19]
	v_mfma_f32_16x16x32_bf16 v[4:7], v[230:233], v[222:225], v[4:7]
	v_mfma_f32_16x16x32_bf16 v[0:3], v[238:241], v[222:225], v[0:3]
	s_setprio 0
	s_add_i32 s26, s26, 2
	s_add_u32 s2, s2, 0x100
	s_addc_u32 s3, s3, 0
	s_cmp_gt_u32 s26, 29
	s_barrier
	s_cbranch_scc0 .LBB0_1132
	s_waitcnt lgkmcnt(0)
	s_lshl_b32 s0, s4, 8
	s_ashr_i32 s1, s0, 31
	s_lshl_b64 s[26:27], s[0:1], 1
	s_add_u32 s6, s93, s26
	s_addc_u32 s7, s94, s27
	s_addk_i32 s0, 0xf800
	s_mov_b32 s1, s23
	s_lshl_b64 s[0:1], s[0:1], 1
	s_add_u32 s8, s91, s0
	s_addc_u32 s9, s92, s1
	s_cmp_lt_i32 s4, 8
	s_cselect_b64 s[0:1], -1, 0
	s_and_b64 s[2:3], s[0:1], exec
	s_cselect_b32 s3, s6, s8
	s_cselect_b32 s2, s7, s9
	s_add_u32 s6, s3, s22
	s_addc_u32 s7, s2, 0
	s_lshl_b32 s2, s5, 8
	v_add_u32_e32 v180, s2, v204
	v_ashrrev_i32_e32 v181, 31, v180
	v_lshl_add_u64 v[182:183], s[6:7], 0, v[160:161]
	v_lshlrev_b64 v[96:97], 12, v[180:181]
	v_lshl_add_u64 v[96:97], v[182:183], 0, v[96:97]
	global_load_dwordx4 v[156:159], v[96:97], off
	global_load_dwordx4 v[152:155], v[96:97], off offset:256
	s_lshl_b32 s6, s4, 2
	s_ashr_i32 s7, s6, 31
	s_lshl_b64 s[6:7], s[6:7], 2
	s_add_u32 s36, s95, s6
	s_addc_u32 s37, s96, s7
	s_cmp_gt_i32 s4, 7
	v_mov_b32_e32 v212, 1.0
	v_mov_b32_e32 v213, 1.0
	s_cbranch_scc1 .LBB0_1135
	v_lshlrev_b64 v[96:97], 7, v[180:181]
	v_lshl_add_u64 v[96:97], s[36:37], 0, v[96:97]
	global_load_dwordx4 v[96:99], v[96:97], off
	s_waitcnt vmcnt(0)
	v_add_f32_e32 v96, v96, v97
	v_add_f32_e32 v96, v98, v96
	v_add_f32_e32 v96, v99, v96
	v_fmamk_f32 v96, v96, 0x3b800000, v194
	v_mul_f32_e32 v97, 0x4b800000, v96
	v_cmp_gt_f32_e32 vcc, s55, v96
	s_nop 1
	v_cndmask_b32_e32 v96, v96, v97, vcc
	v_rsq_f32_e32 v96, v96
	s_nop 0
	v_mul_f32_e32 v97, 0x45800000, v96
	v_cndmask_b32_e32 v213, v96, v97, vcc

; #define PG8_STAGE(bufoff, gbase, voff) do { _Pragma("unroll") for (int _i = 0; _i < 2; ++_i) \
;         __builtin_amdgcn_global_load_lds((const unsigned*)((const char*)(gbase) + (voff)[_i]), (LAS unsigned*)(lds + (bufoff) + ldsw + _i * 8192), 16, 0, 0); } while (0)
; #define PG8_STAGE_A(bufoff, ptr, half, rev) do { if (REVA && (rev)) { const char* _p = (ptr) - ((half) ? hstepA : 0); PG8_STAGE(bufoff, _p, voffAr); } else { const char* _p = (ptr) + ((half) ? hstepA : 0); PG8_STAGE(bufoff, _p, voffA); } } while (0)
; #define PG8_LDA(dst, b, h) do { _Pragma("unroll") for (int m = 0; m < 4; ++m) _Pragma("unroll") for (int k = 0; k < 2; ++k) dst[m][k] = *(const LAS bf16x8*)(lds + PG8_SA(b, h) + aoff + m * 2048 + k * 1024); } while (0)
; #define PG8_LDB(dst, b, h) do { _Pragma("unroll") for (int n = 0; n < 2; ++n) _Pragma("unroll") for (int k = 0; k < 2; ++k) dst[n][k] = *(const LAS bf16x8*)(lds + PG8_SB(b, h) + boff + n * 2048 + k * 1024); } while (0)
; #define PG8_MMA(ai, bj, At, Bt) do { __builtin_amdgcn_s_setprio(1); _Pragma("unroll") for (int m = 0; m < 4; ++m) _Pragma("unroll") for (int n = 0; n < 2; ++n) _Pragma("unroll") for (int k = 0; k < 2; ++k) \
;         acc[ai][bj][m][n] = __builtin_amdgcn_mfma_f32_16x16x32_bf16(Bt[n][k], At[m][k], acc[ai][bj][m][n], 0, 0, 0); __builtin_amdgcn_s_setprio(0); } while (0)
;     ...
;         for (int t = 0; t < nt; t += 2) {
;             const bool last = (t == nt - 2);
;             const char* a1 = PG8_APTR(cA, cAr, t + 1); const bool r1 = REVA && ((t + 1) & 4);
;             const char* a2 = last ? nA : PG8_APTR(cA, cAr, t + 2); const bool r2 = REVA && !last && ((t + 2) & 4);
;             const char* a3 = last ? nA + kstep : PG8_APTR(cA, cAr, t + 3); const bool r3 = REVA && !last && ((t + 3) & 4);
;             const char* b2 = last ? nB : cB + (size_t)(t + 2) * kstep; const char* b3 = b2 + kstep; const size_t hb2 = last ? nHb : cHb;
;             PG8_LDB(B0, 0, 0); PG8_SCHED; PG8_LDA(At, 0, 0); PG8_STAGE_A(PG8_SA(1, 1), a1, 1, r1);
;             PG8_WAIT_L(8); PG8_BAR; PG8_WAIT_L(0); PG8_MMA(0, 0, At, B0); PG8_BAR; PG8_SCHED;
;             PG8_LDB(B1, 0, 1); PG8_STAGE(PG8_SB(0, 0), b2, voffB);
;             PG8_BAR; PG8_WAIT_L(0); PG8_MMA(0, 1, At, B1); PG8_BAR;
;             PG8_LDA(At, 0, 1); PG8_STAGE_A(PG8_SA(0, 0), a2, 0, r2);
;             PG8_BAR; PG8_WAIT_L(0); PG8_MMA(1, 0, At, B0); PG8_BAR; PG8_SCHED;
.LBB0_1229:
	s_add_u32 s10, s0, s42
	s_addc_u32 s11, s1, s43
	s_add_u32 s16, s10, 0x100
	s_addc_u32 s17, s11, 0
	s_add_u32 s10, s10, 0x180
	s_addc_u32 s11, s11, 0
	s_add_u32 s14, s69, s42
	s_addc_u32 s15, s70, s43
	s_add_i32 s78, 0, 0x10000
	s_cmpk_eq_i32 s42, 0x1f00
	s_cselect_b32 s15, s39, s15
	s_cselect_b32 s14, s38, s14
	s_cselect_b32 s21, s37, s17
	s_cselect_b32 s20, s36, s16
	s_cselect_b32 s17, s27, s11
	s_cselect_b32 s16, s3, s10
	v_lshl_add_u64 v[158:159], v[128:129], 0, s[42:43]
	s_add_i32 m0, s48, 0xc000
	ds_read_b128 v[178:181], v172
	ds_read_b128 v[182:185], v172 offset:1024
	ds_read_b128 v[204:207], v172 offset:2048
	ds_read_b128 v[208:211], v172 offset:3072
	ds_read_b128 v[212:215], v172 offset:4096
	ds_read_b128 v[216:219], v172 offset:5120
	ds_read_b128 v[220:223], v172 offset:6144
	ds_read_b128 v[224:227], v172 offset:7168
	global_load_lds_dwordx4 v[158:159], off
	v_lshl_add_u64 v[158:159], v[130:131], 0, s[42:43]
	s_add_i32 m0, s48, 0xe000
	s_nop 0
	global_load_lds_dwordx4 v[158:159], off
	s_waitcnt lgkmcnt(8)
	s_waitcnt vmcnt(10)
	s_barrier
	s_waitcnt lgkmcnt(0)
	s_setprio 1
	s_waitcnt lgkmcnt(0)
	v_mfma_f32_16x16x32_bf16 v[124:127], v[132:135], v[178:181], v[124:127]
	v_mfma_f32_16x16x32_bf16 v[120:123], v[140:143], v[178:181], v[120:123]
	v_mfma_f32_16x16x32_bf16 v[112:115], v[132:135], v[204:207], v[112:115]
	v_mfma_f32_16x16x32_bf16 v[108:111], v[140:143], v[204:207], v[108:111]
	v_mfma_f32_16x16x32_bf16 v[92:95], v[132:135], v[212:215], v[92:95]
	v_mfma_f32_16x16x32_bf16 v[88:91], v[140:143], v[212:215], v[88:91]
	v_mfma_f32_16x16x32_bf16 v[84:87], v[132:135], v[220:223], v[84:87]
	v_mfma_f32_16x16x32_bf16 v[76:79], v[140:143], v[220:223], v[76:79]
	v_mfma_f32_16x16x32_bf16 v[124:127], v[136:139], v[182:185], v[124:127]
	v_mfma_f32_16x16x32_bf16 v[120:123], v[174:177], v[182:185], v[120:123]
	v_mfma_f32_16x16x32_bf16 v[112:115], v[136:139], v[208:211], v[112:115]
	v_mfma_f32_16x16x32_bf16 v[108:111], v[174:177], v[208:211], v[108:111]
	v_mfma_f32_16x16x32_bf16 v[92:95], v[136:139], v[216:219], v[92:95]
	v_mfma_f32_16x16x32_bf16 v[88:91], v[174:177], v[216:219], v[88:91]
	v_mfma_f32_16x16x32_bf16 v[84:87], v[136:139], v[224:227], v[84:87]
	v_mfma_f32_16x16x32_bf16 v[76:79], v[174:177], v[224:227], v[76:79]
	s_setprio 0
	s_barrier
	s_add_i32 s10, 0, 0x14000
	v_add_u32_e32 v158, s10, v171
	s_add_i32 s11, s78, s5
	ds_read_b128 v[228:231], v158
	ds_read_b128 v[232:235], v158 offset:1024
	ds_read_b128 v[236:239], v158 offset:2048
	ds_read_b128 v[240:243], v158 offset:3072
	v_lshl_add_u64 v[158:159], s[14:15], 0, v[150:151]
	s_mov_b32 m0, s11
	v_lshl_add_u64 v[168:169], s[14:15], 0, v[148:149]
	global_load_lds_dwordx4 v[158:159], off
	s_add_i32 m0, s11, 0x2000
	s_nop 0
	global_load_lds_dwordx4 v[168:169], off
	s_waitcnt vmcnt(10)
	s_barrier
	s_waitcnt lgkmcnt(0)
	s_setprio 1
	s_waitcnt lgkmcnt(0)
	v_mfma_f32_16x16x32_bf16 v[116:119], v[228:231], v[178:181], v[116:119]
	v_mfma_f32_16x16x32_bf16 v[104:107], v[236:239], v[178:181], v[104:107]
	v_mfma_f32_16x16x32_bf16 v[100:103], v[228:231], v[204:207], v[100:103]
	v_mfma_f32_16x16x32_bf16 v[96:99], v[236:239], v[204:207], v[96:99]
	v_mfma_f32_16x16x32_bf16 v[80:83], v[228:231], v[212:215], v[80:83]
	v_mfma_f32_16x16x32_bf16 v[72:75], v[236:239], v[212:215], v[72:75]
	v_mfma_f32_16x16x32_bf16 v[68:71], v[228:231], v[220:223], v[68:71]
	v_mfma_f32_16x16x32_bf16 v[64:67], v[236:239], v[220:223], v[64:67]
	v_mfma_f32_16x16x32_bf16 v[116:119], v[232:235], v[182:185], v[116:119]
	v_mfma_f32_16x16x32_bf16 v[104:107], v[240:243], v[182:185], v[104:107]
	v_mfma_f32_16x16x32_bf16 v[100:103], v[232:235], v[208:211], v[100:103]
	v_mfma_f32_16x16x32_bf16 v[96:99], v[240:243], v[208:211], v[96:99]
	v_mfma_f32_16x16x32_bf16 v[80:83], v[232:235], v[216:219], v[80:83]
	v_mfma_f32_16x16x32_bf16 v[72:75], v[240:243], v[216:219], v[72:75]
	v_mfma_f32_16x16x32_bf16 v[68:71], v[232:235], v[224:227], v[68:71]
	v_mfma_f32_16x16x32_bf16 v[64:67], v[240:243], v[224:227], v[64:67]
	s_setprio 0
	s_mov_b32 m0, s48
	v_lshl_add_u64 v[190:191], s[20:21], 0, v[150:151]
	s_barrier
	ds_read_b128 v[178:181], v172 offset:16384
	ds_read_b128 v[182:185], v172 offset:17408
	ds_read_b128 v[204:207], v172 offset:18432
	ds_read_b128 v[208:211], v172 offset:19456
	ds_read_b128 v[212:215], v172 offset:20480
	ds_read_b128 v[216:219], v172 offset:21504
	ds_read_b128 v[220:223], v172 offset:22528
	ds_read_b128 v[224:227], v172 offset:23552
	global_load_lds_dwordx4 v[190:191], off
	v_lshl_add_u64 v[190:191], s[20:21], 0, v[148:149]
	s_mov_b32 m0, s49
	s_nop 0
	global_load_lds_dwordx4 v[190:191], off
	s_waitcnt vmcnt(10)
	s_barrier
	s_waitcnt lgkmcnt(0)
	s_setprio 1
	s_waitcnt lgkmcnt(0)
	v_mfma_f32_16x16x32_bf16 v[60:63], v[132:135], v[178:181], v[60:63]
	v_mfma_f32_16x16x32_bf16 v[56:59], v[140:143], v[178:181], v[56:59]
	v_mfma_f32_16x16x32_bf16 v[52:55], v[132:135], v[204:207], v[52:55]
	v_mfma_f32_16x16x32_bf16 v[40:43], v[140:143], v[204:207], v[40:43]
	v_mfma_f32_16x16x32_bf16 v[28:31], v[132:135], v[212:215], v[28:31]
	v_mfma_f32_16x16x32_bf16 v[24:27], v[140:143], v[212:215], v[24:27]
	v_mfma_f32_16x16x32_bf16 v[20:23], v[132:135], v[220:223], v[20:23]
	v_mfma_f32_16x16x32_bf16 v[8:11], v[140:143], v[220:223], v[8:11]
	v_mfma_f32_16x16x32_bf16 v[60:63], v[136:139], v[182:185], v[60:63]
	v_mfma_f32_16x16x32_bf16 v[56:59], v[174:177], v[182:185], v[56:59]
	v_mfma_f32_16x16x32_bf16 v[52:55], v[136:139], v[208:211], v[52:55]
	v_mfma_f32_16x16x32_bf16 v[40:43], v[174:177], v[208:211], v[40:43]
	v_mfma_f32_16x16x32_bf16 v[28:31], v[136:139], v[216:219], v[28:31]
	v_mfma_f32_16x16x32_bf16 v[24:27], v[174:177], v[216:219], v[24:27]
	v_mfma_f32_16x16x32_bf16 v[20:23], v[136:139], v[224:227], v[20:23]
	v_mfma_f32_16x16x32_bf16 v[8:11], v[174:177], v[224:227], v[8:11]
	s_setprio 0
	s_barrier
; #define PG8_STAGE(bufoff, gbase, voff) do { _Pragma("unroll") for (int _i = 0; _i < 2; ++_i) \
;         __builtin_amdgcn_global_load_lds((const unsigned*)((const char*)(gbase) + (voff)[_i]), (LAS unsigned*)(lds + (bufoff) + ldsw + _i * 8192), 16, 0, 0); } while (0)
; #define PG8_STAGE_A(bufoff, ptr, half, rev) do { if (REVA && (rev)) { const char* _p = (ptr) - ((half) ? hstepA : 0); PG8_STAGE(bufoff, _p, voffAr); } else { const char* _p = (ptr) + ((half) ? hstepA : 0); PG8_STAGE(bufoff, _p, voffA); } } while (0)
; #define PG8_LDA(dst, b, h) do { _Pragma("unroll") for (int m = 0; m < 4; ++m) _Pragma("unroll") for (int k = 0; k < 2; ++k) dst[m][k] = *(const LAS bf16x8*)(lds + PG8_SA(b, h) + aoff + m * 2048 + k * 1024); } while (0)
; #define PG8_LDB(dst, b, h) do { _Pragma("unroll") for (int n = 0; n < 2; ++n) _Pragma("unroll") for (int k = 0; k < 2; ++k) dst[n][k] = *(const LAS bf16x8*)(lds + PG8_SB(b, h) + boff + n * 2048 + k * 1024); } while (0)
; #define PG8_MMA(ai, bj, At, Bt) do { __builtin_amdgcn_s_setprio(1); _Pragma("unroll") for (int m = 0; m < 4; ++m) _Pragma("unroll") for (int n = 0; n < 2; ++n) _Pragma("unroll") for (int k = 0; k < 2; ++k) \
;         acc[ai][bj][m][n] = __builtin_amdgcn_mfma_f32_16x16x32_bf16(Bt[n][k], At[m][k], acc[ai][bj][m][n], 0, 0, 0); __builtin_amdgcn_s_setprio(0); } while (0)
; #define PG8_WAIT_V(n) asm volatile("s_waitcnt vmcnt(" #n ")" ::: "memory")
; #define PG8_WAIT_L(n) asm volatile("s_waitcnt lgkmcnt(" #n ")" ::: "memory")
; #define PG8_BAR __builtin_amdgcn_s_barrier()
; #define PG8_SCHED __builtin_amdgcn_sched_barrier(0)
;     ...
;             PG8_STAGE(PG8_SB(0, 1), b2 + hb2, voffB);
;             PG8_WAIT_V(6); PG8_BAR; PG8_MMA(1, 1, At, B1); PG8_BAR;
;             PG8_LDB(B0, 1, 0); PG8_SCHED; PG8_LDA(At, 1, 0); PG8_STAGE_A(PG8_SA(0, 1), a2, 1, r2);
;             PG8_WAIT_L(8); PG8_BAR; PG8_WAIT_L(0); PG8_MMA(0, 0, At, B0); PG8_BAR; PG8_SCHED;
;             PG8_LDB(B1, 1, 1); PG8_STAGE(PG8_SB(1, 0), b3, voffB);
;             PG8_BAR; PG8_WAIT_L(0); PG8_MMA(0, 1, At, B1); PG8_BAR;
	s_add_u32 s78, s14, 0x100000
	s_addc_u32 s79, s15, 0
	s_add_i32 s10, s10, s5
	v_lshl_add_u64 v[132:133], s[78:79], 0, v[150:151]
	s_mov_b32 m0, s10
	s_nop 0
	global_load_lds_dwordx4 v[132:133], off
	v_lshl_add_u64 v[132:133], s[78:79], 0, v[148:149]
	s_add_i32 m0, s10, 0x2000
	s_nop 0
	global_load_lds_dwordx4 v[132:133], off
	v_add_u32_e32 v173, 0x18000, v171
	ds_read_b128 v[132:135], v173
	ds_read_b128 v[136:139], v173 offset:1024
	ds_read_b128 v[140:143], v173 offset:2048
	ds_read_b128 v[174:177], v173 offset:3072
	s_waitcnt vmcnt(10)
	s_barrier
	s_setprio 1
	v_mfma_f32_16x16x32_bf16 v[48:51], v[228:231], v[178:181], v[48:51]
	v_mfma_f32_16x16x32_bf16 v[44:47], v[236:239], v[178:181], v[44:47]
	v_mfma_f32_16x16x32_bf16 v[36:39], v[228:231], v[204:207], v[36:39]
	v_mfma_f32_16x16x32_bf16 v[32:35], v[236:239], v[204:207], v[32:35]
	v_mfma_f32_16x16x32_bf16 v[16:19], v[228:231], v[212:215], v[16:19]
	v_mfma_f32_16x16x32_bf16 v[12:15], v[236:239], v[212:215], v[12:15]
	v_mfma_f32_16x16x32_bf16 v[4:7], v[228:231], v[220:223], v[4:7]
	v_mfma_f32_16x16x32_bf16 v[0:3], v[236:239], v[220:223], v[0:3]
	v_mfma_f32_16x16x32_bf16 v[48:51], v[232:235], v[182:185], v[48:51]
	v_mfma_f32_16x16x32_bf16 v[44:47], v[240:243], v[182:185], v[44:47]
	v_mfma_f32_16x16x32_bf16 v[36:39], v[232:235], v[208:211], v[36:39]
	v_mfma_f32_16x16x32_bf16 v[32:35], v[240:243], v[208:211], v[32:35]
	v_mfma_f32_16x16x32_bf16 v[16:19], v[232:235], v[216:219], v[16:19]
	v_mfma_f32_16x16x32_bf16 v[12:15], v[240:243], v[216:219], v[12:15]
	v_mfma_f32_16x16x32_bf16 v[4:7], v[232:235], v[224:227], v[4:7]
	v_mfma_f32_16x16x32_bf16 v[0:3], v[240:243], v[224:227], v[0:3]
	s_setprio 0
	s_add_i32 s10, 0, 0x18000
	s_barrier
	s_add_u32 s20, s20, 0x100000
	s_addc_u32 s21, s21, 0
	s_mov_b32 m0, s50
	v_lshl_add_u64 v[190:191], s[20:21], 0, v[150:151]
	ds_read_b128 v[178:181], v172 offset:32768
	ds_read_b128 v[182:185], v172 offset:33792
	ds_read_b128 v[204:207], v172 offset:34816
	ds_read_b128 v[208:211], v172 offset:35840
	ds_read_b128 v[212:215], v172 offset:36864
	ds_read_b128 v[216:219], v172 offset:37888
	ds_read_b128 v[220:223], v172 offset:38912
	ds_read_b128 v[224:227], v172 offset:39936
	global_load_lds_dwordx4 v[190:191], off
	v_lshl_add_u64 v[190:191], s[20:21], 0, v[148:149]
	s_mov_b32 m0, s51
	s_nop 0
	global_load_lds_dwordx4 v[190:191], off
	s_waitcnt lgkmcnt(8)
	s_waitcnt vmcnt(10)
	s_barrier
	s_waitcnt lgkmcnt(0)
	s_setprio 1
	s_waitcnt lgkmcnt(0)
	v_mfma_f32_16x16x32_bf16 v[124:127], v[132:135], v[178:181], v[124:127]
	v_mfma_f32_16x16x32_bf16 v[120:123], v[140:143], v[178:181], v[120:123]
	v_mfma_f32_16x16x32_bf16 v[112:115], v[132:135], v[204:207], v[112:115]
	v_mfma_f32_16x16x32_bf16 v[108:111], v[140:143], v[204:207], v[108:111]
	v_mfma_f32_16x16x32_bf16 v[92:95], v[132:135], v[212:215], v[92:95]
	v_mfma_f32_16x16x32_bf16 v[88:91], v[140:143], v[212:215], v[88:91]
	v_mfma_f32_16x16x32_bf16 v[84:87], v[132:135], v[220:223], v[84:87]
	v_mfma_f32_16x16x32_bf16 v[76:79], v[140:143], v[220:223], v[76:79]
	v_mfma_f32_16x16x32_bf16 v[124:127], v[136:139], v[182:185], v[124:127]
	v_mfma_f32_16x16x32_bf16 v[120:123], v[174:177], v[182:185], v[120:123]
	v_mfma_f32_16x16x32_bf16 v[112:115], v[136:139], v[208:211], v[112:115]
	v_mfma_f32_16x16x32_bf16 v[108:111], v[174:177], v[208:211], v[108:111]
	v_mfma_f32_16x16x32_bf16 v[92:95], v[136:139], v[216:219], v[92:95]
	v_mfma_f32_16x16x32_bf16 v[88:91], v[174:177], v[216:219], v[88:91]
	v_mfma_f32_16x16x32_bf16 v[84:87], v[136:139], v[224:227], v[84:87]
	v_mfma_f32_16x16x32_bf16 v[76:79], v[174:177], v[224:227], v[76:79]
	s_setprio 0
	s_barrier
	s_add_i32 s11, 0, 0x1c000
	s_add_i32 s10, s10, s5
	v_add_u32_e32 v173, s11, v171
	v_lshl_add_u64 v[158:159], v[158:159], 0, s[28:29]
	s_mov_b32 m0, s10
	ds_read_b128 v[228:231], v173
	ds_read_b128 v[232:235], v173 offset:1024
	ds_read_b128 v[236:239], v173 offset:2048
	ds_read_b128 v[240:243], v173 offset:3072
	global_load_lds_dwordx4 v[158:159], off
	v_lshl_add_u64 v[158:159], v[168:169], 0, s[28:29]
	s_add_i32 m0, s10, 0x2000
	s_nop 0
	global_load_lds_dwordx4 v[158:159], off
	s_waitcnt vmcnt(10)
	s_barrier
	s_waitcnt lgkmcnt(0)
	s_setprio 1
	s_waitcnt lgkmcnt(0)
	v_mfma_f32_16x16x32_bf16 v[116:119], v[228:231], v[178:181], v[116:119]
	v_mfma_f32_16x16x32_bf16 v[104:107], v[236:239], v[178:181], v[104:107]
	v_mfma_f32_16x16x32_bf16 v[100:103], v[228:231], v[204:207], v[100:103]
	v_mfma_f32_16x16x32_bf16 v[96:99], v[236:239], v[204:207], v[96:99]
	v_mfma_f32_16x16x32_bf16 v[80:83], v[228:231], v[212:215], v[80:83]
	v_mfma_f32_16x16x32_bf16 v[72:75], v[236:239], v[212:215], v[72:75]
	v_mfma_f32_16x16x32_bf16 v[68:71], v[228:231], v[220:223], v[68:71]
	v_mfma_f32_16x16x32_bf16 v[64:67], v[236:239], v[220:223], v[64:67]
	v_mfma_f32_16x16x32_bf16 v[116:119], v[232:235], v[182:185], v[116:119]
	v_mfma_f32_16x16x32_bf16 v[104:107], v[240:243], v[182:185], v[104:107]
	v_mfma_f32_16x16x32_bf16 v[100:103], v[232:235], v[208:211], v[100:103]
	v_mfma_f32_16x16x32_bf16 v[96:99], v[240:243], v[208:211], v[96:99]
	v_mfma_f32_16x16x32_bf16 v[80:83], v[232:235], v[216:219], v[80:83]
	v_mfma_f32_16x16x32_bf16 v[72:75], v[240:243], v[216:219], v[72:75]
	v_mfma_f32_16x16x32_bf16 v[68:71], v[232:235], v[224:227], v[68:71]
	v_mfma_f32_16x16x32_bf16 v[64:67], v[240:243], v[224:227], v[64:67]
	s_setprio 0
	s_mov_b32 m0, s66
	v_lshl_add_u64 v[158:159], s[16:17], 0, v[150:151]
	s_barrier
; #define PG8_STAGE(bufoff, gbase, voff) do { _Pragma("unroll") for (int _i = 0; _i < 2; ++_i) \
;         __builtin_amdgcn_global_load_lds((const unsigned*)((const char*)(gbase) + (voff)[_i]), (LAS unsigned*)(lds + (bufoff) + ldsw + _i * 8192), 16, 0, 0); } while (0)
; #define PG8_STAGE_A(bufoff, ptr, half, rev) do { if (REVA && (rev)) { const char* _p = (ptr) - ((half) ? hstepA : 0); PG8_STAGE(bufoff, _p, voffAr); } else { const char* _p = (ptr) + ((half) ? hstepA : 0); PG8_STAGE(bufoff, _p, voffA); } } while (0)
; #define PG8_LDA(dst, b, h) do { _Pragma("unroll") for (int m = 0; m < 4; ++m) _Pragma("unroll") for (int k = 0; k < 2; ++k) dst[m][k] = *(const LAS bf16x8*)(lds + PG8_SA(b, h) + aoff + m * 2048 + k * 1024); } while (0)
; #define PG8_WAIT_V(n) asm volatile("s_waitcnt vmcnt(" #n ")" ::: "memory")
;     ...
;             PG8_LDA(At, 1, 1); PG8_STAGE_A(PG8_SA(1, 0), a3, 0, r3);
;             PG8_BAR; PG8_WAIT_L(0); PG8_MMA(1, 0, At, B0); PG8_BAR; PG8_SCHED;
;             PG8_STAGE(PG8_SB(1, 1), b3 + hb2, voffB);
;             PG8_WAIT_V(6); PG8_BAR; PG8_MMA(1, 1, At, B1); PG8_BAR;
;     __device__ __forceinline__ void operator()(const f32x4 (&acc)[2][2][4][2], const Unit& u, int wr, int wc, int fr, int fq, int lane) const {
;         const bool lat = u.pm < 128;
;         const int s = lat ? (u.pm >> 4) : 8;
;         const float* gate = modi + s * 6144 + 4096 + u.pn * BM + wc * 32 + 4 * fq;
;         const size_t r0 = lat ? (size_t)u.pm * BM : (size_t)(u.pm - 128) * BM;
;         const float* base = (lat ? baseL : baseC) + u.pn * BM + wc * 32 + 4 * fq;
;         float* out = (lat ? outL : outC) + u.pn * BM + wc * 32 + 4 * fq;
;         f32x4 gv[2][2];
; #pragma unroll
;         for (int bj = 0; bj < 2; ++bj)
; #pragma unroll
;             for (int n = 0; n < 2; ++n) gv[bj][n] = *(const f32x4*)(gate + bj * HALF + n * 16);
; #pragma unroll
;         for (int ai = 0; ai < 2; ++ai)
; #pragma unroll
;           for (int mh = 0; mh < 2; ++mh) {
;             f32x4 bs[2][2][2];
; #pragma unroll
;             for (int m2 = 0; m2 < 2; ++m2) {
;                 const size_t ro = (r0 + ai * HALF + wr * 64 + (mh * 2 + m2) * 16 + fr) * (size_t)D;
; #pragma unroll
;                 for (int bj = 0; bj < 2; ++bj)
; #pragma unroll
;                     for (int n = 0; n < 2; ++n) bs[m2][bj][n] = *(const f32x4*)(base + ro + bj * HALF + n * 16);
	ds_read_b128 v[178:181], v172 offset:49152
	ds_read_b128 v[182:185], v172 offset:50176
	ds_read_b128 v[204:207], v172 offset:51200
	ds_read_b128 v[208:211], v172 offset:52224
	ds_read_b128 v[212:215], v172 offset:53248
	ds_read_b128 v[216:219], v172 offset:54272
	ds_read_b128 v[220:223], v172 offset:55296
	ds_read_b128 v[224:227], v172 offset:56320
	global_load_lds_dwordx4 v[158:159], off
	v_lshl_add_u64 v[158:159], s[16:17], 0, v[148:149]
	s_mov_b32 m0, s67
	s_nop 0
	global_load_lds_dwordx4 v[158:159], off
	s_waitcnt vmcnt(10)
	s_barrier
	s_waitcnt lgkmcnt(0)
	s_setprio 1
	s_waitcnt lgkmcnt(0)
	v_mfma_f32_16x16x32_bf16 v[60:63], v[132:135], v[178:181], v[60:63]
	v_mfma_f32_16x16x32_bf16 v[56:59], v[140:143], v[178:181], v[56:59]
	v_mfma_f32_16x16x32_bf16 v[52:55], v[132:135], v[204:207], v[52:55]
	v_mfma_f32_16x16x32_bf16 v[40:43], v[140:143], v[204:207], v[40:43]
	v_mfma_f32_16x16x32_bf16 v[28:31], v[132:135], v[212:215], v[28:31]
	v_mfma_f32_16x16x32_bf16 v[24:27], v[140:143], v[212:215], v[24:27]
	v_mfma_f32_16x16x32_bf16 v[20:23], v[132:135], v[220:223], v[20:23]
	v_mfma_f32_16x16x32_bf16 v[8:11], v[140:143], v[220:223], v[8:11]
	v_mfma_f32_16x16x32_bf16 v[60:63], v[136:139], v[182:185], v[60:63]
	v_mfma_f32_16x16x32_bf16 v[56:59], v[174:177], v[182:185], v[56:59]
	v_mfma_f32_16x16x32_bf16 v[52:55], v[136:139], v[208:211], v[52:55]
	v_mfma_f32_16x16x32_bf16 v[40:43], v[174:177], v[208:211], v[40:43]
	v_mfma_f32_16x16x32_bf16 v[28:31], v[136:139], v[216:219], v[28:31]
	v_mfma_f32_16x16x32_bf16 v[24:27], v[174:177], v[216:219], v[24:27]
	v_mfma_f32_16x16x32_bf16 v[20:23], v[136:139], v[224:227], v[20:23]
	v_mfma_f32_16x16x32_bf16 v[8:11], v[174:177], v[224:227], v[8:11]
	s_setprio 0
	s_barrier
	s_add_u32 s14, s14, 0x100080
	s_addc_u32 s15, s15, 0
	s_add_i32 s10, s11, s5
	v_lshl_add_u64 v[132:133], s[14:15], 0, v[150:151]
	s_mov_b32 m0, s10
	s_nop 0
	global_load_lds_dwordx4 v[132:133], off
	v_lshl_add_u64 v[132:133], s[14:15], 0, v[148:149]
	s_add_i32 m0, s10, 0x2000
	s_nop 0
	global_load_lds_dwordx4 v[132:133], off
	v_add_u32_e32 v158, 0x10000, v171
	ds_read_b128 v[132:135], v158
	ds_read_b128 v[136:139], v158 offset:1024
	ds_read_b128 v[140:143], v158 offset:2048
	ds_read_b128 v[174:177], v158 offset:3072
	s_waitcnt vmcnt(10)
	s_barrier
	s_setprio 1
	v_mfma_f32_16x16x32_bf16 v[48:51], v[228:231], v[178:181], v[48:51]
	v_mfma_f32_16x16x32_bf16 v[44:47], v[236:239], v[178:181], v[44:47]
	v_mfma_f32_16x16x32_bf16 v[36:39], v[228:231], v[204:207], v[36:39]
	v_mfma_f32_16x16x32_bf16 v[32:35], v[236:239], v[204:207], v[32:35]
	v_mfma_f32_16x16x32_bf16 v[16:19], v[228:231], v[212:215], v[16:19]
	v_mfma_f32_16x16x32_bf16 v[12:15], v[236:239], v[212:215], v[12:15]
	v_mfma_f32_16x16x32_bf16 v[4:7], v[228:231], v[220:223], v[4:7]
	v_mfma_f32_16x16x32_bf16 v[0:3], v[236:239], v[220:223], v[0:3]
	v_mfma_f32_16x16x32_bf16 v[48:51], v[232:235], v[182:185], v[48:51]
	v_mfma_f32_16x16x32_bf16 v[44:47], v[240:243], v[182:185], v[44:47]
	v_mfma_f32_16x16x32_bf16 v[36:39], v[232:235], v[208:211], v[36:39]
	v_mfma_f32_16x16x32_bf16 v[32:35], v[240:243], v[208:211], v[32:35]
	v_mfma_f32_16x16x32_bf16 v[16:19], v[232:235], v[216:219], v[16:19]
	v_mfma_f32_16x16x32_bf16 v[12:15], v[240:243], v[216:219], v[12:15]
	v_mfma_f32_16x16x32_bf16 v[4:7], v[232:235], v[224:227], v[4:7]
	v_mfma_f32_16x16x32_bf16 v[0:3], v[240:243], v[224:227], v[0:3]
	s_setprio 0
	s_add_i32 s71, s71, 2
	s_add_u32 s42, s42, 0x100
	s_addc_u32 s43, s43, 0
	s_cmp_gt_u32 s71, 61
	s_barrier
	s_cbranch_scc0 .LBB0_1229
	s_waitcnt lgkmcnt(0)
	s_cmpk_lt_i32 s9, 0x80
	s_cselect_b64 vcc, -1, 0
	s_cselect_b32 s3, s61, s53
	s_cselect_b32 s10, s60, s52
	s_add_i32 s0, s9, 0xffffff80
	s_cmpk_lt_i32 s9, 0x80
	s_cselect_b32 s0, s9, s0
	s_lshr_b32 s1, s9, 4
	s_cmpk_lt_i32 s9, 0x80
	s_mulk_i32 s1, 0x1800
	s_cselect_b32 s14, s1, 0xc000
	s_ashr_i32 s15, s14, 31
	s_lshl_b64 s[14:15], s[14:15], 2
	s_add_u32 s1, s6, s14
	s_addc_u32 s11, s7, s15
	s_lshl_b32 s8, s8, 8
	s_ashr_i32 s9, s8, 31
	s_lshl_b64 s[8:9], s[8:9], 2
	s_add_u32 s1, s1, s8
	s_addc_u32 s11, s11, s9
	s_add_u32 s14, s1, s22
	s_waitcnt vmcnt(0)
	v_cndmask_b32_e32 v129, v147, v145, vcc
	v_cndmask_b32_e32 v128, v146, v144, vcc
	s_addc_u32 s15, s11, 0
	s_ashr_i32 s1, s0, 31
	v_lshl_add_u64 v[128:129], v[128:129], 0, s[8:9]
	s_add_u32 s8, s10, s8
	s_addc_u32 s3, s3, s9
	s_add_u32 s8, s8, s22
	v_lshl_add_u64 v[130:131], s[14:15], 0, v[160:161]
	s_addc_u32 s9, s3, 0
	s_mov_b32 s3, 0x704000
	s_lshl_b64 s[0:1], s[0:1], 21
	s_mov_b64 s[14:15], 0x704000
	v_lshl_add_u64 v[168:169], v[128:129], 0, s[22:23]
	v_add_co_u32_e32 v128, vcc, s3, v130
	v_lshl_add_u64 v[224:225], s[0:1], 0, v[152:153]
	v_lshl_add_u64 v[158:159], v[130:131], 0, s[14:15]
	v_addc_co_u32_e32 v129, vcc, 0, v131, vcc
	v_lshl_add_u64 v[190:191], v[168:169], 0, v[160:161]
	v_or_b32_e32 v226, 0x20000, v224
	v_mov_b32_e32 v227, v225
	global_load_dwordx4 v[136:139], v[158:159], off offset:64
	global_load_dwordx4 v[132:135], v[158:159], off offset:512
	global_load_dwordx4 v[140:143], v[128:129], off
	s_nop 0
	global_load_dwordx4 v[128:131], v[158:159], off offset:576
	v_lshl_add_u64 v[168:169], v[190:191], 0, v[224:225]
	v_lshl_add_u64 v[158:159], v[190:191], 0, v[226:227]
	global_load_dwordx4 v[174:177], v[168:169], off
	global_load_dwordx4 v[178:181], v[168:169], off offset:64
	global_load_dwordx4 v[182:185], v[168:169], off offset:512
	global_load_dwordx4 v[204:207], v[168:169], off offset:576
	global_load_dwordx4 v[208:211], v[158:159], off
	global_load_dwordx4 v[212:215], v[158:159], off offset:64
	global_load_dwordx4 v[216:219], v[158:159], off offset:512
	global_load_dwordx4 v[220:223], v[158:159], off offset:576
	v_lshl_add_u64 v[228:229], s[8:9], 0, v[160:161]
	v_lshl_add_u64 v[158:159], v[228:229], 0, v[224:225]
	s_waitcnt vmcnt(0)
;     __device__ __forceinline__ void operator()(const f32x4 (&acc)[2][2][4][2], const Unit& u, int wr, int wc, int fr, int fq, int lane) const {
;     ...
;         for (int ai = 0; ai < 2; ++ai)
; #pragma unroll
;           for (int mh = 0; mh < 2; ++mh) {
;             f32x4 bs[2][2][2];
; #pragma unroll
;             for (int m2 = 0; m2 < 2; ++m2) {
;                 const size_t ro = (r0 + ai * HALF + wr * 64 + (mh * 2 + m2) * 16 + fr) * (size_t)D;
; #pragma unroll
;                 for (int bj = 0; bj < 2; ++bj)
; #pragma unroll
;                     for (int n = 0; n < 2; ++n) bs[m2][bj][n] = *(const f32x4*)(base + ro + bj * HALF + n * 16);
;             }
;             __builtin_amdgcn_sched_barrier(0);
; #pragma unroll
;             for (int m2 = 0; m2 < 2; ++m2) {
;                 const size_t ro = (r0 + ai * HALF + wr * 64 + (mh * 2 + m2) * 16 + fr) * (size_t)D;
; #pragma unroll
;                 for (int bj = 0; bj < 2; ++bj)
; #pragma unroll
;                     for (int n = 0; n < 2; ++n) *(f32x4*)(out + ro + bj * HALF + n * 16) = bs[m2][bj][n] + gv[bj][n] * acc[ai][bj][mh * 2 + m2][n];
;             }
;             __builtin_amdgcn_sched_barrier(0);
;           }
	v_pk_fma_f32 v[118:119], v[118:119], v[134:135], v[184:185]
	v_pk_fma_f32 v[116:117], v[116:117], v[132:133], v[182:183]
	v_pk_fma_f32 v[106:107], v[106:107], v[130:131], v[206:207]
	v_pk_fma_f32 v[104:105], v[104:105], v[128:129], v[204:205]
	global_store_dwordx4 v[158:159], v[116:119], off offset:512
	global_store_dwordx4 v[158:159], v[104:107], off offset:576
	v_pk_fma_f32 v[126:127], v[126:127], v[142:143], v[176:177]
	v_lshl_add_u64 v[116:117], v[228:229], 0, v[226:227]
	v_pk_fma_f32 v[106:107], v[114:115], v[142:143], v[210:211]
	v_pk_fma_f32 v[104:105], v[112:113], v[140:141], v[208:209]
	v_pk_fma_f32 v[124:125], v[124:125], v[140:141], v[174:175]
	v_pk_fma_f32 v[122:123], v[122:123], v[138:139], v[180:181]
	v_pk_fma_f32 v[120:121], v[120:121], v[136:137], v[178:179]
	global_store_dwordx4 v[116:117], v[104:107], off
	v_pk_fma_f32 v[102:103], v[102:103], v[134:135], v[218:219]
	v_pk_fma_f32 v[100:101], v[100:101], v[132:133], v[216:217]
	v_pk_fma_f32 v[106:107], v[110:111], v[138:139], v[214:215]
	v_pk_fma_f32 v[104:105], v[108:109], v[136:137], v[212:213]
	v_pk_fma_f32 v[98:99], v[98:99], v[130:131], v[222:223]
	v_pk_fma_f32 v[96:97], v[96:97], v[128:129], v[220:221]
	global_store_dwordx4 v[158:159], v[124:127], off
	global_store_dwordx4 v[158:159], v[120:123], off offset:64
	global_store_dwordx4 v[116:117], v[104:107], off offset:64
	global_store_dwordx4 v[116:117], v[100:103], off offset:512
	global_store_dwordx4 v[116:117], v[96:99], off offset:576
	v_or_b32_e32 v174, 0x40000, v224
	v_mov_b32_e32 v175, v225
	v_or_b32_e32 v224, 0x60000, v224
	v_lshl_add_u64 v[108:109], v[190:191], 0, v[174:175]
	v_lshl_add_u64 v[124:125], v[190:191], 0, v[224:225]
	global_load_dwordx4 v[96:99], v[108:109], off
	global_load_dwordx4 v[100:103], v[108:109], off offset:64
	global_load_dwordx4 v[104:107], v[108:109], off offset:512
	s_nop 0
	global_load_dwordx4 v[108:111], v[108:109], off offset:576
	s_nop 0
	global_load_dwordx4 v[112:115], v[124:125], off
	global_load_dwordx4 v[116:119], v[124:125], off offset:64
	global_load_dwordx4 v[120:123], v[124:125], off offset:512
	s_nop 0
	global_load_dwordx4 v[124:127], v[124:125], off offset:576
	v_lshl_add_u64 v[174:175], v[228:229], 0, v[174:175]
	s_waitcnt vmcnt(0)
	v_pk_fma_f32 v[82:83], v[82:83], v[134:135], v[106:107]
	v_pk_fma_f32 v[80:81], v[80:81], v[132:133], v[104:105]
	v_pk_fma_f32 v[74:75], v[74:75], v[130:131], v[110:111]
	v_pk_fma_f32 v[72:73], v[72:73], v[128:129], v[108:109]
	global_store_dwordx4 v[174:175], v[80:83], off offset:512
	global_store_dwordx4 v[174:175], v[72:75], off offset:576
	v_pk_fma_f32 v[94:95], v[94:95], v[142:143], v[98:99]
	v_lshl_add_u64 v[80:81], v[228:229], 0, v[224:225]
	v_pk_fma_f32 v[74:75], v[86:87], v[142:143], v[114:115]
	v_pk_fma_f32 v[72:73], v[84:85], v[140:141], v[112:113]
	v_pk_fma_f32 v[92:93], v[92:93], v[140:141], v[96:97]
	v_pk_fma_f32 v[90:91], v[90:91], v[138:139], v[102:103]
	v_pk_fma_f32 v[88:89], v[88:89], v[136:137], v[100:101]
	global_store_dwordx4 v[80:81], v[72:75], off
	v_pk_fma_f32 v[70:71], v[70:71], v[134:135], v[122:123]
	v_pk_fma_f32 v[68:69], v[68:69], v[132:133], v[120:121]
	v_pk_fma_f32 v[74:75], v[78:79], v[138:139], v[118:119]
	v_pk_fma_f32 v[72:73], v[76:77], v[136:137], v[116:117]
	v_pk_fma_f32 v[66:67], v[66:67], v[130:131], v[126:127]
	v_pk_fma_f32 v[64:65], v[64:65], v[128:129], v[124:125]
	global_store_dwordx4 v[174:175], v[92:95], off
	global_store_dwordx4 v[174:175], v[88:91], off offset:64
	global_store_dwordx4 v[80:81], v[72:75], off offset:64
	global_store_dwordx4 v[80:81], v[68:71], off offset:512
	global_store_dwordx4 v[80:81], v[64:67], off offset:576
	s_mov_b32 s3, 0x100000
	v_add_co_u32_e32 v72, vcc, s3, v168
	s_mov_b32 s8, 0x120000
	s_nop 0
	v_addc_co_u32_e32 v73, vcc, 0, v169, vcc
	s_mov_b64 s[0:1], 0x100000
	s_mov_b64 s[10:11], 0x120000
	v_add_co_u32_e32 v88, vcc, s8, v168
	v_lshl_add_u64 v[76:77], v[168:169], 0, s[0:1]
	v_lshl_add_u64 v[92:93], v[168:169], 0, s[10:11]
	v_addc_co_u32_e32 v89, vcc, 0, v169, vcc
	global_load_dwordx4 v[64:67], v[76:77], off offset:64
	global_load_dwordx4 v[68:71], v[76:77], off offset:512
	s_nop 0
	global_load_dwordx4 v[72:75], v[72:73], off
	s_nop 0
	global_load_dwordx4 v[76:79], v[76:77], off offset:576
	s_nop 0
	global_load_dwordx4 v[80:83], v[92:93], off offset:64
	global_load_dwordx4 v[84:87], v[92:93], off offset:512
	s_nop 0
	global_load_dwordx4 v[88:91], v[88:89], off
	s_nop 0
	global_load_dwordx4 v[92:95], v[92:93], off offset:576
	s_waitcnt vmcnt(0)
; #define PG8_WAIT_V(n) asm volatile("s_waitcnt vmcnt(" #n ")" ::: "memory")
; #define PG8_BAR __builtin_amdgcn_s_barrier()
;     ...
;         cur = nxt; cA = nA; cB = nB; cAr = nAr; cHb = nHb; ++ui;
;     }
;     PG8_WAIT_V(0);
;     if (wr == 0) PG8_BAR;
;     PG8_BAR;
;     __device__ __forceinline__ void operator()(const f32x4 (&acc)[2][2][4][2], const Unit& u, int wr, int wc, int fr, int fq, int lane) const {
;     ...
;         for (int ai = 0; ai < 2; ++ai)
; #pragma unroll
;           for (int mh = 0; mh < 2; ++mh) {
;             f32x4 bs[2][2][2];
; #pragma unroll
;             for (int m2 = 0; m2 < 2; ++m2) {
;                 const size_t ro = (r0 + ai * HALF + wr * 64 + (mh * 2 + m2) * 16 + fr) * (size_t)D;
; #pragma unroll
;                 for (int bj = 0; bj < 2; ++bj)
; #pragma unroll
;                     for (int n = 0; n < 2; ++n) bs[m2][bj][n] = *(const f32x4*)(base + ro + bj * HALF + n * 16);
;             }
;             __builtin_amdgcn_sched_barrier(0);
; #pragma unroll
;             for (int m2 = 0; m2 < 2; ++m2) {
;                 const size_t ro = (r0 + ai * HALF + wr * 64 + (mh * 2 + m2) * 16 + fr) * (size_t)D;
; #pragma unroll
;                 for (int bj = 0; bj < 2; ++bj)
; #pragma unroll
;                     for (int n = 0; n < 2; ++n) *(f32x4*)(out + ro + bj * HALF + n * 16) = bs[m2][bj][n] + gv[bj][n] * acc[ai][bj][mh * 2 + m2][n];
;             }
;             __builtin_amdgcn_sched_barrier(0);
;           }
	v_pk_fma_f32 v[60:61], v[60:61], v[140:141], v[72:73]
	v_add_co_u32_e32 v72, vcc, s3, v158
	v_lshl_add_u64 v[96:97], v[158:159], 0, s[0:1]
	s_nop 0
	v_addc_co_u32_e32 v73, vcc, 0, v159, vcc
	v_pk_fma_f32 v[50:51], v[50:51], v[134:135], v[70:71]
	v_pk_fma_f32 v[48:49], v[48:49], v[132:133], v[68:69]
	global_store_dwordx4 v[96:97], v[48:51], off offset:512
	v_pk_fma_f32 v[46:47], v[46:47], v[130:131], v[78:79]
	v_pk_fma_f32 v[44:45], v[44:45], v[128:129], v[76:77]
	v_add_co_u32_e32 v50, vcc, s8, v158
	s_mov_b64 s[74:75], 0x100000
	v_pk_fma_f32 v[62:63], v[62:63], v[142:143], v[74:75]
	s_mov_b32 s76, 0x100000
	v_pk_fma_f32 v[58:59], v[58:59], v[138:139], v[66:67]
	v_pk_fma_f32 v[56:57], v[56:57], v[136:137], v[64:65]
	global_store_dwordx4 v[96:97], v[44:47], off offset:576
	v_lshl_add_u64 v[48:49], v[158:159], 0, s[10:11]
	s_mov_b32 s77, 0x120000
	v_pk_fma_f32 v[46:47], v[54:55], v[142:143], v[90:91]
	v_pk_fma_f32 v[44:45], v[52:53], v[140:141], v[88:89]
	v_addc_co_u32_e32 v51, vcc, 0, v159, vcc
	v_pk_fma_f32 v[42:43], v[42:43], v[138:139], v[82:83]
	v_pk_fma_f32 v[40:41], v[40:41], v[136:137], v[80:81]
	v_pk_fma_f32 v[38:39], v[38:39], v[134:135], v[86:87]
	v_pk_fma_f32 v[36:37], v[36:37], v[132:133], v[84:85]
	v_pk_fma_f32 v[34:35], v[34:35], v[130:131], v[94:95]
	v_pk_fma_f32 v[32:33], v[32:33], v[128:129], v[92:93]
	global_store_dwordx4 v[72:73], v[60:63], off
	global_store_dwordx4 v[96:97], v[56:59], off offset:64
	global_store_dwordx4 v[50:51], v[44:47], off
	global_store_dwordx4 v[48:49], v[40:43], off offset:64
	global_store_dwordx4 v[48:49], v[36:39], off offset:512
	global_store_dwordx4 v[48:49], v[32:35], off offset:576
	s_mov_b32 s0, 0x140000
	v_add_co_u32_e32 v40, vcc, s0, v168
	s_mov_b32 s1, 0x160000
	s_nop 0
	v_addc_co_u32_e32 v41, vcc, 0, v169, vcc
	s_mov_b64 s[8:9], 0x140000
	s_mov_b64 s[10:11], 0x160000
	v_add_co_u32_e32 v56, vcc, s1, v168
	v_lshl_add_u64 v[44:45], v[168:169], 0, s[8:9]
	v_lshl_add_u64 v[60:61], v[168:169], 0, s[10:11]
	v_addc_co_u32_e32 v57, vcc, 0, v169, vcc
	global_load_dwordx4 v[32:35], v[44:45], off offset:64
	global_load_dwordx4 v[36:39], v[44:45], off offset:512
	s_nop 0
	global_load_dwordx4 v[40:43], v[40:41], off
	s_nop 0
	global_load_dwordx4 v[44:47], v[44:45], off offset:576
	s_nop 0
	global_load_dwordx4 v[48:51], v[60:61], off offset:64
	global_load_dwordx4 v[52:55], v[60:61], off offset:512
	s_nop 0
	global_load_dwordx4 v[56:59], v[56:57], off
	s_nop 0
	global_load_dwordx4 v[60:63], v[60:61], off offset:576
	s_waitcnt vmcnt(0)
	v_pk_fma_f32 v[28:29], v[28:29], v[140:141], v[40:41]
	v_add_co_u32_e32 v40, vcc, s0, v158
	v_lshl_add_u64 v[64:65], v[158:159], 0, s[8:9]
	s_nop 0
	v_addc_co_u32_e32 v41, vcc, 0, v159, vcc
	v_pk_fma_f32 v[18:19], v[18:19], v[134:135], v[38:39]
	v_pk_fma_f32 v[16:17], v[16:17], v[132:133], v[36:37]
	global_store_dwordx4 v[64:65], v[16:19], off offset:512
	v_pk_fma_f32 v[14:15], v[14:15], v[130:131], v[46:47]
	v_pk_fma_f32 v[12:13], v[12:13], v[128:129], v[44:45]
	v_add_co_u32_e32 v18, vcc, s1, v158
	v_pk_fma_f32 v[30:31], v[30:31], v[142:143], v[42:43]
	s_mov_b32 s18, 0x140000
	v_pk_fma_f32 v[26:27], v[26:27], v[138:139], v[34:35]
	v_pk_fma_f32 v[24:25], v[24:25], v[136:137], v[32:33]
	global_store_dwordx4 v[64:65], v[12:15], off offset:576
	v_lshl_add_u64 v[16:17], v[158:159], 0, s[10:11]
	s_mov_b32 s54, 0x160000
	v_pk_fma_f32 v[14:15], v[22:23], v[142:143], v[58:59]
	v_pk_fma_f32 v[12:13], v[20:21], v[140:141], v[56:57]
	v_addc_co_u32_e32 v19, vcc, 0, v159, vcc
	v_pk_fma_f32 v[10:11], v[10:11], v[138:139], v[50:51]
	v_pk_fma_f32 v[8:9], v[8:9], v[136:137], v[48:49]
	v_pk_fma_f32 v[6:7], v[6:7], v[134:135], v[54:55]
	v_pk_fma_f32 v[4:5], v[4:5], v[132:133], v[52:53]
	v_pk_fma_f32 v[2:3], v[2:3], v[130:131], v[62:63]
	v_pk_fma_f32 v[0:1], v[0:1], v[128:129], v[60:61]
	global_store_dwordx4 v[40:41], v[28:31], off
	global_store_dwordx4 v[64:65], v[24:27], off offset:64
	global_store_dwordx4 v[18:19], v[12:15], off
	global_store_dwordx4 v[16:17], v[8:11], off offset:64
	global_store_dwordx4 v[16:17], v[4:7], off offset:512
	global_store_dwordx4 v[16:17], v[0:3], off offset:576
	s_and_b64 vcc, exec, s[40:41]
	s_mov_b32 s8, s2
	s_mov_b32 s9, s26
	s_mov_b64 s[20:21], s[38:39]
	s_mov_b64 s[0:1], s[36:37]
	s_cbranch_vccz .LBB0_1226
	s_waitcnt vmcnt(0)
	v_readlane_b32 s52, v255, 4
	s_cmpk_gt_u32 s4, 0xff
	v_readlane_b32 s53, v255, 5
	s_cbranch_scc1 .LBB0_1233
	s_barrier
